# mlp1/mlp2/outproj ported to 128x128 tiles with full-line LDS-DMA ring of 5 x 16KB units (dynamic ring positions); merge4 ring5 half-burst
# speedup vs baseline: 1.1990x; 1.0395x over previous
; template <int NI> ...
;     ...
;   const int lane = tid & 63, wid = tid >> 6, wr = wid >> 1, wc = wid & 1;
;   const int lrow = tid >> 2, lch = (tid & 3) * 8;
;   const int l15 = lane & 15, lq = lane >> 4;
;   const bf16_t* pa = A + (size_t)lrow * lda + lch;
;   const bf16_t* pb = B + (size_t)lrow * ldb + lch;
;   const size_t a64 = (size_t)64 * lda, b64 = (size_t)64 * ldb;
;   u32x4 a0[2], a1[2], b0[NB], b1[NB];
;   const int nk = K >> 5;
;   const int klast = K - 32;
;   const int wofs = lrow * GROW + lch;
;   const int raofs = (wr * 64 + l15) * GROW + lq * 8;
;   const int rbofs = 128 * GROW + (wc * (16 * NI) + l15) * GROW + lq * 8;
;     ...
;   G_LOAD(a0, b0, 0);
;   G_LOAD(a1, b1, 32);
;   __syncthreads();
;   G_WRITE(a0, b0, 0);
;   __syncthreads();
; __device__ void phase_merge4(CParams& p, int l, int tm, int tn, char* smem) {
;     ...
;   for (int kb0 = 0; kb0 < 4; kb0++) {
;     int kb = kb0;
;     asm volatile("" : "+s"(kb));
;     int tid2 = tid;
;     asm volatile("" : "+v"(tid2));
;     unsigned pk[4][4][2];
;     {
;       f32x4 acc[4][4];
;       zero_acc<4>(acc);
;       gemm_mainloop<4>(p.br + (size_t)row0 * 1024 + kb * 256, 1024,
;                        p.WbT + (((size_t)l * 4 + kb) * 1024 + col0) * 256, 256, 256, sA, sB, acc, tid2);
.LBB0_878:
	s_or_b64 exec, exec, s[20:21]
	s_mov_b64 s[42:43], s[34:35]
	s_waitcnt lgkmcnt(0)
	s_barrier
	s_lshl_b64 s[6:7], s[50:51], 12
	s_load_dwordx4 s[48:51], s[42:43], 0x1d0
	s_load_dwordx4 s[52:55], s[42:43], 0x108
	s_load_dwordx2 s[20:21], s[42:43], 0x150
	s_add_u32 s24, s6, s88
	s_addc_u32 s25, s7, s89
	s_lshl_b64 s[6:7], s[88:89], 1
	s_waitcnt lgkmcnt(0)
	s_add_u32 s44, s50, s6
	s_addc_u32 s45, s51, s7
	s_mov_b64 exec, -1
	ds_read_b128 v[252:255], v145 offset:40960
	v_cndmask_b32_e64 v0, 0, 1, s[84:85]
	v_cmp_ne_u32_e64 s[40:41], 1, v0
	s_load_dwordx2 s[0:1], s[34:35], 0x150
	s_load_dwordx2 s[6:7], s[34:35], 0x1d0
	s_load_dwordx2 s[8:9], s[34:35], 0x1d8
	s_load_dwordx2 s[12:13], s[34:35], 0x108
	s_load_dwordx2 s[18:19], s[34:35], 0x110
	s_lshr_b32 s2, s24, 12
	v_readlane_b32 s4, v225, 4
	v_readfirstlane_b32 s56, v147
	v_and_b32_e32 v166, 63, v147
	s_nop 3
	s_and_b32 s20, s4, 7
	s_lshl_b32 s20, s20, 3
	s_lshr_b32 s57, s4, 6
	s_add_u32 s20, s20, s57
	s_lshr_b32 s21, s4, 3
	s_and_b32 s21, s21, 7
	s_lshl_b32 s21, s21, 7
	s_lshr_b32 s57, s56, 6
	s_lshl_b32 s56, s57, 12
	v_lshrrev_b32_e32 v167, 3, v166
	s_lshl_b32 s62, s57, 5
	v_add_u32_e32 v167, s62, v167
	v_and_b32_e32 v226, 7, v166
	v_lshrrev_b32_e32 v227, 4, v166
	v_xor_b32_e32 v248, v226, v227
	v_xor_b32_e32 v249, 0, v248
	v_lshlrev_b32_e32 v249, 4, v249
	v_add_u32_e32 v250, 0, v167
	v_lshl_add_u32 v236, v250, 11, v249
	v_xor_b32_e32 v249, 4, v248
	v_lshlrev_b32_e32 v249, 4, v249
	v_add_u32_e32 v250, 8, v167
	v_lshl_add_u32 v237, v250, 11, v249
	v_xor_b32_e32 v249, 0, v248
	v_lshlrev_b32_e32 v249, 4, v249
	v_add_u32_e32 v250, 16, v167
	v_lshl_add_u32 v238, v250, 11, v249
	v_xor_b32_e32 v249, 4, v248
	v_lshlrev_b32_e32 v249, 4, v249
	v_add_u32_e32 v250, 24, v167
	v_lshl_add_u32 v239, v250, 11, v249
	s_and_b32 s63, s57, 1
	s_lshl_b32 s63, s63, 2
	v_and_b32_e32 v248, 1, v227
	v_or_b32_e32 v248, s63, v248
	v_xor_b32_e32 v248, v226, v248
	v_xor_b32_e32 v249, 0, v248
	v_lshlrev_b32_e32 v249, 4, v249
	v_add_u32_e32 v250, 0, v167
	v_lshl_add_u32 v240, v250, 9, v249
	v_lshl_add_u32 v244, v250, 11, v249
	v_xor_b32_e32 v249, 0, v248
	v_lshlrev_b32_e32 v249, 4, v249
	v_add_u32_e32 v250, 8, v167
	v_lshl_add_u32 v241, v250, 9, v249
	v_lshl_add_u32 v245, v250, 11, v249
	v_xor_b32_e32 v249, 2, v248
	v_lshlrev_b32_e32 v249, 4, v249
	v_add_u32_e32 v250, 16, v167
	v_lshl_add_u32 v242, v250, 9, v249
	v_lshl_add_u32 v246, v250, 11, v249
	v_xor_b32_e32 v249, 2, v248
	v_lshlrev_b32_e32 v249, 4, v249
	v_add_u32_e32 v250, 24, v167
	v_lshl_add_u32 v243, v250, 9, v249
	v_lshl_add_u32 v247, v250, 11, v249
	v_and_b32_e32 v167, 15, v166
	v_lshrrev_b32_e32 v227, 4, v166
	s_lshr_b32 s62, s57, 1
	s_and_b32 s63, s57, 1
	s_lshl_b32 s92, s62, 6
	s_lshl_b32 s93, s63, 6
	v_lshrrev_b32_e32 v226, 1, v167
	v_xor_b32_e32 v226, v227, v226
	v_lshlrev_b32_e32 v226, 4, v226
	v_add_u32_e32 v248, s92, v167
	v_lshl_add_u32 v248, v248, 7, v226
	v_xor_b32_e32 v249, 64, v248
	v_lshrrev_b32_e32 v226, 2, v167
	v_lshrrev_b32_e32 v250, 1, v167
	v_and_b32_e32 v250, 1, v250
	v_lshl_or_b32 v250, v226, 1, v250
	v_xor_b32_e32 v250, v227, v250
	v_lshlrev_b32_e32 v250, 4, v250
	v_and_b32_e32 v251, 3, v167
	v_lshl_add_u32 v251, v226, 4, v251
	v_add_u32_e32 v251, s93, v251
	v_lshl_add_u32 v250, v251, 7, v250
	v_xor_b32_e32 v251, 64, v250
	v_add_u32_e32 v226, s92, v167
	v_lshlrev_b32_e32 v226, 10, v226
	v_lshl_add_u32 v226, v227, 4, v226
	v_add_u32_e32 v226, s93, v226
	v_lshlrev_b32_e32 v144, 1, v226
	v_add_u32_e32 v166, 0x4000, v248
	v_add_u32_e32 v226, 0x4000, v250
	v_add_u32_e32 v167, 0x4000, v249
	v_add_u32_e32 v227, 0x4000, v251
	s_waitcnt lgkmcnt(0)
	s_mov_b32 s22, 0
	s_lshr_b32 s62, s22, 2
	s_lshl_b32 s62, s62, 6
	s_add_u32 s62, s62, s20
	s_lshl_b32 s62, s62, 18
	s_and_b32 s63, s22, 3
	s_lshl_b32 s92, s63, 9
	s_add_u32 s62, s62, s92
	s_add_u32 s24, s6, s62
	s_addc_u32 s25, s7, 0
	s_lshl_b32 s92, s2, 2
	s_add_u32 s92, s92, s63
	s_lshl_b32 s92, s92, 10
	s_add_u32 s92, s92, s21
	s_lshl_b32 s93, s92, 9
	s_add_u32 s26, s18, s93
	s_addc_u32 s27, s19, 0
	s_barrier
	s_add_u32 m0, s56, 0x0
	s_nop 0
	global_load_lds_dwordx4 v236, s[24:25]
	s_add_u32 m0, s56, 0x400
	s_nop 0
	global_load_lds_dwordx4 v237, s[24:25]
	s_add_u32 m0, s56, 0x800
	s_nop 0
	global_load_lds_dwordx4 v238, s[24:25]
	s_add_u32 m0, s56, 0xc00
	s_nop 0
	global_load_lds_dwordx4 v239, s[24:25]
	s_add_u32 s24, s24, 128
	s_addc_u32 s25, s25, 0
	s_add_u32 m0, s56, 0x4000
	s_nop 0
	global_load_lds_dwordx4 v240, s[26:27]
	s_add_u32 m0, s56, 0x4400
	s_nop 0
	global_load_lds_dwordx4 v241, s[26:27]
	s_add_u32 m0, s56, 0x4800
	s_nop 0
	global_load_lds_dwordx4 v242, s[26:27]
	s_add_u32 m0, s56, 0x4c00
	s_nop 0
	global_load_lds_dwordx4 v243, s[26:27]
	s_add_u32 s26, s26, 128
	s_addc_u32 s27, s27, 0
	s_add_u32 m0, s56, 0x8000
	s_nop 0
	global_load_lds_dwordx4 v236, s[24:25]
	s_add_u32 m0, s56, 0x8400
	s_nop 0
	global_load_lds_dwordx4 v237, s[24:25]
	s_add_u32 m0, s56, 0x8800
	s_nop 0
	global_load_lds_dwordx4 v238, s[24:25]
	s_add_u32 m0, s56, 0x8c00
	s_nop 0
	global_load_lds_dwordx4 v239, s[24:25]
	s_add_u32 s24, s24, 128
	s_addc_u32 s25, s25, 0
	s_add_u32 m0, s56, 0xc000
	s_nop 0
	global_load_lds_dwordx4 v240, s[26:27]
	s_add_u32 m0, s56, 0xc400
	s_nop 0
	global_load_lds_dwordx4 v241, s[26:27]
	s_add_u32 m0, s56, 0xc800
	s_nop 0
	global_load_lds_dwordx4 v242, s[26:27]
	s_add_u32 m0, s56, 0xcc00
	s_nop 0
	global_load_lds_dwordx4 v243, s[26:27]
	s_add_u32 s26, s26, 128
	s_addc_u32 s27, s27, 0
	s_waitcnt vmcnt(8)
	s_barrier
	ds_read_b128 v[168:171], v248 offset:0
	ds_read_b128 v[184:187], v250 offset:16384
	ds_read_b128 v[172:175], v248 offset:2048
	ds_read_b128 v[188:191], v250 offset:16896
	ds_read_b128 v[176:179], v248 offset:4096
	ds_read_b128 v[192:195], v250 offset:17408
	ds_read_b128 v[180:183], v248 offset:6144
	ds_read_b128 v[196:199], v250 offset:17920

; template <int NI> ...
;     ...
;   for (int kt = 0; kt < nk; kt += 2) {
;     G_LOAD(a0, b0, min((kt + 2) * 32, klast));
;     G_COMPUTE(0);
;     G_WRITE(a1, b1, 1);
;     __syncthreads();
;     G_LOAD(a1, b1, min((kt + 3) * 32, klast));
;     G_COMPUTE(1);
;     G_WRITE(a0, b0, 0);
;     __syncthreads();
;   }
.Lmg4_nozero:
	s_waitcnt lgkmcnt(0)
	s_add_u32 m0, s56, 0x10000
	s_nop 0
	global_load_lds_dwordx4 v236, s[24:25]
	s_add_u32 m0, s56, 0x10400
	s_nop 0
	global_load_lds_dwordx4 v237, s[24:25]
	s_add_u32 m0, s56, 0x10800
	s_nop 0
	global_load_lds_dwordx4 v238, s[24:25]
	s_add_u32 m0, s56, 0x10c00
	s_nop 0
	global_load_lds_dwordx4 v239, s[24:25]
	s_add_u32 s24, s24, 128
	s_addc_u32 s25, s25, 0
	v_mfma_f32_16x16x32_bf16 v[0:3], v[184:187], v[168:171], 0
	ds_read_b128 v[200:203], v249 offset:0
	v_mfma_f32_16x16x32_bf16 v[4:7], v[188:191], v[168:171], 0
	ds_read_b128 v[216:219], v251 offset:16384
	v_mfma_f32_16x16x32_bf16 v[8:11], v[192:195], v[168:171], 0
	ds_read_b128 v[204:207], v249 offset:2048
	v_mfma_f32_16x16x32_bf16 v[12:15], v[196:199], v[168:171], 0
	ds_read_b128 v[220:223], v251 offset:16896
	v_mfma_f32_16x16x32_bf16 v[16:19], v[184:187], v[172:175], 0
	ds_read_b128 v[208:211], v249 offset:4096
	v_mfma_f32_16x16x32_bf16 v[20:23], v[188:191], v[172:175], 0
	ds_read_b128 v[228:231], v251 offset:17408
	v_mfma_f32_16x16x32_bf16 v[24:27], v[192:195], v[172:175], 0
	ds_read_b128 v[212:215], v249 offset:6144
	v_mfma_f32_16x16x32_bf16 v[28:31], v[196:199], v[172:175], 0
	ds_read_b128 v[232:235], v251 offset:17920
	v_mfma_f32_16x16x32_bf16 v[32:35], v[184:187], v[176:179], 0
	v_mfma_f32_16x16x32_bf16 v[36:39], v[188:191], v[176:179], 0
	v_mfma_f32_16x16x32_bf16 v[40:43], v[192:195], v[176:179], 0
	v_mfma_f32_16x16x32_bf16 v[44:47], v[196:199], v[176:179], 0
	v_mfma_f32_16x16x32_bf16 v[48:51], v[184:187], v[180:183], 0
	v_mfma_f32_16x16x32_bf16 v[52:55], v[188:191], v[180:183], 0
	v_mfma_f32_16x16x32_bf16 v[56:59], v[192:195], v[180:183], 0
	v_mfma_f32_16x16x32_bf16 v[60:63], v[196:199], v[180:183], 0
	s_waitcnt vmcnt(4) lgkmcnt(0)
	s_barrier
	s_add_u32 m0, s56, 0x0
	s_nop 0
	global_load_lds_dwordx4 v240, s[26:27]
	s_add_u32 m0, s56, 0x400
	s_nop 0
	global_load_lds_dwordx4 v241, s[26:27]
	s_add_u32 m0, s56, 0x800
	s_nop 0
	global_load_lds_dwordx4 v242, s[26:27]
	s_add_u32 m0, s56, 0xc00
	s_nop 0
	global_load_lds_dwordx4 v243, s[26:27]
	s_add_u32 s26, s26, 128
	s_addc_u32 s27, s27, 0
	v_mfma_f32_16x16x32_bf16 v[0:3], v[216:219], v[200:203], v[0:3]
	ds_read_b128 v[168:171], v248 offset:32768
	v_mfma_f32_16x16x32_bf16 v[4:7], v[220:223], v[200:203], v[4:7]
	ds_read_b128 v[184:187], v250 offset:49152
	v_mfma_f32_16x16x32_bf16 v[8:11], v[228:231], v[200:203], v[8:11]
	ds_read_b128 v[172:175], v248 offset:34816
	v_mfma_f32_16x16x32_bf16 v[12:15], v[232:235], v[200:203], v[12:15]
	ds_read_b128 v[188:191], v250 offset:49664
	v_mfma_f32_16x16x32_bf16 v[16:19], v[216:219], v[204:207], v[16:19]
	ds_read_b128 v[176:179], v248 offset:36864
	v_mfma_f32_16x16x32_bf16 v[20:23], v[220:223], v[204:207], v[20:23]
	ds_read_b128 v[192:195], v250 offset:50176
	v_mfma_f32_16x16x32_bf16 v[24:27], v[228:231], v[204:207], v[24:27]
	ds_read_b128 v[180:183], v248 offset:38912
	v_mfma_f32_16x16x32_bf16 v[28:31], v[232:235], v[204:207], v[28:31]
	ds_read_b128 v[196:199], v250 offset:50688
	v_mfma_f32_16x16x32_bf16 v[32:35], v[216:219], v[208:211], v[32:35]
	v_mfma_f32_16x16x32_bf16 v[36:39], v[220:223], v[208:211], v[36:39]
	v_mfma_f32_16x16x32_bf16 v[40:43], v[228:231], v[208:211], v[40:43]
	v_mfma_f32_16x16x32_bf16 v[44:47], v[232:235], v[208:211], v[44:47]
	v_mfma_f32_16x16x32_bf16 v[48:51], v[216:219], v[212:215], v[48:51]
	v_mfma_f32_16x16x32_bf16 v[52:55], v[220:223], v[212:215], v[52:55]
	v_mfma_f32_16x16x32_bf16 v[56:59], v[228:231], v[212:215], v[56:59]
	v_mfma_f32_16x16x32_bf16 v[60:63], v[232:235], v[212:215], v[60:63]
	s_waitcnt lgkmcnt(0)
	s_add_u32 m0, s56, 0x4000
	s_nop 0
	global_load_lds_dwordx4 v236, s[24:25]
	s_add_u32 m0, s56, 0x4400
	s_nop 0
	global_load_lds_dwordx4 v237, s[24:25]
	s_add_u32 m0, s56, 0x4800
	s_nop 0
	global_load_lds_dwordx4 v238, s[24:25]
	s_add_u32 m0, s56, 0x4c00
	s_nop 0
	global_load_lds_dwordx4 v239, s[24:25]
	s_add_u32 s24, s24, 128
	s_addc_u32 s25, s25, 0
	v_mfma_f32_16x16x32_bf16 v[0:3], v[184:187], v[168:171], v[0:3]
	ds_read_b128 v[200:203], v249 offset:32768
	v_mfma_f32_16x16x32_bf16 v[4:7], v[188:191], v[168:171], v[4:7]
	ds_read_b128 v[216:219], v251 offset:49152
	v_mfma_f32_16x16x32_bf16 v[8:11], v[192:195], v[168:171], v[8:11]
	ds_read_b128 v[204:207], v249 offset:34816
	v_mfma_f32_16x16x32_bf16 v[12:15], v[196:199], v[168:171], v[12:15]
	ds_read_b128 v[220:223], v251 offset:49664
	v_mfma_f32_16x16x32_bf16 v[16:19], v[184:187], v[172:175], v[16:19]
	ds_read_b128 v[208:211], v249 offset:36864
	v_mfma_f32_16x16x32_bf16 v[20:23], v[188:191], v[172:175], v[20:23]
	ds_read_b128 v[228:231], v251 offset:50176
	v_mfma_f32_16x16x32_bf16 v[24:27], v[192:195], v[172:175], v[24:27]
	ds_read_b128 v[212:215], v249 offset:38912
	v_mfma_f32_16x16x32_bf16 v[28:31], v[196:199], v[172:175], v[28:31]
	ds_read_b128 v[232:235], v251 offset:50688
	v_mfma_f32_16x16x32_bf16 v[32:35], v[184:187], v[176:179], v[32:35]
	v_mfma_f32_16x16x32_bf16 v[36:39], v[188:191], v[176:179], v[36:39]
	v_mfma_f32_16x16x32_bf16 v[40:43], v[192:195], v[176:179], v[40:43]
	v_mfma_f32_16x16x32_bf16 v[44:47], v[196:199], v[176:179], v[44:47]
	v_mfma_f32_16x16x32_bf16 v[48:51], v[184:187], v[180:183], v[48:51]
	v_mfma_f32_16x16x32_bf16 v[52:55], v[188:191], v[180:183], v[52:55]
	v_mfma_f32_16x16x32_bf16 v[56:59], v[192:195], v[180:183], v[56:59]
	v_mfma_f32_16x16x32_bf16 v[60:63], v[196:199], v[180:183], v[60:63]
	s_waitcnt vmcnt(4) lgkmcnt(0)
	s_barrier
; template <int NI> ...
;     ...
;   for (int kt = 0; kt < nk; kt += 2) {
;     G_LOAD(a0, b0, min((kt + 2) * 32, klast));
;     G_COMPUTE(0);
;     G_WRITE(a1, b1, 1);
;     __syncthreads();
;     G_LOAD(a1, b1, min((kt + 3) * 32, klast));
;     G_COMPUTE(1);
;     G_WRITE(a0, b0, 0);
;     __syncthreads();
;   }
; __device__ void phase_merge4(CParams& p, int l, int tm, int tn, char* smem) {
;     ...
;     f32x4 acc[4][4];
;     zero_acc<4>(acc);
;     asm volatile("" : "+v"(tid2));
;     gemm_mainloop<4>(p.hbuf + (size_t)row0 * DM, DM,
;                      p.WgT + (((size_t)l * 4 + kb) * 1024 + col0) * 1024, 1024, 1024, sA, sB, acc, tid2);
	s_add_u32 m0, s56, 0x8000
	s_nop 0
	global_load_lds_dwordx4 v240, s[26:27]
	s_add_u32 m0, s56, 0x8400
	s_nop 0
	global_load_lds_dwordx4 v241, s[26:27]
	s_add_u32 m0, s56, 0x8800
	s_nop 0
	global_load_lds_dwordx4 v242, s[26:27]
	s_add_u32 m0, s56, 0x8c00
	s_nop 0
	global_load_lds_dwordx4 v243, s[26:27]
	s_add_u32 s26, s26, 128
	s_addc_u32 s27, s27, 0
	v_mfma_f32_16x16x32_bf16 v[0:3], v[216:219], v[200:203], v[0:3]
	ds_read_b128 v[168:171], v166 offset:49152
	v_mfma_f32_16x16x32_bf16 v[4:7], v[220:223], v[200:203], v[4:7]
	ds_read_b128 v[184:187], v250 offset:0
	v_mfma_f32_16x16x32_bf16 v[8:11], v[228:231], v[200:203], v[8:11]
	ds_read_b128 v[172:175], v166 offset:51200
	v_mfma_f32_16x16x32_bf16 v[12:15], v[232:235], v[200:203], v[12:15]
	ds_read_b128 v[188:191], v250 offset:512
	v_mfma_f32_16x16x32_bf16 v[16:19], v[216:219], v[204:207], v[16:19]
	ds_read_b128 v[176:179], v166 offset:53248
	v_mfma_f32_16x16x32_bf16 v[20:23], v[220:223], v[204:207], v[20:23]
	ds_read_b128 v[192:195], v250 offset:1024
	v_mfma_f32_16x16x32_bf16 v[24:27], v[228:231], v[204:207], v[24:27]
	ds_read_b128 v[180:183], v166 offset:55296
	v_mfma_f32_16x16x32_bf16 v[28:31], v[232:235], v[204:207], v[28:31]
	ds_read_b128 v[196:199], v250 offset:1536
	v_mfma_f32_16x16x32_bf16 v[32:35], v[216:219], v[208:211], v[32:35]
	v_mfma_f32_16x16x32_bf16 v[36:39], v[220:223], v[208:211], v[36:39]
	v_mfma_f32_16x16x32_bf16 v[40:43], v[228:231], v[208:211], v[40:43]
	v_mfma_f32_16x16x32_bf16 v[44:47], v[232:235], v[208:211], v[44:47]
	v_mfma_f32_16x16x32_bf16 v[48:51], v[216:219], v[212:215], v[48:51]
	v_mfma_f32_16x16x32_bf16 v[52:55], v[220:223], v[212:215], v[52:55]
	v_mfma_f32_16x16x32_bf16 v[56:59], v[228:231], v[212:215], v[56:59]
	v_mfma_f32_16x16x32_bf16 v[60:63], v[232:235], v[212:215], v[60:63]
	s_waitcnt lgkmcnt(0)
	s_mov_b64 s[24:25], s[50:51]
	s_add_u32 m0, s56, 0xc000
	s_nop 0
	global_load_lds_dwordx4 v236, s[24:25]
	s_add_u32 m0, s56, 0xc400
	s_nop 0
	global_load_lds_dwordx4 v237, s[24:25]
	s_add_u32 m0, s56, 0xc800
	s_nop 0
	global_load_lds_dwordx4 v238, s[24:25]
	s_add_u32 m0, s56, 0xcc00
	s_nop 0
	global_load_lds_dwordx4 v239, s[24:25]
	s_add_u32 s24, s24, 128
	s_addc_u32 s25, s25, 0
	v_mfma_f32_16x16x32_bf16 v[0:3], v[184:187], v[168:171], v[0:3]
	ds_read_b128 v[200:203], v167 offset:49152
	v_mfma_f32_16x16x32_bf16 v[4:7], v[188:191], v[168:171], v[4:7]
	ds_read_b128 v[216:219], v251 offset:0
	v_mfma_f32_16x16x32_bf16 v[8:11], v[192:195], v[168:171], v[8:11]
	ds_read_b128 v[204:207], v167 offset:51200
	v_mfma_f32_16x16x32_bf16 v[12:15], v[196:199], v[168:171], v[12:15]
	ds_read_b128 v[220:223], v251 offset:512
	v_mfma_f32_16x16x32_bf16 v[16:19], v[184:187], v[172:175], v[16:19]
	ds_read_b128 v[208:211], v167 offset:53248
	v_mfma_f32_16x16x32_bf16 v[20:23], v[188:191], v[172:175], v[20:23]
	ds_read_b128 v[228:231], v251 offset:1024
	v_mfma_f32_16x16x32_bf16 v[24:27], v[192:195], v[172:175], v[24:27]
	ds_read_b128 v[212:215], v167 offset:55296
	v_mfma_f32_16x16x32_bf16 v[28:31], v[196:199], v[172:175], v[28:31]
	ds_read_b128 v[232:235], v251 offset:1536
	v_mfma_f32_16x16x32_bf16 v[32:35], v[184:187], v[176:179], v[32:35]
	v_mfma_f32_16x16x32_bf16 v[36:39], v[188:191], v[176:179], v[36:39]
	v_mfma_f32_16x16x32_bf16 v[40:43], v[192:195], v[176:179], v[40:43]
	v_mfma_f32_16x16x32_bf16 v[44:47], v[196:199], v[176:179], v[44:47]
	v_mfma_f32_16x16x32_bf16 v[48:51], v[184:187], v[180:183], v[48:51]
	v_mfma_f32_16x16x32_bf16 v[52:55], v[188:191], v[180:183], v[52:55]
	v_mfma_f32_16x16x32_bf16 v[56:59], v[192:195], v[180:183], v[56:59]
	v_mfma_f32_16x16x32_bf16 v[60:63], v[196:199], v[180:183], v[60:63]
	s_waitcnt vmcnt(4) lgkmcnt(0)
	s_barrier
	s_mov_b64 s[26:27], s[54:55]
	s_add_u32 m0, s56, 0x10000
	s_nop 0
	global_load_lds_dwordx4 v244, s[26:27]
	s_add_u32 m0, s56, 0x10400
	s_nop 0
	global_load_lds_dwordx4 v245, s[26:27]
	s_add_u32 m0, s56, 0x10800
	s_nop 0
	global_load_lds_dwordx4 v246, s[26:27]
	s_add_u32 m0, s56, 0x10c00
	s_nop 0
	global_load_lds_dwordx4 v247, s[26:27]
	s_add_u32 s26, s26, 128
	s_addc_u32 s27, s27, 0
	v_mfma_f32_16x16x32_bf16 v[0:3], v[216:219], v[200:203], v[0:3]
	ds_read_b128 v[168:171], v248 offset:16384
	v_mfma_f32_16x16x32_bf16 v[4:7], v[220:223], v[200:203], v[4:7]
	ds_read_b128 v[184:187], v250 offset:32768
	v_mfma_f32_16x16x32_bf16 v[8:11], v[228:231], v[200:203], v[8:11]
	ds_read_b128 v[172:175], v248 offset:18432
	v_mfma_f32_16x16x32_bf16 v[12:15], v[232:235], v[200:203], v[12:15]
	ds_read_b128 v[188:191], v250 offset:33280
	v_mfma_f32_16x16x32_bf16 v[16:19], v[216:219], v[204:207], v[16:19]
	ds_read_b128 v[176:179], v248 offset:20480
	v_mfma_f32_16x16x32_bf16 v[20:23], v[220:223], v[204:207], v[20:23]
	ds_read_b128 v[192:195], v250 offset:33792
	v_mfma_f32_16x16x32_bf16 v[24:27], v[228:231], v[204:207], v[24:27]
	ds_read_b128 v[180:183], v248 offset:22528
	v_mfma_f32_16x16x32_bf16 v[28:31], v[232:235], v[204:207], v[28:31]
	ds_read_b128 v[196:199], v250 offset:34304
	v_mfma_f32_16x16x32_bf16 v[32:35], v[216:219], v[208:211], v[32:35]
	v_mfma_f32_16x16x32_bf16 v[36:39], v[220:223], v[208:211], v[36:39]
	v_mfma_f32_16x16x32_bf16 v[40:43], v[228:231], v[208:211], v[40:43]
	v_mfma_f32_16x16x32_bf16 v[44:47], v[232:235], v[208:211], v[44:47]
	v_mfma_f32_16x16x32_bf16 v[48:51], v[216:219], v[212:215], v[48:51]
	v_mfma_f32_16x16x32_bf16 v[52:55], v[220:223], v[212:215], v[52:55]
	v_mfma_f32_16x16x32_bf16 v[56:59], v[228:231], v[212:215], v[56:59]
	v_mfma_f32_16x16x32_bf16 v[60:63], v[232:235], v[212:215], v[60:63]
	s_waitcnt lgkmcnt(0)
; template <int NI> ...
;     ...
;   for (int kt = 0; kt < nk; kt += 2) {
;     G_LOAD(a0, b0, min((kt + 2) * 32, klast));
;     G_COMPUTE(0);
;     G_WRITE(a1, b1, 1);
;     __syncthreads();
;     G_LOAD(a1, b1, min((kt + 3) * 32, klast));
;     G_COMPUTE(1);
;     G_WRITE(a0, b0, 0);
;     __syncthreads();
;   }
; __device__ void phase_merge4(CParams& p, int l, int tm, int tn, char* smem) {
;     ...
; #pragma unroll
;       for (int mi = 0; mi < 4; mi++)
; #pragma unroll
;         for (int ni = 0; ni < 4; ni++) {
;           pk[mi][ni][0] = (unsigned)f2bf(acc[mi][ni][0]) | ((unsigned)f2bf(acc[mi][ni][1]) << 16);
;           pk[mi][ni][1] = (unsigned)f2bf(acc[mi][ni][2]) | ((unsigned)f2bf(acc[mi][ni][3]) << 16);
;         }
;     }
;     f32x4 acc[4][4];
;     zero_acc<4>(acc);
;     asm volatile("" : "+v"(tid2));
;     gemm_mainloop<4>(p.hbuf + (size_t)row0 * DM, DM,
;                      p.WgT + (((size_t)l * 4 + kb) * 1024 + col0) * 1024, 1024, 1024, sA, sB, acc, tid2);
	s_add_u32 m0, s56, 0x0
	s_nop 0
	global_load_lds_dwordx4 v236, s[24:25]
	s_add_u32 m0, s56, 0x400
	s_nop 0
	global_load_lds_dwordx4 v237, s[24:25]
	s_add_u32 m0, s56, 0x800
	s_nop 0
	global_load_lds_dwordx4 v238, s[24:25]
	s_add_u32 m0, s56, 0xc00
	s_nop 0
	global_load_lds_dwordx4 v239, s[24:25]
	s_add_u32 s24, s24, 128
	s_addc_u32 s25, s25, 0
	v_mfma_f32_16x16x32_bf16 v[0:3], v[184:187], v[168:171], v[0:3]
	ds_read_b128 v[200:203], v249 offset:16384
	v_mfma_f32_16x16x32_bf16 v[4:7], v[188:191], v[168:171], v[4:7]
	ds_read_b128 v[216:219], v251 offset:32768
	v_mfma_f32_16x16x32_bf16 v[8:11], v[192:195], v[168:171], v[8:11]
	ds_read_b128 v[204:207], v249 offset:18432
	v_mfma_f32_16x16x32_bf16 v[12:15], v[196:199], v[168:171], v[12:15]
	ds_read_b128 v[220:223], v251 offset:33280
	v_mfma_f32_16x16x32_bf16 v[16:19], v[184:187], v[172:175], v[16:19]
	ds_read_b128 v[208:211], v249 offset:20480
	v_mfma_f32_16x16x32_bf16 v[20:23], v[188:191], v[172:175], v[20:23]
	ds_read_b128 v[228:231], v251 offset:33792
	v_mfma_f32_16x16x32_bf16 v[24:27], v[192:195], v[172:175], v[24:27]
	ds_read_b128 v[212:215], v249 offset:22528
	v_mfma_f32_16x16x32_bf16 v[28:31], v[196:199], v[172:175], v[28:31]
	ds_read_b128 v[232:235], v251 offset:34304
	v_mfma_f32_16x16x32_bf16 v[32:35], v[184:187], v[176:179], v[32:35]
	v_mfma_f32_16x16x32_bf16 v[36:39], v[188:191], v[176:179], v[36:39]
	v_mfma_f32_16x16x32_bf16 v[40:43], v[192:195], v[176:179], v[40:43]
	v_mfma_f32_16x16x32_bf16 v[44:47], v[196:199], v[176:179], v[44:47]
	v_mfma_f32_16x16x32_bf16 v[48:51], v[184:187], v[180:183], v[48:51]
	v_mfma_f32_16x16x32_bf16 v[52:55], v[188:191], v[180:183], v[52:55]
	v_mfma_f32_16x16x32_bf16 v[56:59], v[192:195], v[180:183], v[56:59]
	v_mfma_f32_16x16x32_bf16 v[60:63], v[196:199], v[180:183], v[60:63]
	s_waitcnt vmcnt(4) lgkmcnt(0)
	s_barrier
	s_add_u32 m0, s56, 0x4000
	s_nop 0
	global_load_lds_dwordx4 v244, s[26:27]
	s_add_u32 m0, s56, 0x4400
	s_nop 0
	global_load_lds_dwordx4 v245, s[26:27]
	s_add_u32 m0, s56, 0x4800
	s_nop 0
	global_load_lds_dwordx4 v246, s[26:27]
	s_add_u32 m0, s56, 0x4c00
	s_nop 0
	global_load_lds_dwordx4 v247, s[26:27]
	s_add_u32 s26, s26, 128
	s_addc_u32 s27, s27, 0
	v_mfma_f32_16x16x32_bf16 v[0:3], v[216:219], v[200:203], v[0:3]
	ds_read_b128 v[168:171], v248 offset:49152
	v_mfma_f32_16x16x32_bf16 v[4:7], v[220:223], v[200:203], v[4:7]
	ds_read_b128 v[184:187], v226 offset:49152
	v_mfma_f32_16x16x32_bf16 v[8:11], v[228:231], v[200:203], v[8:11]
	ds_read_b128 v[172:175], v248 offset:51200
	v_mfma_f32_16x16x32_bf16 v[12:15], v[232:235], v[200:203], v[12:15]
	ds_read_b128 v[188:191], v226 offset:49664
	v_mfma_f32_16x16x32_bf16 v[16:19], v[216:219], v[204:207], v[16:19]
	ds_read_b128 v[176:179], v248 offset:53248
	v_mfma_f32_16x16x32_bf16 v[20:23], v[220:223], v[204:207], v[20:23]
	ds_read_b128 v[192:195], v226 offset:50176
	v_mfma_f32_16x16x32_bf16 v[24:27], v[228:231], v[204:207], v[24:27]
	ds_read_b128 v[180:183], v248 offset:55296
	v_mfma_f32_16x16x32_bf16 v[28:31], v[232:235], v[204:207], v[28:31]
	ds_read_b128 v[196:199], v226 offset:50688
	v_mfma_f32_16x16x32_bf16 v[32:35], v[216:219], v[208:211], v[32:35]
	v_mfma_f32_16x16x32_bf16 v[36:39], v[220:223], v[208:211], v[36:39]
	v_mfma_f32_16x16x32_bf16 v[40:43], v[228:231], v[208:211], v[40:43]
	v_mfma_f32_16x16x32_bf16 v[44:47], v[232:235], v[208:211], v[44:47]
	v_mfma_f32_16x16x32_bf16 v[48:51], v[216:219], v[212:215], v[48:51]
	v_mfma_f32_16x16x32_bf16 v[52:55], v[220:223], v[212:215], v[52:55]
	v_mfma_f32_16x16x32_bf16 v[56:59], v[228:231], v[212:215], v[56:59]
	v_mfma_f32_16x16x32_bf16 v[60:63], v[232:235], v[212:215], v[60:63]
	s_nop 15
	s_nop 7
	v_cvt_pk_bf16_f32 v128, v0, v1
	v_cvt_pk_bf16_f32 v129, v2, v3
	v_cvt_pk_bf16_f32 v130, v4, v5
	v_cvt_pk_bf16_f32 v131, v6, v7
	v_cvt_pk_bf16_f32 v132, v8, v9
	v_cvt_pk_bf16_f32 v133, v10, v11
	v_cvt_pk_bf16_f32 v134, v12, v13
	v_cvt_pk_bf16_f32 v135, v14, v15
	v_cvt_pk_bf16_f32 v136, v16, v17
	v_cvt_pk_bf16_f32 v137, v18, v19
	v_cvt_pk_bf16_f32 v138, v20, v21
	v_cvt_pk_bf16_f32 v139, v22, v23
	v_cvt_pk_bf16_f32 v140, v24, v25
	v_cvt_pk_bf16_f32 v141, v26, v27
	v_cvt_pk_bf16_f32 v142, v28, v29
	v_cvt_pk_bf16_f32 v143, v30, v31
	v_cvt_pk_bf16_f32 v148, v32, v33
	v_cvt_pk_bf16_f32 v149, v34, v35
	v_cvt_pk_bf16_f32 v150, v36, v37
	v_cvt_pk_bf16_f32 v151, v38, v39
	v_cvt_pk_bf16_f32 v152, v40, v41
	v_cvt_pk_bf16_f32 v153, v42, v43
	v_cvt_pk_bf16_f32 v154, v44, v45
	v_cvt_pk_bf16_f32 v155, v46, v47
	v_cvt_pk_bf16_f32 v156, v48, v49
	v_cvt_pk_bf16_f32 v157, v50, v51
	v_cvt_pk_bf16_f32 v158, v52, v53
	v_cvt_pk_bf16_f32 v159, v54, v55
	v_cvt_pk_bf16_f32 v160, v56, v57
	v_cvt_pk_bf16_f32 v161, v58, v59
	v_cvt_pk_bf16_f32 v162, v60, v61
	v_cvt_pk_bf16_f32 v163, v62, v63
	s_waitcnt lgkmcnt(0)
	s_add_u32 m0, s56, 0x8000
	s_nop 0
	global_load_lds_dwordx4 v236, s[24:25]
	s_add_u32 m0, s56, 0x8400
	s_nop 0
	global_load_lds_dwordx4 v237, s[24:25]
	s_add_u32 m0, s56, 0x8800
	s_nop 0
	global_load_lds_dwordx4 v238, s[24:25]
	s_add_u32 m0, s56, 0x8c00
	s_nop 0
	global_load_lds_dwordx4 v239, s[24:25]
	s_add_u32 s24, s24, 128
	s_addc_u32 s25, s25, 0
	v_mfma_f32_16x16x32_bf16 v[0:3], v[184:187], v[168:171], 0
	ds_read_b128 v[200:203], v249 offset:49152
	v_mfma_f32_16x16x32_bf16 v[4:7], v[188:191], v[168:171], 0
	ds_read_b128 v[216:219], v227 offset:49152
	v_mfma_f32_16x16x32_bf16 v[8:11], v[192:195], v[168:171], 0
	ds_read_b128 v[204:207], v249 offset:51200
	v_mfma_f32_16x16x32_bf16 v[12:15], v[196:199], v[168:171], 0
	ds_read_b128 v[220:223], v227 offset:49664
	v_mfma_f32_16x16x32_bf16 v[16:19], v[184:187], v[172:175], 0
	ds_read_b128 v[208:211], v249 offset:53248
	v_mfma_f32_16x16x32_bf16 v[20:23], v[188:191], v[172:175], 0
	ds_read_b128 v[228:231], v227 offset:50176
	v_mfma_f32_16x16x32_bf16 v[24:27], v[192:195], v[172:175], 0
	ds_read_b128 v[212:215], v249 offset:55296
	v_mfma_f32_16x16x32_bf16 v[28:31], v[196:199], v[172:175], 0
	ds_read_b128 v[232:235], v227 offset:50688
	v_mfma_f32_16x16x32_bf16 v[32:35], v[184:187], v[176:179], 0
	v_mfma_f32_16x16x32_bf16 v[36:39], v[188:191], v[176:179], 0
	v_mfma_f32_16x16x32_bf16 v[40:43], v[192:195], v[176:179], 0
	v_mfma_f32_16x16x32_bf16 v[44:47], v[196:199], v[176:179], 0
	v_mfma_f32_16x16x32_bf16 v[48:51], v[184:187], v[180:183], 0
	v_mfma_f32_16x16x32_bf16 v[52:55], v[188:191], v[180:183], 0
	v_mfma_f32_16x16x32_bf16 v[56:59], v[192:195], v[180:183], 0
	v_mfma_f32_16x16x32_bf16 v[60:63], v[196:199], v[180:183], 0
	s_waitcnt vmcnt(4) lgkmcnt(0)
	s_barrier
; template <int NI> ...
;     ...
;   for (int kt = 0; kt < nk; kt += 2) {
;     G_LOAD(a0, b0, min((kt + 2) * 32, klast));
;     G_COMPUTE(0);
;     G_WRITE(a1, b1, 1);
;     __syncthreads();
;     G_LOAD(a1, b1, min((kt + 3) * 32, klast));
;     G_COMPUTE(1);
;     G_WRITE(a0, b0, 0);
;     __syncthreads();
;   }
	s_add_u32 m0, s56, 0xc000
	s_nop 0
	global_load_lds_dwordx4 v244, s[26:27]
	s_add_u32 m0, s56, 0xc400
	s_nop 0
	global_load_lds_dwordx4 v245, s[26:27]
	s_add_u32 m0, s56, 0xc800
	s_nop 0
	global_load_lds_dwordx4 v246, s[26:27]
	s_add_u32 m0, s56, 0xcc00
	s_nop 0
	global_load_lds_dwordx4 v247, s[26:27]
	s_add_u32 s26, s26, 128
	s_addc_u32 s27, s27, 0
	v_mfma_f32_16x16x32_bf16 v[0:3], v[216:219], v[200:203], v[0:3]
	ds_read_b128 v[168:171], v248 offset:0
	v_mfma_f32_16x16x32_bf16 v[4:7], v[220:223], v[200:203], v[4:7]
	ds_read_b128 v[184:187], v250 offset:16384
	v_mfma_f32_16x16x32_bf16 v[8:11], v[228:231], v[200:203], v[8:11]
	ds_read_b128 v[172:175], v248 offset:2048
	v_mfma_f32_16x16x32_bf16 v[12:15], v[232:235], v[200:203], v[12:15]
	ds_read_b128 v[188:191], v250 offset:16896
	v_mfma_f32_16x16x32_bf16 v[16:19], v[216:219], v[204:207], v[16:19]
	ds_read_b128 v[176:179], v248 offset:4096
	v_mfma_f32_16x16x32_bf16 v[20:23], v[220:223], v[204:207], v[20:23]
	ds_read_b128 v[192:195], v250 offset:17408
	v_mfma_f32_16x16x32_bf16 v[24:27], v[228:231], v[204:207], v[24:27]
	ds_read_b128 v[180:183], v248 offset:6144
	v_mfma_f32_16x16x32_bf16 v[28:31], v[232:235], v[204:207], v[28:31]
	ds_read_b128 v[196:199], v250 offset:17920
	v_mfma_f32_16x16x32_bf16 v[32:35], v[216:219], v[208:211], v[32:35]
	v_mfma_f32_16x16x32_bf16 v[36:39], v[220:223], v[208:211], v[36:39]
	v_mfma_f32_16x16x32_bf16 v[40:43], v[228:231], v[208:211], v[40:43]
	v_mfma_f32_16x16x32_bf16 v[44:47], v[232:235], v[208:211], v[44:47]
	v_mfma_f32_16x16x32_bf16 v[48:51], v[216:219], v[212:215], v[48:51]
	v_mfma_f32_16x16x32_bf16 v[52:55], v[220:223], v[212:215], v[52:55]
	v_mfma_f32_16x16x32_bf16 v[56:59], v[228:231], v[212:215], v[56:59]
	v_mfma_f32_16x16x32_bf16 v[60:63], v[232:235], v[212:215], v[60:63]
	s_waitcnt lgkmcnt(0)
	s_add_u32 m0, s56, 0x10000
	s_nop 0
	global_load_lds_dwordx4 v236, s[24:25]
	s_add_u32 m0, s56, 0x10400
	s_nop 0
	global_load_lds_dwordx4 v237, s[24:25]
	s_add_u32 m0, s56, 0x10800
	s_nop 0
	global_load_lds_dwordx4 v238, s[24:25]
	s_add_u32 m0, s56, 0x10c00
	s_nop 0
	global_load_lds_dwordx4 v239, s[24:25]
	s_add_u32 s24, s24, 128
	s_addc_u32 s25, s25, 0
	v_mfma_f32_16x16x32_bf16 v[0:3], v[184:187], v[168:171], v[0:3]
	ds_read_b128 v[200:203], v249 offset:0
	v_mfma_f32_16x16x32_bf16 v[4:7], v[188:191], v[168:171], v[4:7]
	ds_read_b128 v[216:219], v251 offset:16384
	v_mfma_f32_16x16x32_bf16 v[8:11], v[192:195], v[168:171], v[8:11]
	ds_read_b128 v[204:207], v249 offset:2048
	v_mfma_f32_16x16x32_bf16 v[12:15], v[196:199], v[168:171], v[12:15]
	ds_read_b128 v[220:223], v251 offset:16896
	v_mfma_f32_16x16x32_bf16 v[16:19], v[184:187], v[172:175], v[16:19]
	ds_read_b128 v[208:211], v249 offset:4096
	v_mfma_f32_16x16x32_bf16 v[20:23], v[188:191], v[172:175], v[20:23]
	ds_read_b128 v[228:231], v251 offset:17408
	v_mfma_f32_16x16x32_bf16 v[24:27], v[192:195], v[172:175], v[24:27]
	ds_read_b128 v[212:215], v249 offset:6144
	v_mfma_f32_16x16x32_bf16 v[28:31], v[196:199], v[172:175], v[28:31]
	ds_read_b128 v[232:235], v251 offset:17920
	v_mfma_f32_16x16x32_bf16 v[32:35], v[184:187], v[176:179], v[32:35]
	v_mfma_f32_16x16x32_bf16 v[36:39], v[188:191], v[176:179], v[36:39]
	v_mfma_f32_16x16x32_bf16 v[40:43], v[192:195], v[176:179], v[40:43]
	v_mfma_f32_16x16x32_bf16 v[44:47], v[196:199], v[176:179], v[44:47]
	v_mfma_f32_16x16x32_bf16 v[48:51], v[184:187], v[180:183], v[48:51]
	v_mfma_f32_16x16x32_bf16 v[52:55], v[188:191], v[180:183], v[52:55]
	v_mfma_f32_16x16x32_bf16 v[56:59], v[192:195], v[180:183], v[56:59]
	v_mfma_f32_16x16x32_bf16 v[60:63], v[196:199], v[180:183], v[60:63]
	s_waitcnt vmcnt(4) lgkmcnt(0)
	s_barrier
	s_add_u32 m0, s56, 0x0
	s_nop 0
	global_load_lds_dwordx4 v244, s[26:27]
	s_add_u32 m0, s56, 0x400
	s_nop 0
	global_load_lds_dwordx4 v245, s[26:27]
	s_add_u32 m0, s56, 0x800
	s_nop 0
	global_load_lds_dwordx4 v246, s[26:27]
	s_add_u32 m0, s56, 0xc00
	s_nop 0
	global_load_lds_dwordx4 v247, s[26:27]
	s_add_u32 s26, s26, 128
	s_addc_u32 s27, s27, 0
	v_mfma_f32_16x16x32_bf16 v[0:3], v[216:219], v[200:203], v[0:3]
	ds_read_b128 v[168:171], v248 offset:32768
	v_mfma_f32_16x16x32_bf16 v[4:7], v[220:223], v[200:203], v[4:7]
	ds_read_b128 v[184:187], v250 offset:49152
	v_mfma_f32_16x16x32_bf16 v[8:11], v[228:231], v[200:203], v[8:11]
	ds_read_b128 v[172:175], v248 offset:34816
	v_mfma_f32_16x16x32_bf16 v[12:15], v[232:235], v[200:203], v[12:15]
	ds_read_b128 v[188:191], v250 offset:49664
	v_mfma_f32_16x16x32_bf16 v[16:19], v[216:219], v[204:207], v[16:19]
	ds_read_b128 v[176:179], v248 offset:36864
	v_mfma_f32_16x16x32_bf16 v[20:23], v[220:223], v[204:207], v[20:23]
	ds_read_b128 v[192:195], v250 offset:50176
	v_mfma_f32_16x16x32_bf16 v[24:27], v[228:231], v[204:207], v[24:27]
	ds_read_b128 v[180:183], v248 offset:38912
	v_mfma_f32_16x16x32_bf16 v[28:31], v[232:235], v[204:207], v[28:31]
	ds_read_b128 v[196:199], v250 offset:50688
	v_mfma_f32_16x16x32_bf16 v[32:35], v[216:219], v[208:211], v[32:35]
	v_mfma_f32_16x16x32_bf16 v[36:39], v[220:223], v[208:211], v[36:39]
	v_mfma_f32_16x16x32_bf16 v[40:43], v[228:231], v[208:211], v[40:43]
	v_mfma_f32_16x16x32_bf16 v[44:47], v[232:235], v[208:211], v[44:47]
	v_mfma_f32_16x16x32_bf16 v[48:51], v[216:219], v[212:215], v[48:51]
	v_mfma_f32_16x16x32_bf16 v[52:55], v[220:223], v[212:215], v[52:55]
	v_mfma_f32_16x16x32_bf16 v[56:59], v[228:231], v[212:215], v[56:59]
	v_mfma_f32_16x16x32_bf16 v[60:63], v[232:235], v[212:215], v[60:63]
	s_waitcnt lgkmcnt(0)
; template <int NI> ...
;     ...
;   for (int kt = 0; kt < nk; kt += 2) {
;     G_LOAD(a0, b0, min((kt + 2) * 32, klast));
;     G_COMPUTE(0);
;     G_WRITE(a1, b1, 1);
;     __syncthreads();
;     G_LOAD(a1, b1, min((kt + 3) * 32, klast));
;     G_COMPUTE(1);
;     G_WRITE(a0, b0, 0);
;     __syncthreads();
;   }
	s_add_u32 m0, s56, 0x4000
	s_nop 0
	global_load_lds_dwordx4 v236, s[24:25]
	s_add_u32 m0, s56, 0x4400
	s_nop 0
	global_load_lds_dwordx4 v237, s[24:25]
	s_add_u32 m0, s56, 0x4800
	s_nop 0
	global_load_lds_dwordx4 v238, s[24:25]
	s_add_u32 m0, s56, 0x4c00
	s_nop 0
	global_load_lds_dwordx4 v239, s[24:25]
	s_add_u32 s24, s24, 128
	s_addc_u32 s25, s25, 0
	v_mfma_f32_16x16x32_bf16 v[0:3], v[184:187], v[168:171], v[0:3]
	ds_read_b128 v[200:203], v249 offset:32768
	v_mfma_f32_16x16x32_bf16 v[4:7], v[188:191], v[168:171], v[4:7]
	ds_read_b128 v[216:219], v251 offset:49152
	v_mfma_f32_16x16x32_bf16 v[8:11], v[192:195], v[168:171], v[8:11]
	ds_read_b128 v[204:207], v249 offset:34816
	v_mfma_f32_16x16x32_bf16 v[12:15], v[196:199], v[168:171], v[12:15]
	ds_read_b128 v[220:223], v251 offset:49664
	v_mfma_f32_16x16x32_bf16 v[16:19], v[184:187], v[172:175], v[16:19]
	ds_read_b128 v[208:211], v249 offset:36864
	v_mfma_f32_16x16x32_bf16 v[20:23], v[188:191], v[172:175], v[20:23]
	ds_read_b128 v[228:231], v251 offset:50176
	v_mfma_f32_16x16x32_bf16 v[24:27], v[192:195], v[172:175], v[24:27]
	ds_read_b128 v[212:215], v249 offset:38912
	v_mfma_f32_16x16x32_bf16 v[28:31], v[196:199], v[172:175], v[28:31]
	ds_read_b128 v[232:235], v251 offset:50688
	v_mfma_f32_16x16x32_bf16 v[32:35], v[184:187], v[176:179], v[32:35]
	v_mfma_f32_16x16x32_bf16 v[36:39], v[188:191], v[176:179], v[36:39]
	v_mfma_f32_16x16x32_bf16 v[40:43], v[192:195], v[176:179], v[40:43]
	v_mfma_f32_16x16x32_bf16 v[44:47], v[196:199], v[176:179], v[44:47]
	v_mfma_f32_16x16x32_bf16 v[48:51], v[184:187], v[180:183], v[48:51]
	v_mfma_f32_16x16x32_bf16 v[52:55], v[188:191], v[180:183], v[52:55]
	v_mfma_f32_16x16x32_bf16 v[56:59], v[192:195], v[180:183], v[56:59]
	v_mfma_f32_16x16x32_bf16 v[60:63], v[196:199], v[180:183], v[60:63]
	s_waitcnt vmcnt(4) lgkmcnt(0)
	s_barrier
	s_add_u32 m0, s56, 0x8000
	s_nop 0
	global_load_lds_dwordx4 v244, s[26:27]
	s_add_u32 m0, s56, 0x8400
	s_nop 0
	global_load_lds_dwordx4 v245, s[26:27]
	s_add_u32 m0, s56, 0x8800
	s_nop 0
	global_load_lds_dwordx4 v246, s[26:27]
	s_add_u32 m0, s56, 0x8c00
	s_nop 0
	global_load_lds_dwordx4 v247, s[26:27]
	s_add_u32 s26, s26, 128
	s_addc_u32 s27, s27, 0
	v_mfma_f32_16x16x32_bf16 v[0:3], v[216:219], v[200:203], v[0:3]
	ds_read_b128 v[168:171], v166 offset:49152
	v_mfma_f32_16x16x32_bf16 v[4:7], v[220:223], v[200:203], v[4:7]
	ds_read_b128 v[184:187], v250 offset:0
	v_mfma_f32_16x16x32_bf16 v[8:11], v[228:231], v[200:203], v[8:11]
	ds_read_b128 v[172:175], v166 offset:51200
	v_mfma_f32_16x16x32_bf16 v[12:15], v[232:235], v[200:203], v[12:15]
	ds_read_b128 v[188:191], v250 offset:512
	v_mfma_f32_16x16x32_bf16 v[16:19], v[216:219], v[204:207], v[16:19]
	ds_read_b128 v[176:179], v166 offset:53248
	v_mfma_f32_16x16x32_bf16 v[20:23], v[220:223], v[204:207], v[20:23]
	ds_read_b128 v[192:195], v250 offset:1024
	v_mfma_f32_16x16x32_bf16 v[24:27], v[228:231], v[204:207], v[24:27]
	ds_read_b128 v[180:183], v166 offset:55296
	v_mfma_f32_16x16x32_bf16 v[28:31], v[232:235], v[204:207], v[28:31]
	ds_read_b128 v[196:199], v250 offset:1536
	v_mfma_f32_16x16x32_bf16 v[32:35], v[216:219], v[208:211], v[32:35]
	v_mfma_f32_16x16x32_bf16 v[36:39], v[220:223], v[208:211], v[36:39]
	v_mfma_f32_16x16x32_bf16 v[40:43], v[228:231], v[208:211], v[40:43]
	v_mfma_f32_16x16x32_bf16 v[44:47], v[232:235], v[208:211], v[44:47]
	v_mfma_f32_16x16x32_bf16 v[48:51], v[216:219], v[212:215], v[48:51]
	v_mfma_f32_16x16x32_bf16 v[52:55], v[220:223], v[212:215], v[52:55]
	v_mfma_f32_16x16x32_bf16 v[56:59], v[228:231], v[212:215], v[56:59]
	v_mfma_f32_16x16x32_bf16 v[60:63], v[232:235], v[212:215], v[60:63]
	s_waitcnt lgkmcnt(0)
	s_add_u32 m0, s56, 0xc000
	s_nop 0
	global_load_lds_dwordx4 v236, s[24:25]
	s_add_u32 m0, s56, 0xc400
	s_nop 0
	global_load_lds_dwordx4 v237, s[24:25]
	s_add_u32 m0, s56, 0xc800
	s_nop 0
	global_load_lds_dwordx4 v238, s[24:25]
	s_add_u32 m0, s56, 0xcc00
	s_nop 0
	global_load_lds_dwordx4 v239, s[24:25]
	s_add_u32 s24, s24, 128
	s_addc_u32 s25, s25, 0
	v_mfma_f32_16x16x32_bf16 v[0:3], v[184:187], v[168:171], v[0:3]
	ds_read_b128 v[200:203], v167 offset:49152
	v_mfma_f32_16x16x32_bf16 v[4:7], v[188:191], v[168:171], v[4:7]
	ds_read_b128 v[216:219], v251 offset:0
	v_mfma_f32_16x16x32_bf16 v[8:11], v[192:195], v[168:171], v[8:11]
	ds_read_b128 v[204:207], v167 offset:51200
	v_mfma_f32_16x16x32_bf16 v[12:15], v[196:199], v[168:171], v[12:15]
	ds_read_b128 v[220:223], v251 offset:512
	v_mfma_f32_16x16x32_bf16 v[16:19], v[184:187], v[172:175], v[16:19]
	ds_read_b128 v[208:211], v167 offset:53248
	v_mfma_f32_16x16x32_bf16 v[20:23], v[188:191], v[172:175], v[20:23]
	ds_read_b128 v[228:231], v251 offset:1024
	v_mfma_f32_16x16x32_bf16 v[24:27], v[192:195], v[172:175], v[24:27]
	ds_read_b128 v[212:215], v167 offset:55296
	v_mfma_f32_16x16x32_bf16 v[28:31], v[196:199], v[172:175], v[28:31]
	ds_read_b128 v[232:235], v251 offset:1536
	v_mfma_f32_16x16x32_bf16 v[32:35], v[184:187], v[176:179], v[32:35]
	v_mfma_f32_16x16x32_bf16 v[36:39], v[188:191], v[176:179], v[36:39]
	v_mfma_f32_16x16x32_bf16 v[40:43], v[192:195], v[176:179], v[40:43]
	v_mfma_f32_16x16x32_bf16 v[44:47], v[196:199], v[176:179], v[44:47]
	v_mfma_f32_16x16x32_bf16 v[48:51], v[184:187], v[180:183], v[48:51]
	v_mfma_f32_16x16x32_bf16 v[52:55], v[188:191], v[180:183], v[52:55]
	v_mfma_f32_16x16x32_bf16 v[56:59], v[192:195], v[180:183], v[56:59]
	v_mfma_f32_16x16x32_bf16 v[60:63], v[196:199], v[180:183], v[60:63]
	s_waitcnt vmcnt(4) lgkmcnt(0)
	s_barrier
; template <int NI> ...
;     ...
;   for (int kt = 0; kt < nk; kt += 2) {
;     G_LOAD(a0, b0, min((kt + 2) * 32, klast));
;     G_COMPUTE(0);
;     G_WRITE(a1, b1, 1);
;     __syncthreads();
;     G_LOAD(a1, b1, min((kt + 3) * 32, klast));
;     G_COMPUTE(1);
;     G_WRITE(a0, b0, 0);
;     __syncthreads();
;   }
	s_add_u32 m0, s56, 0x10000
	s_nop 0
	global_load_lds_dwordx4 v244, s[26:27]
	s_add_u32 m0, s56, 0x10400
	s_nop 0
	global_load_lds_dwordx4 v245, s[26:27]
	s_add_u32 m0, s56, 0x10800
	s_nop 0
	global_load_lds_dwordx4 v246, s[26:27]
	s_add_u32 m0, s56, 0x10c00
	s_nop 0
	global_load_lds_dwordx4 v247, s[26:27]
	s_add_u32 s26, s26, 128
	s_addc_u32 s27, s27, 0
	v_mfma_f32_16x16x32_bf16 v[0:3], v[216:219], v[200:203], v[0:3]
	ds_read_b128 v[168:171], v248 offset:16384
	v_mfma_f32_16x16x32_bf16 v[4:7], v[220:223], v[200:203], v[4:7]
	ds_read_b128 v[184:187], v250 offset:32768
	v_mfma_f32_16x16x32_bf16 v[8:11], v[228:231], v[200:203], v[8:11]
	ds_read_b128 v[172:175], v248 offset:18432
	v_mfma_f32_16x16x32_bf16 v[12:15], v[232:235], v[200:203], v[12:15]
	ds_read_b128 v[188:191], v250 offset:33280
	v_mfma_f32_16x16x32_bf16 v[16:19], v[216:219], v[204:207], v[16:19]
	ds_read_b128 v[176:179], v248 offset:20480
	v_mfma_f32_16x16x32_bf16 v[20:23], v[220:223], v[204:207], v[20:23]
	ds_read_b128 v[192:195], v250 offset:33792
	v_mfma_f32_16x16x32_bf16 v[24:27], v[228:231], v[204:207], v[24:27]
	ds_read_b128 v[180:183], v248 offset:22528
	v_mfma_f32_16x16x32_bf16 v[28:31], v[232:235], v[204:207], v[28:31]
	ds_read_b128 v[196:199], v250 offset:34304
	v_mfma_f32_16x16x32_bf16 v[32:35], v[216:219], v[208:211], v[32:35]
	v_mfma_f32_16x16x32_bf16 v[36:39], v[220:223], v[208:211], v[36:39]
	v_mfma_f32_16x16x32_bf16 v[40:43], v[228:231], v[208:211], v[40:43]
	v_mfma_f32_16x16x32_bf16 v[44:47], v[232:235], v[208:211], v[44:47]
	v_mfma_f32_16x16x32_bf16 v[48:51], v[216:219], v[212:215], v[48:51]
	v_mfma_f32_16x16x32_bf16 v[52:55], v[220:223], v[212:215], v[52:55]
	v_mfma_f32_16x16x32_bf16 v[56:59], v[228:231], v[212:215], v[56:59]
	v_mfma_f32_16x16x32_bf16 v[60:63], v[232:235], v[212:215], v[60:63]
	s_waitcnt lgkmcnt(0)
	s_add_u32 m0, s56, 0x0
	s_nop 0
	global_load_lds_dwordx4 v236, s[24:25]
	s_add_u32 m0, s56, 0x400
	s_nop 0
	global_load_lds_dwordx4 v237, s[24:25]
	s_add_u32 m0, s56, 0x800
	s_nop 0
	global_load_lds_dwordx4 v238, s[24:25]
	s_add_u32 m0, s56, 0xc00
	s_nop 0
	global_load_lds_dwordx4 v239, s[24:25]
	s_add_u32 s24, s24, 128
	s_addc_u32 s25, s25, 0
	v_mfma_f32_16x16x32_bf16 v[0:3], v[184:187], v[168:171], v[0:3]
	ds_read_b128 v[200:203], v249 offset:16384
	v_mfma_f32_16x16x32_bf16 v[4:7], v[188:191], v[168:171], v[4:7]
	ds_read_b128 v[216:219], v251 offset:32768
	v_mfma_f32_16x16x32_bf16 v[8:11], v[192:195], v[168:171], v[8:11]
	ds_read_b128 v[204:207], v249 offset:18432
	v_mfma_f32_16x16x32_bf16 v[12:15], v[196:199], v[168:171], v[12:15]
	ds_read_b128 v[220:223], v251 offset:33280
	v_mfma_f32_16x16x32_bf16 v[16:19], v[184:187], v[172:175], v[16:19]
	ds_read_b128 v[208:211], v249 offset:20480
	v_mfma_f32_16x16x32_bf16 v[20:23], v[188:191], v[172:175], v[20:23]
	ds_read_b128 v[228:231], v251 offset:33792
	v_mfma_f32_16x16x32_bf16 v[24:27], v[192:195], v[172:175], v[24:27]
	ds_read_b128 v[212:215], v249 offset:22528
	v_mfma_f32_16x16x32_bf16 v[28:31], v[196:199], v[172:175], v[28:31]
	ds_read_b128 v[232:235], v251 offset:34304
	v_mfma_f32_16x16x32_bf16 v[32:35], v[184:187], v[176:179], v[32:35]
	v_mfma_f32_16x16x32_bf16 v[36:39], v[188:191], v[176:179], v[36:39]
	v_mfma_f32_16x16x32_bf16 v[40:43], v[192:195], v[176:179], v[40:43]
	v_mfma_f32_16x16x32_bf16 v[44:47], v[196:199], v[176:179], v[44:47]
	v_mfma_f32_16x16x32_bf16 v[48:51], v[184:187], v[180:183], v[48:51]
	v_mfma_f32_16x16x32_bf16 v[52:55], v[188:191], v[180:183], v[52:55]
	v_mfma_f32_16x16x32_bf16 v[56:59], v[192:195], v[180:183], v[56:59]
	v_mfma_f32_16x16x32_bf16 v[60:63], v[196:199], v[180:183], v[60:63]
	s_waitcnt vmcnt(4) lgkmcnt(0)
	s_barrier
	s_add_u32 m0, s56, 0x4000
	s_nop 0
	global_load_lds_dwordx4 v244, s[26:27]
	s_add_u32 m0, s56, 0x4400
	s_nop 0
	global_load_lds_dwordx4 v245, s[26:27]
	s_add_u32 m0, s56, 0x4800
	s_nop 0
	global_load_lds_dwordx4 v246, s[26:27]
	s_add_u32 m0, s56, 0x4c00
	s_nop 0
	global_load_lds_dwordx4 v247, s[26:27]
	s_add_u32 s26, s26, 128
	s_addc_u32 s27, s27, 0
	v_mfma_f32_16x16x32_bf16 v[0:3], v[216:219], v[200:203], v[0:3]
	ds_read_b128 v[168:171], v248 offset:49152
	v_mfma_f32_16x16x32_bf16 v[4:7], v[220:223], v[200:203], v[4:7]
	ds_read_b128 v[184:187], v226 offset:49152
	v_mfma_f32_16x16x32_bf16 v[8:11], v[228:231], v[200:203], v[8:11]
	ds_read_b128 v[172:175], v248 offset:51200
	v_mfma_f32_16x16x32_bf16 v[12:15], v[232:235], v[200:203], v[12:15]
	ds_read_b128 v[188:191], v226 offset:49664
	v_mfma_f32_16x16x32_bf16 v[16:19], v[216:219], v[204:207], v[16:19]
	ds_read_b128 v[176:179], v248 offset:53248
	v_mfma_f32_16x16x32_bf16 v[20:23], v[220:223], v[204:207], v[20:23]
	ds_read_b128 v[192:195], v226 offset:50176
	v_mfma_f32_16x16x32_bf16 v[24:27], v[228:231], v[204:207], v[24:27]
	ds_read_b128 v[180:183], v248 offset:55296
	v_mfma_f32_16x16x32_bf16 v[28:31], v[232:235], v[204:207], v[28:31]
	ds_read_b128 v[196:199], v226 offset:50688
	v_mfma_f32_16x16x32_bf16 v[32:35], v[216:219], v[208:211], v[32:35]
	v_mfma_f32_16x16x32_bf16 v[36:39], v[220:223], v[208:211], v[36:39]
	v_mfma_f32_16x16x32_bf16 v[40:43], v[228:231], v[208:211], v[40:43]
	v_mfma_f32_16x16x32_bf16 v[44:47], v[232:235], v[208:211], v[44:47]
	v_mfma_f32_16x16x32_bf16 v[48:51], v[216:219], v[212:215], v[48:51]
	v_mfma_f32_16x16x32_bf16 v[52:55], v[220:223], v[212:215], v[52:55]
	v_mfma_f32_16x16x32_bf16 v[56:59], v[228:231], v[212:215], v[56:59]
	v_mfma_f32_16x16x32_bf16 v[60:63], v[232:235], v[212:215], v[60:63]
	s_waitcnt lgkmcnt(0)
; template <int NI> ...
;     ...
;   for (int kt = 0; kt < nk; kt += 2) {
;     G_LOAD(a0, b0, min((kt + 2) * 32, klast));
;     G_COMPUTE(0);
;     G_WRITE(a1, b1, 1);
;     __syncthreads();
;     G_LOAD(a1, b1, min((kt + 3) * 32, klast));
;     G_COMPUTE(1);
;     G_WRITE(a0, b0, 0);
;     __syncthreads();
;   }
	s_add_u32 m0, s56, 0x8000
	s_nop 0
	global_load_lds_dwordx4 v236, s[24:25]
	s_add_u32 m0, s56, 0x8400
	s_nop 0
	global_load_lds_dwordx4 v237, s[24:25]
	s_add_u32 m0, s56, 0x8800
	s_nop 0
	global_load_lds_dwordx4 v238, s[24:25]
	s_add_u32 m0, s56, 0x8c00
	s_nop 0
	global_load_lds_dwordx4 v239, s[24:25]
	s_add_u32 s24, s24, 128
	s_addc_u32 s25, s25, 0
	v_mfma_f32_16x16x32_bf16 v[0:3], v[184:187], v[168:171], v[0:3]
	ds_read_b128 v[200:203], v249 offset:49152
	v_mfma_f32_16x16x32_bf16 v[4:7], v[188:191], v[168:171], v[4:7]
	ds_read_b128 v[216:219], v227 offset:49152
	v_mfma_f32_16x16x32_bf16 v[8:11], v[192:195], v[168:171], v[8:11]
	ds_read_b128 v[204:207], v249 offset:51200
	v_mfma_f32_16x16x32_bf16 v[12:15], v[196:199], v[168:171], v[12:15]
	ds_read_b128 v[220:223], v227 offset:49664
	v_mfma_f32_16x16x32_bf16 v[16:19], v[184:187], v[172:175], v[16:19]
	ds_read_b128 v[208:211], v249 offset:53248
	v_mfma_f32_16x16x32_bf16 v[20:23], v[188:191], v[172:175], v[20:23]
	ds_read_b128 v[228:231], v227 offset:50176
	v_mfma_f32_16x16x32_bf16 v[24:27], v[192:195], v[172:175], v[24:27]
	ds_read_b128 v[212:215], v249 offset:55296
	v_mfma_f32_16x16x32_bf16 v[28:31], v[196:199], v[172:175], v[28:31]
	ds_read_b128 v[232:235], v227 offset:50688
	v_mfma_f32_16x16x32_bf16 v[32:35], v[184:187], v[176:179], v[32:35]
	v_mfma_f32_16x16x32_bf16 v[36:39], v[188:191], v[176:179], v[36:39]
	v_mfma_f32_16x16x32_bf16 v[40:43], v[192:195], v[176:179], v[40:43]
	v_mfma_f32_16x16x32_bf16 v[44:47], v[196:199], v[176:179], v[44:47]
	v_mfma_f32_16x16x32_bf16 v[48:51], v[184:187], v[180:183], v[48:51]
	v_mfma_f32_16x16x32_bf16 v[52:55], v[188:191], v[180:183], v[52:55]
	v_mfma_f32_16x16x32_bf16 v[56:59], v[192:195], v[180:183], v[56:59]
	v_mfma_f32_16x16x32_bf16 v[60:63], v[196:199], v[180:183], v[60:63]
	s_waitcnt vmcnt(4) lgkmcnt(0)
	s_barrier
	s_add_u32 m0, s56, 0xc000
	s_nop 0
	global_load_lds_dwordx4 v244, s[26:27]
	s_add_u32 m0, s56, 0xc400
	s_nop 0
	global_load_lds_dwordx4 v245, s[26:27]
	s_add_u32 m0, s56, 0xc800
	s_nop 0
	global_load_lds_dwordx4 v246, s[26:27]
	s_add_u32 m0, s56, 0xcc00
	s_nop 0
	global_load_lds_dwordx4 v247, s[26:27]
	s_add_u32 s26, s26, 128
	s_addc_u32 s27, s27, 0
	v_mfma_f32_16x16x32_bf16 v[0:3], v[216:219], v[200:203], v[0:3]
	ds_read_b128 v[168:171], v248 offset:0
	v_mfma_f32_16x16x32_bf16 v[4:7], v[220:223], v[200:203], v[4:7]
	ds_read_b128 v[184:187], v250 offset:16384
	v_mfma_f32_16x16x32_bf16 v[8:11], v[228:231], v[200:203], v[8:11]
	ds_read_b128 v[172:175], v248 offset:2048
	v_mfma_f32_16x16x32_bf16 v[12:15], v[232:235], v[200:203], v[12:15]
	ds_read_b128 v[188:191], v250 offset:16896
	v_mfma_f32_16x16x32_bf16 v[16:19], v[216:219], v[204:207], v[16:19]
	ds_read_b128 v[176:179], v248 offset:4096
	v_mfma_f32_16x16x32_bf16 v[20:23], v[220:223], v[204:207], v[20:23]
	ds_read_b128 v[192:195], v250 offset:17408
	v_mfma_f32_16x16x32_bf16 v[24:27], v[228:231], v[204:207], v[24:27]
	ds_read_b128 v[180:183], v248 offset:6144
	v_mfma_f32_16x16x32_bf16 v[28:31], v[232:235], v[204:207], v[28:31]
	ds_read_b128 v[196:199], v250 offset:17920
	v_mfma_f32_16x16x32_bf16 v[32:35], v[216:219], v[208:211], v[32:35]
	v_mfma_f32_16x16x32_bf16 v[36:39], v[220:223], v[208:211], v[36:39]
	v_mfma_f32_16x16x32_bf16 v[40:43], v[228:231], v[208:211], v[40:43]
	v_mfma_f32_16x16x32_bf16 v[44:47], v[232:235], v[208:211], v[44:47]
	v_mfma_f32_16x16x32_bf16 v[48:51], v[216:219], v[212:215], v[48:51]
	v_mfma_f32_16x16x32_bf16 v[52:55], v[220:223], v[212:215], v[52:55]
	v_mfma_f32_16x16x32_bf16 v[56:59], v[228:231], v[212:215], v[56:59]
	v_mfma_f32_16x16x32_bf16 v[60:63], v[232:235], v[212:215], v[60:63]
	s_waitcnt lgkmcnt(0)
	s_add_u32 m0, s56, 0x10000
	s_nop 0
	global_load_lds_dwordx4 v236, s[24:25]
	s_add_u32 m0, s56, 0x10400
	s_nop 0
	global_load_lds_dwordx4 v237, s[24:25]
	s_add_u32 m0, s56, 0x10800
	s_nop 0
	global_load_lds_dwordx4 v238, s[24:25]
	s_add_u32 m0, s56, 0x10c00
	s_nop 0
	global_load_lds_dwordx4 v239, s[24:25]
	s_add_u32 s24, s24, 128
	s_addc_u32 s25, s25, 0
	v_mfma_f32_16x16x32_bf16 v[0:3], v[184:187], v[168:171], v[0:3]
	ds_read_b128 v[200:203], v249 offset:0
	v_mfma_f32_16x16x32_bf16 v[4:7], v[188:191], v[168:171], v[4:7]
	ds_read_b128 v[216:219], v251 offset:16384
	v_mfma_f32_16x16x32_bf16 v[8:11], v[192:195], v[168:171], v[8:11]
	ds_read_b128 v[204:207], v249 offset:2048
	v_mfma_f32_16x16x32_bf16 v[12:15], v[196:199], v[168:171], v[12:15]
	ds_read_b128 v[220:223], v251 offset:16896
	v_mfma_f32_16x16x32_bf16 v[16:19], v[184:187], v[172:175], v[16:19]
	ds_read_b128 v[208:211], v249 offset:4096
	v_mfma_f32_16x16x32_bf16 v[20:23], v[188:191], v[172:175], v[20:23]
	ds_read_b128 v[228:231], v251 offset:17408
	v_mfma_f32_16x16x32_bf16 v[24:27], v[192:195], v[172:175], v[24:27]
	ds_read_b128 v[212:215], v249 offset:6144
	v_mfma_f32_16x16x32_bf16 v[28:31], v[196:199], v[172:175], v[28:31]
	ds_read_b128 v[232:235], v251 offset:17920
	v_mfma_f32_16x16x32_bf16 v[32:35], v[184:187], v[176:179], v[32:35]
	v_mfma_f32_16x16x32_bf16 v[36:39], v[188:191], v[176:179], v[36:39]
	v_mfma_f32_16x16x32_bf16 v[40:43], v[192:195], v[176:179], v[40:43]
	v_mfma_f32_16x16x32_bf16 v[44:47], v[196:199], v[176:179], v[44:47]
	v_mfma_f32_16x16x32_bf16 v[48:51], v[184:187], v[180:183], v[48:51]
	v_mfma_f32_16x16x32_bf16 v[52:55], v[188:191], v[180:183], v[52:55]
	v_mfma_f32_16x16x32_bf16 v[56:59], v[192:195], v[180:183], v[56:59]
	v_mfma_f32_16x16x32_bf16 v[60:63], v[196:199], v[180:183], v[60:63]
	s_waitcnt vmcnt(4) lgkmcnt(0)
	s_barrier
; template <int NI> ...
;     ...
;   for (int kt = 0; kt < nk; kt += 2) {
;     G_LOAD(a0, b0, min((kt + 2) * 32, klast));
;     G_COMPUTE(0);
;     G_WRITE(a1, b1, 1);
;     __syncthreads();
;     G_LOAD(a1, b1, min((kt + 3) * 32, klast));
;     G_COMPUTE(1);
;     G_WRITE(a0, b0, 0);
;     __syncthreads();
;   }
	s_add_u32 m0, s56, 0x0
	s_nop 0
	global_load_lds_dwordx4 v244, s[26:27]
	s_add_u32 m0, s56, 0x400
	s_nop 0
	global_load_lds_dwordx4 v245, s[26:27]
	s_add_u32 m0, s56, 0x800
	s_nop 0
	global_load_lds_dwordx4 v246, s[26:27]
	s_add_u32 m0, s56, 0xc00
	s_nop 0
	global_load_lds_dwordx4 v247, s[26:27]
	s_add_u32 s26, s26, 128
	s_addc_u32 s27, s27, 0
	v_mfma_f32_16x16x32_bf16 v[0:3], v[216:219], v[200:203], v[0:3]
	ds_read_b128 v[168:171], v248 offset:32768
	v_mfma_f32_16x16x32_bf16 v[4:7], v[220:223], v[200:203], v[4:7]
	ds_read_b128 v[184:187], v250 offset:49152
	v_mfma_f32_16x16x32_bf16 v[8:11], v[228:231], v[200:203], v[8:11]
	ds_read_b128 v[172:175], v248 offset:34816
	v_mfma_f32_16x16x32_bf16 v[12:15], v[232:235], v[200:203], v[12:15]
	ds_read_b128 v[188:191], v250 offset:49664
	v_mfma_f32_16x16x32_bf16 v[16:19], v[216:219], v[204:207], v[16:19]
	ds_read_b128 v[176:179], v248 offset:36864
	v_mfma_f32_16x16x32_bf16 v[20:23], v[220:223], v[204:207], v[20:23]
	ds_read_b128 v[192:195], v250 offset:50176
	v_mfma_f32_16x16x32_bf16 v[24:27], v[228:231], v[204:207], v[24:27]
	ds_read_b128 v[180:183], v248 offset:38912
	v_mfma_f32_16x16x32_bf16 v[28:31], v[232:235], v[204:207], v[28:31]
	ds_read_b128 v[196:199], v250 offset:50688
	v_mfma_f32_16x16x32_bf16 v[32:35], v[216:219], v[208:211], v[32:35]
	v_mfma_f32_16x16x32_bf16 v[36:39], v[220:223], v[208:211], v[36:39]
	v_mfma_f32_16x16x32_bf16 v[40:43], v[228:231], v[208:211], v[40:43]
	v_mfma_f32_16x16x32_bf16 v[44:47], v[232:235], v[208:211], v[44:47]
	v_mfma_f32_16x16x32_bf16 v[48:51], v[216:219], v[212:215], v[48:51]
	v_mfma_f32_16x16x32_bf16 v[52:55], v[220:223], v[212:215], v[52:55]
	v_mfma_f32_16x16x32_bf16 v[56:59], v[228:231], v[212:215], v[56:59]
	v_mfma_f32_16x16x32_bf16 v[60:63], v[232:235], v[212:215], v[60:63]
	s_waitcnt lgkmcnt(0)
	s_add_u32 m0, s56, 0x4000
	s_nop 0
	global_load_lds_dwordx4 v236, s[24:25]
	s_add_u32 m0, s56, 0x4400
	s_nop 0
	global_load_lds_dwordx4 v237, s[24:25]
	s_add_u32 m0, s56, 0x4800
	s_nop 0
	global_load_lds_dwordx4 v238, s[24:25]
	s_add_u32 m0, s56, 0x4c00
	s_nop 0
	global_load_lds_dwordx4 v239, s[24:25]
	s_add_u32 s24, s24, 128
	s_addc_u32 s25, s25, 0
	v_mfma_f32_16x16x32_bf16 v[0:3], v[184:187], v[168:171], v[0:3]
	ds_read_b128 v[200:203], v249 offset:32768
	v_mfma_f32_16x16x32_bf16 v[4:7], v[188:191], v[168:171], v[4:7]
	ds_read_b128 v[216:219], v251 offset:49152
	v_mfma_f32_16x16x32_bf16 v[8:11], v[192:195], v[168:171], v[8:11]
	ds_read_b128 v[204:207], v249 offset:34816
	v_mfma_f32_16x16x32_bf16 v[12:15], v[196:199], v[168:171], v[12:15]
	ds_read_b128 v[220:223], v251 offset:49664
	v_mfma_f32_16x16x32_bf16 v[16:19], v[184:187], v[172:175], v[16:19]
	ds_read_b128 v[208:211], v249 offset:36864
	v_mfma_f32_16x16x32_bf16 v[20:23], v[188:191], v[172:175], v[20:23]
	ds_read_b128 v[228:231], v251 offset:50176
	v_mfma_f32_16x16x32_bf16 v[24:27], v[192:195], v[172:175], v[24:27]
	ds_read_b128 v[212:215], v249 offset:38912
	v_mfma_f32_16x16x32_bf16 v[28:31], v[196:199], v[172:175], v[28:31]
	ds_read_b128 v[232:235], v251 offset:50688
	v_mfma_f32_16x16x32_bf16 v[32:35], v[184:187], v[176:179], v[32:35]
	v_mfma_f32_16x16x32_bf16 v[36:39], v[188:191], v[176:179], v[36:39]
	v_mfma_f32_16x16x32_bf16 v[40:43], v[192:195], v[176:179], v[40:43]
	v_mfma_f32_16x16x32_bf16 v[44:47], v[196:199], v[176:179], v[44:47]
	v_mfma_f32_16x16x32_bf16 v[48:51], v[184:187], v[180:183], v[48:51]
	v_mfma_f32_16x16x32_bf16 v[52:55], v[188:191], v[180:183], v[52:55]
	v_mfma_f32_16x16x32_bf16 v[56:59], v[192:195], v[180:183], v[56:59]
	v_mfma_f32_16x16x32_bf16 v[60:63], v[196:199], v[180:183], v[60:63]
	s_waitcnt vmcnt(4) lgkmcnt(0)
	s_barrier
	s_add_u32 m0, s56, 0x8000
	s_nop 0
	global_load_lds_dwordx4 v244, s[26:27]
	s_add_u32 m0, s56, 0x8400
	s_nop 0
	global_load_lds_dwordx4 v245, s[26:27]
	s_add_u32 m0, s56, 0x8800
	s_nop 0
	global_load_lds_dwordx4 v246, s[26:27]
	s_add_u32 m0, s56, 0x8c00
	s_nop 0
	global_load_lds_dwordx4 v247, s[26:27]
	s_add_u32 s26, s26, 128
	s_addc_u32 s27, s27, 0
	v_mfma_f32_16x16x32_bf16 v[0:3], v[216:219], v[200:203], v[0:3]
	ds_read_b128 v[168:171], v166 offset:49152
	v_mfma_f32_16x16x32_bf16 v[4:7], v[220:223], v[200:203], v[4:7]
	ds_read_b128 v[184:187], v250 offset:0
	v_mfma_f32_16x16x32_bf16 v[8:11], v[228:231], v[200:203], v[8:11]
	ds_read_b128 v[172:175], v166 offset:51200
	v_mfma_f32_16x16x32_bf16 v[12:15], v[232:235], v[200:203], v[12:15]
	ds_read_b128 v[188:191], v250 offset:512
	v_mfma_f32_16x16x32_bf16 v[16:19], v[216:219], v[204:207], v[16:19]
	ds_read_b128 v[176:179], v166 offset:53248
	v_mfma_f32_16x16x32_bf16 v[20:23], v[220:223], v[204:207], v[20:23]
	ds_read_b128 v[192:195], v250 offset:1024
	v_mfma_f32_16x16x32_bf16 v[24:27], v[228:231], v[204:207], v[24:27]
	ds_read_b128 v[180:183], v166 offset:55296
	v_mfma_f32_16x16x32_bf16 v[28:31], v[232:235], v[204:207], v[28:31]
	ds_read_b128 v[196:199], v250 offset:1536
	v_mfma_f32_16x16x32_bf16 v[32:35], v[216:219], v[208:211], v[32:35]
	v_mfma_f32_16x16x32_bf16 v[36:39], v[220:223], v[208:211], v[36:39]
	v_mfma_f32_16x16x32_bf16 v[40:43], v[228:231], v[208:211], v[40:43]
	v_mfma_f32_16x16x32_bf16 v[44:47], v[232:235], v[208:211], v[44:47]
	v_mfma_f32_16x16x32_bf16 v[48:51], v[216:219], v[212:215], v[48:51]
	v_mfma_f32_16x16x32_bf16 v[52:55], v[220:223], v[212:215], v[52:55]
	v_mfma_f32_16x16x32_bf16 v[56:59], v[228:231], v[212:215], v[56:59]
	v_mfma_f32_16x16x32_bf16 v[60:63], v[232:235], v[212:215], v[60:63]
	s_waitcnt lgkmcnt(0)
; template <int NI> ...
;     ...
;   for (int kt = 0; kt < nk; kt += 2) {
;     G_LOAD(a0, b0, min((kt + 2) * 32, klast));
;     G_COMPUTE(0);
;     G_WRITE(a1, b1, 1);
;     __syncthreads();
;     G_LOAD(a1, b1, min((kt + 3) * 32, klast));
;     G_COMPUTE(1);
;     G_WRITE(a0, b0, 0);
;     __syncthreads();
;   }
	s_add_u32 m0, s56, 0xc000
	s_nop 0
	global_load_lds_dwordx4 v236, s[24:25]
	s_add_u32 m0, s56, 0xc400
	s_nop 0
	global_load_lds_dwordx4 v237, s[24:25]
	s_add_u32 m0, s56, 0xc800
	s_nop 0
	global_load_lds_dwordx4 v238, s[24:25]
	s_add_u32 m0, s56, 0xcc00
	s_nop 0
	global_load_lds_dwordx4 v239, s[24:25]
	s_add_u32 s24, s24, 128
	s_addc_u32 s25, s25, 0
	v_mfma_f32_16x16x32_bf16 v[0:3], v[184:187], v[168:171], v[0:3]
	ds_read_b128 v[200:203], v167 offset:49152
	v_mfma_f32_16x16x32_bf16 v[4:7], v[188:191], v[168:171], v[4:7]
	ds_read_b128 v[216:219], v251 offset:0
	v_mfma_f32_16x16x32_bf16 v[8:11], v[192:195], v[168:171], v[8:11]
	ds_read_b128 v[204:207], v167 offset:51200
	v_mfma_f32_16x16x32_bf16 v[12:15], v[196:199], v[168:171], v[12:15]
	ds_read_b128 v[220:223], v251 offset:512
	v_mfma_f32_16x16x32_bf16 v[16:19], v[184:187], v[172:175], v[16:19]
	ds_read_b128 v[208:211], v167 offset:53248
	v_mfma_f32_16x16x32_bf16 v[20:23], v[188:191], v[172:175], v[20:23]
	ds_read_b128 v[228:231], v251 offset:1024
	v_mfma_f32_16x16x32_bf16 v[24:27], v[192:195], v[172:175], v[24:27]
	ds_read_b128 v[212:215], v167 offset:55296
	v_mfma_f32_16x16x32_bf16 v[28:31], v[196:199], v[172:175], v[28:31]
	ds_read_b128 v[232:235], v251 offset:1536
	v_mfma_f32_16x16x32_bf16 v[32:35], v[184:187], v[176:179], v[32:35]
	v_mfma_f32_16x16x32_bf16 v[36:39], v[188:191], v[176:179], v[36:39]
	v_mfma_f32_16x16x32_bf16 v[40:43], v[192:195], v[176:179], v[40:43]
	v_mfma_f32_16x16x32_bf16 v[44:47], v[196:199], v[176:179], v[44:47]
	v_mfma_f32_16x16x32_bf16 v[48:51], v[184:187], v[180:183], v[48:51]
	v_mfma_f32_16x16x32_bf16 v[52:55], v[188:191], v[180:183], v[52:55]
	v_mfma_f32_16x16x32_bf16 v[56:59], v[192:195], v[180:183], v[56:59]
	v_mfma_f32_16x16x32_bf16 v[60:63], v[196:199], v[180:183], v[60:63]
	s_waitcnt vmcnt(4) lgkmcnt(0)
	s_barrier
	s_add_u32 m0, s56, 0x10000
	s_nop 0
	global_load_lds_dwordx4 v244, s[26:27]
	s_add_u32 m0, s56, 0x10400
	s_nop 0
	global_load_lds_dwordx4 v245, s[26:27]
	s_add_u32 m0, s56, 0x10800
	s_nop 0
	global_load_lds_dwordx4 v246, s[26:27]
	s_add_u32 m0, s56, 0x10c00
	s_nop 0
	global_load_lds_dwordx4 v247, s[26:27]
	s_add_u32 s26, s26, 128
	s_addc_u32 s27, s27, 0
	v_mfma_f32_16x16x32_bf16 v[0:3], v[216:219], v[200:203], v[0:3]
	ds_read_b128 v[168:171], v248 offset:16384
	v_mfma_f32_16x16x32_bf16 v[4:7], v[220:223], v[200:203], v[4:7]
	ds_read_b128 v[184:187], v250 offset:32768
	v_mfma_f32_16x16x32_bf16 v[8:11], v[228:231], v[200:203], v[8:11]
	ds_read_b128 v[172:175], v248 offset:18432
	v_mfma_f32_16x16x32_bf16 v[12:15], v[232:235], v[200:203], v[12:15]
	ds_read_b128 v[188:191], v250 offset:33280
	v_mfma_f32_16x16x32_bf16 v[16:19], v[216:219], v[204:207], v[16:19]
	ds_read_b128 v[176:179], v248 offset:20480
	v_mfma_f32_16x16x32_bf16 v[20:23], v[220:223], v[204:207], v[20:23]
	ds_read_b128 v[192:195], v250 offset:33792
	v_mfma_f32_16x16x32_bf16 v[24:27], v[228:231], v[204:207], v[24:27]
	ds_read_b128 v[180:183], v248 offset:22528
	v_mfma_f32_16x16x32_bf16 v[28:31], v[232:235], v[204:207], v[28:31]
	ds_read_b128 v[196:199], v250 offset:34304
	v_mfma_f32_16x16x32_bf16 v[32:35], v[216:219], v[208:211], v[32:35]
	v_mfma_f32_16x16x32_bf16 v[36:39], v[220:223], v[208:211], v[36:39]
	v_mfma_f32_16x16x32_bf16 v[40:43], v[228:231], v[208:211], v[40:43]
	v_mfma_f32_16x16x32_bf16 v[44:47], v[232:235], v[208:211], v[44:47]
	v_mfma_f32_16x16x32_bf16 v[48:51], v[216:219], v[212:215], v[48:51]
	v_mfma_f32_16x16x32_bf16 v[52:55], v[220:223], v[212:215], v[52:55]
	v_mfma_f32_16x16x32_bf16 v[56:59], v[228:231], v[212:215], v[56:59]
	v_mfma_f32_16x16x32_bf16 v[60:63], v[232:235], v[212:215], v[60:63]
	s_waitcnt lgkmcnt(0)
	s_add_u32 m0, s56, 0x0
	s_nop 0
	global_load_lds_dwordx4 v236, s[24:25]
	s_add_u32 m0, s56, 0x400
	s_nop 0
	global_load_lds_dwordx4 v237, s[24:25]
	s_add_u32 m0, s56, 0x800
	s_nop 0
	global_load_lds_dwordx4 v238, s[24:25]
	s_add_u32 m0, s56, 0xc00
	s_nop 0
	global_load_lds_dwordx4 v239, s[24:25]
	s_add_u32 s24, s24, 128
	s_addc_u32 s25, s25, 0
	v_mfma_f32_16x16x32_bf16 v[0:3], v[184:187], v[168:171], v[0:3]
	ds_read_b128 v[200:203], v249 offset:16384
	v_mfma_f32_16x16x32_bf16 v[4:7], v[188:191], v[168:171], v[4:7]
	ds_read_b128 v[216:219], v251 offset:32768
	v_mfma_f32_16x16x32_bf16 v[8:11], v[192:195], v[168:171], v[8:11]
	ds_read_b128 v[204:207], v249 offset:18432
	v_mfma_f32_16x16x32_bf16 v[12:15], v[196:199], v[168:171], v[12:15]
	ds_read_b128 v[220:223], v251 offset:33280
	v_mfma_f32_16x16x32_bf16 v[16:19], v[184:187], v[172:175], v[16:19]
	ds_read_b128 v[208:211], v249 offset:20480
	v_mfma_f32_16x16x32_bf16 v[20:23], v[188:191], v[172:175], v[20:23]
	ds_read_b128 v[228:231], v251 offset:33792
	v_mfma_f32_16x16x32_bf16 v[24:27], v[192:195], v[172:175], v[24:27]
	ds_read_b128 v[212:215], v249 offset:22528
	v_mfma_f32_16x16x32_bf16 v[28:31], v[196:199], v[172:175], v[28:31]
	ds_read_b128 v[232:235], v251 offset:34304
	v_mfma_f32_16x16x32_bf16 v[32:35], v[184:187], v[176:179], v[32:35]
	v_mfma_f32_16x16x32_bf16 v[36:39], v[188:191], v[176:179], v[36:39]
	v_mfma_f32_16x16x32_bf16 v[40:43], v[192:195], v[176:179], v[40:43]
	v_mfma_f32_16x16x32_bf16 v[44:47], v[196:199], v[176:179], v[44:47]
	v_mfma_f32_16x16x32_bf16 v[48:51], v[184:187], v[180:183], v[48:51]
	v_mfma_f32_16x16x32_bf16 v[52:55], v[188:191], v[180:183], v[52:55]
	v_mfma_f32_16x16x32_bf16 v[56:59], v[192:195], v[180:183], v[56:59]
	v_mfma_f32_16x16x32_bf16 v[60:63], v[196:199], v[180:183], v[60:63]
	s_waitcnt vmcnt(4) lgkmcnt(0)
	s_barrier
; template <int NI> ...
;     ...
;   for (int kt = 0; kt < nk; kt += 2) {
;     G_LOAD(a0, b0, min((kt + 2) * 32, klast));
;     G_COMPUTE(0);
;     G_WRITE(a1, b1, 1);
;     __syncthreads();
;     G_LOAD(a1, b1, min((kt + 3) * 32, klast));
;     G_COMPUTE(1);
;     G_WRITE(a0, b0, 0);
;     __syncthreads();
;   }
	s_add_u32 m0, s56, 0x4000
	s_nop 0
	global_load_lds_dwordx4 v244, s[26:27]
	s_add_u32 m0, s56, 0x4400
	s_nop 0
	global_load_lds_dwordx4 v245, s[26:27]
	s_add_u32 m0, s56, 0x4800
	s_nop 0
	global_load_lds_dwordx4 v246, s[26:27]
	s_add_u32 m0, s56, 0x4c00
	s_nop 0
	global_load_lds_dwordx4 v247, s[26:27]
	s_add_u32 s26, s26, 128
	s_addc_u32 s27, s27, 0
	v_mfma_f32_16x16x32_bf16 v[0:3], v[216:219], v[200:203], v[0:3]
	ds_read_b128 v[168:171], v248 offset:49152
	v_mfma_f32_16x16x32_bf16 v[4:7], v[220:223], v[200:203], v[4:7]
	ds_read_b128 v[184:187], v226 offset:49152
	v_mfma_f32_16x16x32_bf16 v[8:11], v[228:231], v[200:203], v[8:11]
	ds_read_b128 v[172:175], v248 offset:51200
	v_mfma_f32_16x16x32_bf16 v[12:15], v[232:235], v[200:203], v[12:15]
	ds_read_b128 v[188:191], v226 offset:49664
	v_mfma_f32_16x16x32_bf16 v[16:19], v[216:219], v[204:207], v[16:19]
	ds_read_b128 v[176:179], v248 offset:53248
	v_mfma_f32_16x16x32_bf16 v[20:23], v[220:223], v[204:207], v[20:23]
	ds_read_b128 v[192:195], v226 offset:50176
	v_mfma_f32_16x16x32_bf16 v[24:27], v[228:231], v[204:207], v[24:27]
	ds_read_b128 v[180:183], v248 offset:55296
	v_mfma_f32_16x16x32_bf16 v[28:31], v[232:235], v[204:207], v[28:31]
	ds_read_b128 v[196:199], v226 offset:50688
	v_mfma_f32_16x16x32_bf16 v[32:35], v[216:219], v[208:211], v[32:35]
	v_mfma_f32_16x16x32_bf16 v[36:39], v[220:223], v[208:211], v[36:39]
	v_mfma_f32_16x16x32_bf16 v[40:43], v[228:231], v[208:211], v[40:43]
	v_mfma_f32_16x16x32_bf16 v[44:47], v[232:235], v[208:211], v[44:47]
	v_mfma_f32_16x16x32_bf16 v[48:51], v[216:219], v[212:215], v[48:51]
	v_mfma_f32_16x16x32_bf16 v[52:55], v[220:223], v[212:215], v[52:55]
	v_mfma_f32_16x16x32_bf16 v[56:59], v[228:231], v[212:215], v[56:59]
	v_mfma_f32_16x16x32_bf16 v[60:63], v[232:235], v[212:215], v[60:63]
	s_waitcnt lgkmcnt(0)
	s_add_u32 m0, s56, 0x8000
	s_nop 0
	global_load_lds_dwordx4 v236, s[24:25]
	s_add_u32 m0, s56, 0x8400
	s_nop 0
	global_load_lds_dwordx4 v237, s[24:25]
	s_add_u32 m0, s56, 0x8800
	s_nop 0
	global_load_lds_dwordx4 v238, s[24:25]
	s_add_u32 m0, s56, 0x8c00
	s_nop 0
	global_load_lds_dwordx4 v239, s[24:25]
	s_add_u32 s24, s24, 128
	s_addc_u32 s25, s25, 0
	v_mfma_f32_16x16x32_bf16 v[0:3], v[184:187], v[168:171], v[0:3]
	ds_read_b128 v[200:203], v249 offset:49152
	v_mfma_f32_16x16x32_bf16 v[4:7], v[188:191], v[168:171], v[4:7]
	ds_read_b128 v[216:219], v227 offset:49152
	v_mfma_f32_16x16x32_bf16 v[8:11], v[192:195], v[168:171], v[8:11]
	ds_read_b128 v[204:207], v249 offset:51200
	v_mfma_f32_16x16x32_bf16 v[12:15], v[196:199], v[168:171], v[12:15]
	ds_read_b128 v[220:223], v227 offset:49664
	v_mfma_f32_16x16x32_bf16 v[16:19], v[184:187], v[172:175], v[16:19]
	ds_read_b128 v[208:211], v249 offset:53248
	v_mfma_f32_16x16x32_bf16 v[20:23], v[188:191], v[172:175], v[20:23]
	ds_read_b128 v[228:231], v227 offset:50176
	v_mfma_f32_16x16x32_bf16 v[24:27], v[192:195], v[172:175], v[24:27]
	ds_read_b128 v[212:215], v249 offset:55296
	v_mfma_f32_16x16x32_bf16 v[28:31], v[196:199], v[172:175], v[28:31]
	ds_read_b128 v[232:235], v227 offset:50688
	v_mfma_f32_16x16x32_bf16 v[32:35], v[184:187], v[176:179], v[32:35]
	v_mfma_f32_16x16x32_bf16 v[36:39], v[188:191], v[176:179], v[36:39]
	v_mfma_f32_16x16x32_bf16 v[40:43], v[192:195], v[176:179], v[40:43]
	v_mfma_f32_16x16x32_bf16 v[44:47], v[196:199], v[176:179], v[44:47]
	v_mfma_f32_16x16x32_bf16 v[48:51], v[184:187], v[180:183], v[48:51]
	v_mfma_f32_16x16x32_bf16 v[52:55], v[188:191], v[180:183], v[52:55]
	v_mfma_f32_16x16x32_bf16 v[56:59], v[192:195], v[180:183], v[56:59]
	v_mfma_f32_16x16x32_bf16 v[60:63], v[196:199], v[180:183], v[60:63]
	s_waitcnt vmcnt(4) lgkmcnt(0)
	s_barrier
	s_add_u32 m0, s56, 0xc000
	s_nop 0
	global_load_lds_dwordx4 v244, s[26:27]
	s_add_u32 m0, s56, 0xc400
	s_nop 0
	global_load_lds_dwordx4 v245, s[26:27]
	s_add_u32 m0, s56, 0xc800
	s_nop 0
	global_load_lds_dwordx4 v246, s[26:27]
	s_add_u32 m0, s56, 0xcc00
	s_nop 0
	global_load_lds_dwordx4 v247, s[26:27]
	s_add_u32 s26, s26, 128
	s_addc_u32 s27, s27, 0
	v_mfma_f32_16x16x32_bf16 v[0:3], v[216:219], v[200:203], v[0:3]
	ds_read_b128 v[168:171], v248 offset:0
	v_mfma_f32_16x16x32_bf16 v[4:7], v[220:223], v[200:203], v[4:7]
	ds_read_b128 v[184:187], v250 offset:16384
	v_mfma_f32_16x16x32_bf16 v[8:11], v[228:231], v[200:203], v[8:11]
	ds_read_b128 v[172:175], v248 offset:2048
	v_mfma_f32_16x16x32_bf16 v[12:15], v[232:235], v[200:203], v[12:15]
	ds_read_b128 v[188:191], v250 offset:16896
	v_mfma_f32_16x16x32_bf16 v[16:19], v[216:219], v[204:207], v[16:19]
	ds_read_b128 v[176:179], v248 offset:4096
	v_mfma_f32_16x16x32_bf16 v[20:23], v[220:223], v[204:207], v[20:23]
	ds_read_b128 v[192:195], v250 offset:17408
	v_mfma_f32_16x16x32_bf16 v[24:27], v[228:231], v[204:207], v[24:27]
	ds_read_b128 v[180:183], v248 offset:6144
	v_mfma_f32_16x16x32_bf16 v[28:31], v[232:235], v[204:207], v[28:31]
	ds_read_b128 v[196:199], v250 offset:17920
	v_mfma_f32_16x16x32_bf16 v[32:35], v[216:219], v[208:211], v[32:35]
	v_mfma_f32_16x16x32_bf16 v[36:39], v[220:223], v[208:211], v[36:39]
	v_mfma_f32_16x16x32_bf16 v[40:43], v[228:231], v[208:211], v[40:43]
	v_mfma_f32_16x16x32_bf16 v[44:47], v[232:235], v[208:211], v[44:47]
	v_mfma_f32_16x16x32_bf16 v[48:51], v[216:219], v[212:215], v[48:51]
	v_mfma_f32_16x16x32_bf16 v[52:55], v[220:223], v[212:215], v[52:55]
	v_mfma_f32_16x16x32_bf16 v[56:59], v[228:231], v[212:215], v[56:59]
	v_mfma_f32_16x16x32_bf16 v[60:63], v[232:235], v[212:215], v[60:63]
	s_waitcnt lgkmcnt(0)
; template <int NI> ...
;     ...
;   for (int kt = 0; kt < nk; kt += 2) {
;     G_LOAD(a0, b0, min((kt + 2) * 32, klast));
;     G_COMPUTE(0);
;     G_WRITE(a1, b1, 1);
;     __syncthreads();
;     G_LOAD(a1, b1, min((kt + 3) * 32, klast));
;     G_COMPUTE(1);
;     G_WRITE(a0, b0, 0);
;     __syncthreads();
;   }
	s_add_u32 m0, s56, 0x10000
	s_nop 0
	global_load_lds_dwordx4 v236, s[24:25]
	s_add_u32 m0, s56, 0x10400
	s_nop 0
	global_load_lds_dwordx4 v237, s[24:25]
	s_add_u32 m0, s56, 0x10800
	s_nop 0
	global_load_lds_dwordx4 v238, s[24:25]
	s_add_u32 m0, s56, 0x10c00
	s_nop 0
	global_load_lds_dwordx4 v239, s[24:25]
	s_add_u32 s24, s24, 128
	s_addc_u32 s25, s25, 0
	v_mfma_f32_16x16x32_bf16 v[0:3], v[184:187], v[168:171], v[0:3]
	ds_read_b128 v[200:203], v249 offset:0
	v_mfma_f32_16x16x32_bf16 v[4:7], v[188:191], v[168:171], v[4:7]
	ds_read_b128 v[216:219], v251 offset:16384
	v_mfma_f32_16x16x32_bf16 v[8:11], v[192:195], v[168:171], v[8:11]
	ds_read_b128 v[204:207], v249 offset:2048
	v_mfma_f32_16x16x32_bf16 v[12:15], v[196:199], v[168:171], v[12:15]
	ds_read_b128 v[220:223], v251 offset:16896
	v_mfma_f32_16x16x32_bf16 v[16:19], v[184:187], v[172:175], v[16:19]
	ds_read_b128 v[208:211], v249 offset:4096
	v_mfma_f32_16x16x32_bf16 v[20:23], v[188:191], v[172:175], v[20:23]
	ds_read_b128 v[228:231], v251 offset:17408
	v_mfma_f32_16x16x32_bf16 v[24:27], v[192:195], v[172:175], v[24:27]
	ds_read_b128 v[212:215], v249 offset:6144
	v_mfma_f32_16x16x32_bf16 v[28:31], v[196:199], v[172:175], v[28:31]
	ds_read_b128 v[232:235], v251 offset:17920
	v_mfma_f32_16x16x32_bf16 v[32:35], v[184:187], v[176:179], v[32:35]
	v_mfma_f32_16x16x32_bf16 v[36:39], v[188:191], v[176:179], v[36:39]
	v_mfma_f32_16x16x32_bf16 v[40:43], v[192:195], v[176:179], v[40:43]
	v_mfma_f32_16x16x32_bf16 v[44:47], v[196:199], v[176:179], v[44:47]
	v_mfma_f32_16x16x32_bf16 v[48:51], v[184:187], v[180:183], v[48:51]
	v_mfma_f32_16x16x32_bf16 v[52:55], v[188:191], v[180:183], v[52:55]
	v_mfma_f32_16x16x32_bf16 v[56:59], v[192:195], v[180:183], v[56:59]
	v_mfma_f32_16x16x32_bf16 v[60:63], v[196:199], v[180:183], v[60:63]
	s_waitcnt vmcnt(4) lgkmcnt(0)
	s_barrier
	s_add_u32 m0, s56, 0x0
	s_nop 0
	global_load_lds_dwordx4 v244, s[26:27]
	s_add_u32 m0, s56, 0x400
	s_nop 0
	global_load_lds_dwordx4 v245, s[26:27]
	s_add_u32 m0, s56, 0x800
	s_nop 0
	global_load_lds_dwordx4 v246, s[26:27]
	s_add_u32 m0, s56, 0xc00
	s_nop 0
	global_load_lds_dwordx4 v247, s[26:27]
	s_add_u32 s26, s26, 128
	s_addc_u32 s27, s27, 0
	v_mfma_f32_16x16x32_bf16 v[0:3], v[216:219], v[200:203], v[0:3]
	ds_read_b128 v[168:171], v248 offset:32768
	v_mfma_f32_16x16x32_bf16 v[4:7], v[220:223], v[200:203], v[4:7]
	ds_read_b128 v[184:187], v250 offset:49152
	v_mfma_f32_16x16x32_bf16 v[8:11], v[228:231], v[200:203], v[8:11]
	ds_read_b128 v[172:175], v248 offset:34816
	v_mfma_f32_16x16x32_bf16 v[12:15], v[232:235], v[200:203], v[12:15]
	ds_read_b128 v[188:191], v250 offset:49664
	v_mfma_f32_16x16x32_bf16 v[16:19], v[216:219], v[204:207], v[16:19]
	ds_read_b128 v[176:179], v248 offset:36864
	v_mfma_f32_16x16x32_bf16 v[20:23], v[220:223], v[204:207], v[20:23]
	ds_read_b128 v[192:195], v250 offset:50176
	v_mfma_f32_16x16x32_bf16 v[24:27], v[228:231], v[204:207], v[24:27]
	ds_read_b128 v[180:183], v248 offset:38912
	v_mfma_f32_16x16x32_bf16 v[28:31], v[232:235], v[204:207], v[28:31]
	ds_read_b128 v[196:199], v250 offset:50688
	v_mfma_f32_16x16x32_bf16 v[32:35], v[216:219], v[208:211], v[32:35]
	v_mfma_f32_16x16x32_bf16 v[36:39], v[220:223], v[208:211], v[36:39]
	v_mfma_f32_16x16x32_bf16 v[40:43], v[228:231], v[208:211], v[40:43]
	v_mfma_f32_16x16x32_bf16 v[44:47], v[232:235], v[208:211], v[44:47]
	v_mfma_f32_16x16x32_bf16 v[48:51], v[216:219], v[212:215], v[48:51]
	v_mfma_f32_16x16x32_bf16 v[52:55], v[220:223], v[212:215], v[52:55]
	v_mfma_f32_16x16x32_bf16 v[56:59], v[228:231], v[212:215], v[56:59]
	v_mfma_f32_16x16x32_bf16 v[60:63], v[232:235], v[212:215], v[60:63]
	s_waitcnt lgkmcnt(0)
	s_add_u32 m0, s56, 0x4000
	s_nop 0
	global_load_lds_dwordx4 v236, s[24:25]
	s_add_u32 m0, s56, 0x4400
	s_nop 0
	global_load_lds_dwordx4 v237, s[24:25]
	s_add_u32 m0, s56, 0x4800
	s_nop 0
	global_load_lds_dwordx4 v238, s[24:25]
	s_add_u32 m0, s56, 0x4c00
	s_nop 0
	global_load_lds_dwordx4 v239, s[24:25]
	s_add_u32 s24, s24, 128
	s_addc_u32 s25, s25, 0
	v_mfma_f32_16x16x32_bf16 v[0:3], v[184:187], v[168:171], v[0:3]
	ds_read_b128 v[200:203], v249 offset:32768
	v_mfma_f32_16x16x32_bf16 v[4:7], v[188:191], v[168:171], v[4:7]
	ds_read_b128 v[216:219], v251 offset:49152
	v_mfma_f32_16x16x32_bf16 v[8:11], v[192:195], v[168:171], v[8:11]
	ds_read_b128 v[204:207], v249 offset:34816
	v_mfma_f32_16x16x32_bf16 v[12:15], v[196:199], v[168:171], v[12:15]
	ds_read_b128 v[220:223], v251 offset:49664
	v_mfma_f32_16x16x32_bf16 v[16:19], v[184:187], v[172:175], v[16:19]
	ds_read_b128 v[208:211], v249 offset:36864
	v_mfma_f32_16x16x32_bf16 v[20:23], v[188:191], v[172:175], v[20:23]
	ds_read_b128 v[228:231], v251 offset:50176
	v_mfma_f32_16x16x32_bf16 v[24:27], v[192:195], v[172:175], v[24:27]
	ds_read_b128 v[212:215], v249 offset:38912
	v_mfma_f32_16x16x32_bf16 v[28:31], v[196:199], v[172:175], v[28:31]
	ds_read_b128 v[232:235], v251 offset:50688
	v_mfma_f32_16x16x32_bf16 v[32:35], v[184:187], v[176:179], v[32:35]
	v_mfma_f32_16x16x32_bf16 v[36:39], v[188:191], v[176:179], v[36:39]
	v_mfma_f32_16x16x32_bf16 v[40:43], v[192:195], v[176:179], v[40:43]
	v_mfma_f32_16x16x32_bf16 v[44:47], v[196:199], v[176:179], v[44:47]
	v_mfma_f32_16x16x32_bf16 v[48:51], v[184:187], v[180:183], v[48:51]
	v_mfma_f32_16x16x32_bf16 v[52:55], v[188:191], v[180:183], v[52:55]
	v_mfma_f32_16x16x32_bf16 v[56:59], v[192:195], v[180:183], v[56:59]
	v_mfma_f32_16x16x32_bf16 v[60:63], v[196:199], v[180:183], v[60:63]
	s_waitcnt vmcnt(4) lgkmcnt(0)
	s_barrier
; template <int NI> ...
;     ...
;   for (int kt = 0; kt < nk; kt += 2) {
;     G_LOAD(a0, b0, min((kt + 2) * 32, klast));
;     G_COMPUTE(0);
;     G_WRITE(a1, b1, 1);
;     __syncthreads();
;     G_LOAD(a1, b1, min((kt + 3) * 32, klast));
;     G_COMPUTE(1);
;     G_WRITE(a0, b0, 0);
;     __syncthreads();
;   }
	s_add_u32 m0, s56, 0x8000
	s_nop 0
	global_load_lds_dwordx4 v244, s[26:27]
	s_add_u32 m0, s56, 0x8400
	s_nop 0
	global_load_lds_dwordx4 v245, s[26:27]
	s_add_u32 m0, s56, 0x8800
	s_nop 0
	global_load_lds_dwordx4 v246, s[26:27]
	s_add_u32 m0, s56, 0x8c00
	s_nop 0
	global_load_lds_dwordx4 v247, s[26:27]
	s_add_u32 s26, s26, 128
	s_addc_u32 s27, s27, 0
	v_mfma_f32_16x16x32_bf16 v[0:3], v[216:219], v[200:203], v[0:3]
	ds_read_b128 v[168:171], v166 offset:49152
	v_mfma_f32_16x16x32_bf16 v[4:7], v[220:223], v[200:203], v[4:7]
	ds_read_b128 v[184:187], v250 offset:0
	v_mfma_f32_16x16x32_bf16 v[8:11], v[228:231], v[200:203], v[8:11]
	ds_read_b128 v[172:175], v166 offset:51200
	v_mfma_f32_16x16x32_bf16 v[12:15], v[232:235], v[200:203], v[12:15]
	ds_read_b128 v[188:191], v250 offset:512
	v_mfma_f32_16x16x32_bf16 v[16:19], v[216:219], v[204:207], v[16:19]
	ds_read_b128 v[176:179], v166 offset:53248
	v_mfma_f32_16x16x32_bf16 v[20:23], v[220:223], v[204:207], v[20:23]
	ds_read_b128 v[192:195], v250 offset:1024
	v_mfma_f32_16x16x32_bf16 v[24:27], v[228:231], v[204:207], v[24:27]
	ds_read_b128 v[180:183], v166 offset:55296
	v_mfma_f32_16x16x32_bf16 v[28:31], v[232:235], v[204:207], v[28:31]
	ds_read_b128 v[196:199], v250 offset:1536
	v_mfma_f32_16x16x32_bf16 v[32:35], v[216:219], v[208:211], v[32:35]
	v_mfma_f32_16x16x32_bf16 v[36:39], v[220:223], v[208:211], v[36:39]
	v_mfma_f32_16x16x32_bf16 v[40:43], v[228:231], v[208:211], v[40:43]
	v_mfma_f32_16x16x32_bf16 v[44:47], v[232:235], v[208:211], v[44:47]
	v_mfma_f32_16x16x32_bf16 v[48:51], v[216:219], v[212:215], v[48:51]
	v_mfma_f32_16x16x32_bf16 v[52:55], v[220:223], v[212:215], v[52:55]
	v_mfma_f32_16x16x32_bf16 v[56:59], v[228:231], v[212:215], v[56:59]
	v_mfma_f32_16x16x32_bf16 v[60:63], v[232:235], v[212:215], v[60:63]
	s_waitcnt lgkmcnt(0)
	s_add_u32 m0, s56, 0xc000
	s_nop 0
	global_load_lds_dwordx4 v236, s[24:25]
	s_add_u32 m0, s56, 0xc400
	s_nop 0
	global_load_lds_dwordx4 v237, s[24:25]
	s_add_u32 m0, s56, 0xc800
	s_nop 0
	global_load_lds_dwordx4 v238, s[24:25]
	s_add_u32 m0, s56, 0xcc00
	s_nop 0
	global_load_lds_dwordx4 v239, s[24:25]
	s_add_u32 s24, s24, 128
	s_addc_u32 s25, s25, 0
	v_mfma_f32_16x16x32_bf16 v[0:3], v[184:187], v[168:171], v[0:3]
	ds_read_b128 v[200:203], v167 offset:49152
	v_mfma_f32_16x16x32_bf16 v[4:7], v[188:191], v[168:171], v[4:7]
	ds_read_b128 v[216:219], v251 offset:0
	v_mfma_f32_16x16x32_bf16 v[8:11], v[192:195], v[168:171], v[8:11]
	ds_read_b128 v[204:207], v167 offset:51200
	v_mfma_f32_16x16x32_bf16 v[12:15], v[196:199], v[168:171], v[12:15]
	ds_read_b128 v[220:223], v251 offset:512
	v_mfma_f32_16x16x32_bf16 v[16:19], v[184:187], v[172:175], v[16:19]
	ds_read_b128 v[208:211], v167 offset:53248
	v_mfma_f32_16x16x32_bf16 v[20:23], v[188:191], v[172:175], v[20:23]
	ds_read_b128 v[228:231], v251 offset:1024
	v_mfma_f32_16x16x32_bf16 v[24:27], v[192:195], v[172:175], v[24:27]
	ds_read_b128 v[212:215], v167 offset:55296
	v_mfma_f32_16x16x32_bf16 v[28:31], v[196:199], v[172:175], v[28:31]
	ds_read_b128 v[232:235], v251 offset:1536
	v_mfma_f32_16x16x32_bf16 v[32:35], v[184:187], v[176:179], v[32:35]
	v_mfma_f32_16x16x32_bf16 v[36:39], v[188:191], v[176:179], v[36:39]
	v_mfma_f32_16x16x32_bf16 v[40:43], v[192:195], v[176:179], v[40:43]
	v_mfma_f32_16x16x32_bf16 v[44:47], v[196:199], v[176:179], v[44:47]
	v_mfma_f32_16x16x32_bf16 v[48:51], v[184:187], v[180:183], v[48:51]
	v_mfma_f32_16x16x32_bf16 v[52:55], v[188:191], v[180:183], v[52:55]
	v_mfma_f32_16x16x32_bf16 v[56:59], v[192:195], v[180:183], v[56:59]
	v_mfma_f32_16x16x32_bf16 v[60:63], v[196:199], v[180:183], v[60:63]
	s_waitcnt vmcnt(4) lgkmcnt(0)
	s_barrier
	s_add_u32 m0, s56, 0x10000
	s_nop 0
	global_load_lds_dwordx4 v244, s[26:27]
	s_add_u32 m0, s56, 0x10400
	s_nop 0
	global_load_lds_dwordx4 v245, s[26:27]
	s_add_u32 m0, s56, 0x10800
	s_nop 0
	global_load_lds_dwordx4 v246, s[26:27]
	s_add_u32 m0, s56, 0x10c00
	s_nop 0
	global_load_lds_dwordx4 v247, s[26:27]
	s_add_u32 s26, s26, 128
	s_addc_u32 s27, s27, 0
	v_mfma_f32_16x16x32_bf16 v[0:3], v[216:219], v[200:203], v[0:3]
	ds_read_b128 v[168:171], v248 offset:16384
	v_mfma_f32_16x16x32_bf16 v[4:7], v[220:223], v[200:203], v[4:7]
	ds_read_b128 v[184:187], v250 offset:32768
	v_mfma_f32_16x16x32_bf16 v[8:11], v[228:231], v[200:203], v[8:11]
	ds_read_b128 v[172:175], v248 offset:18432
	v_mfma_f32_16x16x32_bf16 v[12:15], v[232:235], v[200:203], v[12:15]
	ds_read_b128 v[188:191], v250 offset:33280
	v_mfma_f32_16x16x32_bf16 v[16:19], v[216:219], v[204:207], v[16:19]
	ds_read_b128 v[176:179], v248 offset:20480
	v_mfma_f32_16x16x32_bf16 v[20:23], v[220:223], v[204:207], v[20:23]
	ds_read_b128 v[192:195], v250 offset:33792
	v_mfma_f32_16x16x32_bf16 v[24:27], v[228:231], v[204:207], v[24:27]
	ds_read_b128 v[180:183], v248 offset:22528
	v_mfma_f32_16x16x32_bf16 v[28:31], v[232:235], v[204:207], v[28:31]
	ds_read_b128 v[196:199], v250 offset:34304
	v_mfma_f32_16x16x32_bf16 v[32:35], v[216:219], v[208:211], v[32:35]
	v_mfma_f32_16x16x32_bf16 v[36:39], v[220:223], v[208:211], v[36:39]
	v_mfma_f32_16x16x32_bf16 v[40:43], v[228:231], v[208:211], v[40:43]
	v_mfma_f32_16x16x32_bf16 v[44:47], v[232:235], v[208:211], v[44:47]
	v_mfma_f32_16x16x32_bf16 v[48:51], v[216:219], v[212:215], v[48:51]
	v_mfma_f32_16x16x32_bf16 v[52:55], v[220:223], v[212:215], v[52:55]
	v_mfma_f32_16x16x32_bf16 v[56:59], v[228:231], v[212:215], v[56:59]
	v_mfma_f32_16x16x32_bf16 v[60:63], v[232:235], v[212:215], v[60:63]
	s_waitcnt lgkmcnt(0)
; template <int NI> ...
;     ...
;   for (int kt = 0; kt < nk; kt += 2) {
;     G_LOAD(a0, b0, min((kt + 2) * 32, klast));
;     G_COMPUTE(0);
;     G_WRITE(a1, b1, 1);
;     __syncthreads();
;     G_LOAD(a1, b1, min((kt + 3) * 32, klast));
;     G_COMPUTE(1);
;     G_WRITE(a0, b0, 0);
;     __syncthreads();
;   }
; __device__ void phase_merge4(CParams& p, int l, int tm, int tn, char* smem) {
;     ...
;   for (int kb0 = 0; kb0 < 4; kb0++) {
;     int kb = kb0;
;     asm volatile("" : "+s"(kb));
;     int tid2 = tid;
;     asm volatile("" : "+v"(tid2));
;     unsigned pk[4][4][2];
;     {
;       f32x4 acc[4][4];
;       zero_acc<4>(acc);
;       gemm_mainloop<4>(p.br + (size_t)row0 * 1024 + kb * 256, 1024,
;                        p.WbT + (((size_t)l * 4 + kb) * 1024 + col0) * 256, 256, 256, sA, sB, acc, tid2);
	s_mov_b64 s[24:25], s[28:29]
	s_add_u32 m0, s56, 0x0
	s_nop 0
	global_load_lds_dwordx4 v236, s[24:25]
	s_add_u32 m0, s56, 0x400
	s_nop 0
	global_load_lds_dwordx4 v237, s[24:25]
	s_add_u32 m0, s56, 0x800
	s_nop 0
	global_load_lds_dwordx4 v238, s[24:25]
	s_add_u32 m0, s56, 0xc00
	s_nop 0
	global_load_lds_dwordx4 v239, s[24:25]
	s_add_u32 s24, s24, 128
	s_addc_u32 s25, s25, 0
	v_mfma_f32_16x16x32_bf16 v[0:3], v[184:187], v[168:171], v[0:3]
	ds_read_b128 v[200:203], v249 offset:16384
	v_mfma_f32_16x16x32_bf16 v[4:7], v[188:191], v[168:171], v[4:7]
	ds_read_b128 v[216:219], v251 offset:32768
	v_mfma_f32_16x16x32_bf16 v[8:11], v[192:195], v[168:171], v[8:11]
	ds_read_b128 v[204:207], v249 offset:18432
	v_mfma_f32_16x16x32_bf16 v[12:15], v[196:199], v[168:171], v[12:15]
	ds_read_b128 v[220:223], v251 offset:33280
	v_mfma_f32_16x16x32_bf16 v[16:19], v[184:187], v[172:175], v[16:19]
	ds_read_b128 v[208:211], v249 offset:20480
	v_mfma_f32_16x16x32_bf16 v[20:23], v[188:191], v[172:175], v[20:23]
	ds_read_b128 v[228:231], v251 offset:33792
	v_mfma_f32_16x16x32_bf16 v[24:27], v[192:195], v[172:175], v[24:27]
	ds_read_b128 v[212:215], v249 offset:22528
	v_mfma_f32_16x16x32_bf16 v[28:31], v[196:199], v[172:175], v[28:31]
	ds_read_b128 v[232:235], v251 offset:34304
	v_mfma_f32_16x16x32_bf16 v[32:35], v[184:187], v[176:179], v[32:35]
	v_mfma_f32_16x16x32_bf16 v[36:39], v[188:191], v[176:179], v[36:39]
	v_mfma_f32_16x16x32_bf16 v[40:43], v[192:195], v[176:179], v[40:43]
	v_mfma_f32_16x16x32_bf16 v[44:47], v[196:199], v[176:179], v[44:47]
	v_mfma_f32_16x16x32_bf16 v[48:51], v[184:187], v[180:183], v[48:51]
	v_mfma_f32_16x16x32_bf16 v[52:55], v[188:191], v[180:183], v[52:55]
	v_mfma_f32_16x16x32_bf16 v[56:59], v[192:195], v[180:183], v[56:59]
	v_mfma_f32_16x16x32_bf16 v[60:63], v[196:199], v[180:183], v[60:63]
	s_waitcnt vmcnt(4) lgkmcnt(0)
	s_barrier
	s_mov_b64 s[26:27], s[44:45]
	s_add_u32 m0, s56, 0x4000
	s_nop 0
	global_load_lds_dwordx4 v240, s[26:27]
	s_add_u32 m0, s56, 0x4400
	s_nop 0
	global_load_lds_dwordx4 v241, s[26:27]
	s_add_u32 m0, s56, 0x4800
	s_nop 0
	global_load_lds_dwordx4 v242, s[26:27]
	s_add_u32 m0, s56, 0x4c00
	s_nop 0
	global_load_lds_dwordx4 v243, s[26:27]
	s_add_u32 s26, s26, 128
	s_addc_u32 s27, s27, 0
	v_mfma_f32_16x16x32_bf16 v[0:3], v[216:219], v[200:203], v[0:3]
	ds_read_b128 v[168:171], v248 offset:49152
	v_mfma_f32_16x16x32_bf16 v[4:7], v[220:223], v[200:203], v[4:7]
	ds_read_b128 v[184:187], v226 offset:49152
	v_mfma_f32_16x16x32_bf16 v[8:11], v[228:231], v[200:203], v[8:11]
	ds_read_b128 v[172:175], v248 offset:51200
	v_mfma_f32_16x16x32_bf16 v[12:15], v[232:235], v[200:203], v[12:15]
	ds_read_b128 v[188:191], v226 offset:49664
	v_mfma_f32_16x16x32_bf16 v[16:19], v[216:219], v[204:207], v[16:19]
	ds_read_b128 v[176:179], v248 offset:53248
	v_mfma_f32_16x16x32_bf16 v[20:23], v[220:223], v[204:207], v[20:23]
	ds_read_b128 v[192:195], v226 offset:50176
	v_mfma_f32_16x16x32_bf16 v[24:27], v[228:231], v[204:207], v[24:27]
	ds_read_b128 v[180:183], v248 offset:55296
	v_mfma_f32_16x16x32_bf16 v[28:31], v[232:235], v[204:207], v[28:31]
	ds_read_b128 v[196:199], v226 offset:50688
	v_mfma_f32_16x16x32_bf16 v[32:35], v[216:219], v[208:211], v[32:35]
	v_mfma_f32_16x16x32_bf16 v[36:39], v[220:223], v[208:211], v[36:39]
	v_mfma_f32_16x16x32_bf16 v[40:43], v[228:231], v[208:211], v[40:43]
	v_mfma_f32_16x16x32_bf16 v[44:47], v[232:235], v[208:211], v[44:47]
	v_mfma_f32_16x16x32_bf16 v[48:51], v[216:219], v[212:215], v[48:51]
	v_mfma_f32_16x16x32_bf16 v[52:55], v[220:223], v[212:215], v[52:55]
	v_mfma_f32_16x16x32_bf16 v[56:59], v[228:231], v[212:215], v[56:59]
	v_mfma_f32_16x16x32_bf16 v[60:63], v[232:235], v[212:215], v[60:63]
	s_waitcnt lgkmcnt(0)
	s_add_u32 m0, s56, 0x8000
	s_nop 0
	global_load_lds_dwordx4 v236, s[24:25]
	s_add_u32 m0, s56, 0x8400
	s_nop 0
	global_load_lds_dwordx4 v237, s[24:25]
	s_add_u32 m0, s56, 0x8800
	s_nop 0
	global_load_lds_dwordx4 v238, s[24:25]
	s_add_u32 m0, s56, 0x8c00
	s_nop 0
	global_load_lds_dwordx4 v239, s[24:25]
	s_add_u32 s24, s24, 128
	s_addc_u32 s25, s25, 0
	v_mfma_f32_16x16x32_bf16 v[0:3], v[184:187], v[168:171], v[0:3]
	ds_read_b128 v[200:203], v249 offset:49152
	v_mfma_f32_16x16x32_bf16 v[4:7], v[188:191], v[168:171], v[4:7]
	ds_read_b128 v[216:219], v227 offset:49152
	v_mfma_f32_16x16x32_bf16 v[8:11], v[192:195], v[168:171], v[8:11]
	ds_read_b128 v[204:207], v249 offset:51200
	v_mfma_f32_16x16x32_bf16 v[12:15], v[196:199], v[168:171], v[12:15]
	ds_read_b128 v[220:223], v227 offset:49664
	v_mfma_f32_16x16x32_bf16 v[16:19], v[184:187], v[172:175], v[16:19]
	ds_read_b128 v[208:211], v249 offset:53248
	v_mfma_f32_16x16x32_bf16 v[20:23], v[188:191], v[172:175], v[20:23]
	ds_read_b128 v[228:231], v227 offset:50176
	v_mfma_f32_16x16x32_bf16 v[24:27], v[192:195], v[172:175], v[24:27]
	ds_read_b128 v[212:215], v249 offset:55296
	v_mfma_f32_16x16x32_bf16 v[28:31], v[196:199], v[172:175], v[28:31]
	ds_read_b128 v[232:235], v227 offset:50688
	v_mfma_f32_16x16x32_bf16 v[32:35], v[184:187], v[176:179], v[32:35]
	v_mfma_f32_16x16x32_bf16 v[36:39], v[188:191], v[176:179], v[36:39]
	v_mfma_f32_16x16x32_bf16 v[40:43], v[192:195], v[176:179], v[40:43]
	v_mfma_f32_16x16x32_bf16 v[44:47], v[196:199], v[176:179], v[44:47]
	v_mfma_f32_16x16x32_bf16 v[48:51], v[184:187], v[180:183], v[48:51]
	v_mfma_f32_16x16x32_bf16 v[52:55], v[188:191], v[180:183], v[52:55]
	v_mfma_f32_16x16x32_bf16 v[56:59], v[192:195], v[180:183], v[56:59]
	v_mfma_f32_16x16x32_bf16 v[60:63], v[196:199], v[180:183], v[60:63]
	s_waitcnt vmcnt(4) lgkmcnt(0)
	s_barrier
; __device__ __forceinline__ float sigmoidf_(float v) { return 1.f / (1.f + __expf(-v)); }
; template <int NI> ...
;     ...
;   for (int kt = 0; kt < nk; kt += 2) {
;     G_LOAD(a0, b0, min((kt + 2) * 32, klast));
;     G_COMPUTE(0);
;     G_WRITE(a1, b1, 1);
;     __syncthreads();
;     G_LOAD(a1, b1, min((kt + 3) * 32, klast));
;     G_COMPUTE(1);
;     G_WRITE(a0, b0, 0);
;     __syncthreads();
;   }
; __device__ void phase_merge4(CParams& p, int l, int tm, int tn, char* smem) {
;     ...
; #pragma unroll
;     for (int mi = 0; mi < 4; mi++)
; #pragma unroll
;       for (int ni = 0; ni < 4; ni++) {
;         unsigned p0 = pk[mi][ni][0], p1 = pk[mi][ni][1], m0 = mer[mi][ni][0], m1 = mer[mi][ni][1];
;         float r0 = __uint_as_float(m0 << 16) + sigmoidf_(acc[mi][ni][0]) * __uint_as_float(p0 << 16);
;         float r1 = __uint_as_float(m0 & 0xffff0000u) + sigmoidf_(acc[mi][ni][1]) * __uint_as_float(p0 & 0xffff0000u);
;         float r2 = __uint_as_float(m1 << 16) + sigmoidf_(acc[mi][ni][2]) * __uint_as_float(p1 << 16);
;         float r3 = __uint_as_float(m1 & 0xffff0000u) + sigmoidf_(acc[mi][ni][3]) * __uint_as_float(p1 & 0xffff0000u);
;         mer[mi][ni][0] = (unsigned)f2bf(r0) | ((unsigned)f2bf(r1) << 16);
;         mer[mi][ni][1] = (unsigned)f2bf(r2) | ((unsigned)f2bf(r3) << 16);
;       }
	s_add_u32 m0, s56, 0xc000
	s_nop 0
	global_load_lds_dwordx4 v240, s[26:27]
	s_add_u32 m0, s56, 0xc400
	s_nop 0
	global_load_lds_dwordx4 v241, s[26:27]
	s_add_u32 m0, s56, 0xc800
	s_nop 0
	global_load_lds_dwordx4 v242, s[26:27]
	s_add_u32 m0, s56, 0xcc00
	s_nop 0
	global_load_lds_dwordx4 v243, s[26:27]
	s_add_u32 s26, s26, 128
	s_addc_u32 s27, s27, 0
	v_mfma_f32_16x16x32_bf16 v[0:3], v[216:219], v[200:203], v[0:3]
	ds_read_b128 v[168:171], v248 offset:0
	v_mfma_f32_16x16x32_bf16 v[4:7], v[220:223], v[200:203], v[4:7]
	ds_read_b128 v[184:187], v250 offset:16384
	v_mfma_f32_16x16x32_bf16 v[8:11], v[228:231], v[200:203], v[8:11]
	ds_read_b128 v[172:175], v248 offset:2048
	v_mfma_f32_16x16x32_bf16 v[12:15], v[232:235], v[200:203], v[12:15]
	ds_read_b128 v[188:191], v250 offset:16896
	v_mfma_f32_16x16x32_bf16 v[16:19], v[216:219], v[204:207], v[16:19]
	ds_read_b128 v[176:179], v248 offset:4096
	v_mfma_f32_16x16x32_bf16 v[20:23], v[220:223], v[204:207], v[20:23]
	ds_read_b128 v[192:195], v250 offset:17408
	v_mfma_f32_16x16x32_bf16 v[24:27], v[228:231], v[204:207], v[24:27]
	ds_read_b128 v[180:183], v248 offset:6144
	v_mfma_f32_16x16x32_bf16 v[28:31], v[232:235], v[204:207], v[28:31]
	ds_read_b128 v[196:199], v250 offset:17920
	v_mfma_f32_16x16x32_bf16 v[32:35], v[216:219], v[208:211], v[32:35]
	v_mfma_f32_16x16x32_bf16 v[36:39], v[220:223], v[208:211], v[36:39]
	v_mfma_f32_16x16x32_bf16 v[40:43], v[228:231], v[208:211], v[40:43]
	v_mfma_f32_16x16x32_bf16 v[44:47], v[232:235], v[208:211], v[44:47]
	v_mfma_f32_16x16x32_bf16 v[48:51], v[216:219], v[212:215], v[48:51]
	v_mfma_f32_16x16x32_bf16 v[52:55], v[220:223], v[212:215], v[52:55]
	v_mfma_f32_16x16x32_bf16 v[56:59], v[228:231], v[212:215], v[56:59]
	v_mfma_f32_16x16x32_bf16 v[60:63], v[232:235], v[212:215], v[60:63]
	s_nop 15
	s_nop 7
	v_mul_f32_e32 v200, 0xbfb8aa3b, v0
	v_mul_f32_e32 v201, 0xbfb8aa3b, v1
	v_mul_f32_e32 v202, 0xbfb8aa3b, v2
	v_mul_f32_e32 v203, 0xbfb8aa3b, v3
	v_mul_f32_e32 v204, 0xbfb8aa3b, v4
	v_mul_f32_e32 v205, 0xbfb8aa3b, v5
	v_mul_f32_e32 v206, 0xbfb8aa3b, v6
	v_mul_f32_e32 v207, 0xbfb8aa3b, v7
	v_exp_f32_e32 v200, v200
	v_exp_f32_e32 v201, v201
	v_exp_f32_e32 v202, v202
	v_exp_f32_e32 v203, v203
	v_exp_f32_e32 v204, v204
	v_exp_f32_e32 v205, v205
	v_exp_f32_e32 v206, v206
	v_exp_f32_e32 v207, v207
	v_add_f32_e32 v200, 1.0, v200
	v_add_f32_e32 v201, 1.0, v201
	v_add_f32_e32 v202, 1.0, v202
	v_add_f32_e32 v203, 1.0, v203
	v_add_f32_e32 v204, 1.0, v204
	v_add_f32_e32 v205, 1.0, v205
	v_add_f32_e32 v206, 1.0, v206
	v_add_f32_e32 v207, 1.0, v207
	v_rcp_f32_e32 v200, v200
	v_rcp_f32_e32 v201, v201
	v_rcp_f32_e32 v202, v202
	v_rcp_f32_e32 v203, v203
	v_rcp_f32_e32 v204, v204
	v_rcp_f32_e32 v205, v205
	v_rcp_f32_e32 v206, v206
	v_rcp_f32_e32 v207, v207
	v_lshlrev_b32_e32 v208, 16, v128
	v_and_b32_e32 v209, 0xffff0000, v128
	v_lshlrev_b32_e32 v210, 16, v129
	v_and_b32_e32 v211, 0xffff0000, v129
	v_lshlrev_b32_e32 v212, 16, v130
	v_and_b32_e32 v213, 0xffff0000, v130
	v_lshlrev_b32_e32 v214, 16, v131
	v_and_b32_e32 v215, 0xffff0000, v131
	v_fmac_f32_e32 v64, v200, v208
	v_fmac_f32_e32 v65, v201, v209
	v_fmac_f32_e32 v66, v202, v210
	v_fmac_f32_e32 v67, v203, v211
	v_fmac_f32_e32 v68, v204, v212
	v_fmac_f32_e32 v69, v205, v213
	v_fmac_f32_e32 v70, v206, v214
	v_fmac_f32_e32 v71, v207, v215
	v_mul_f32_e32 v200, 0xbfb8aa3b, v8
	v_mul_f32_e32 v201, 0xbfb8aa3b, v9
	v_mul_f32_e32 v202, 0xbfb8aa3b, v10
	v_mul_f32_e32 v203, 0xbfb8aa3b, v11
	v_mul_f32_e32 v204, 0xbfb8aa3b, v12
	v_mul_f32_e32 v205, 0xbfb8aa3b, v13
	v_mul_f32_e32 v206, 0xbfb8aa3b, v14
	v_mul_f32_e32 v207, 0xbfb8aa3b, v15
	v_exp_f32_e32 v200, v200
	v_exp_f32_e32 v201, v201
	v_exp_f32_e32 v202, v202
	v_exp_f32_e32 v203, v203
	v_exp_f32_e32 v204, v204
	v_exp_f32_e32 v205, v205
	v_exp_f32_e32 v206, v206
	v_exp_f32_e32 v207, v207
	v_add_f32_e32 v200, 1.0, v200
	v_add_f32_e32 v201, 1.0, v201
	v_add_f32_e32 v202, 1.0, v202
	v_add_f32_e32 v203, 1.0, v203
	v_add_f32_e32 v204, 1.0, v204
	v_add_f32_e32 v205, 1.0, v205
	v_add_f32_e32 v206, 1.0, v206
	v_add_f32_e32 v207, 1.0, v207
	v_rcp_f32_e32 v200, v200
	v_rcp_f32_e32 v201, v201
	v_rcp_f32_e32 v202, v202
	v_rcp_f32_e32 v203, v203
	v_rcp_f32_e32 v204, v204
	v_rcp_f32_e32 v205, v205
	v_rcp_f32_e32 v206, v206
	v_rcp_f32_e32 v207, v207
	v_lshlrev_b32_e32 v208, 16, v132
	v_and_b32_e32 v209, 0xffff0000, v132
	v_lshlrev_b32_e32 v210, 16, v133
	v_and_b32_e32 v211, 0xffff0000, v133
	v_lshlrev_b32_e32 v212, 16, v134
	v_and_b32_e32 v213, 0xffff0000, v134
	v_lshlrev_b32_e32 v214, 16, v135
	v_and_b32_e32 v215, 0xffff0000, v135
	v_fmac_f32_e32 v72, v200, v208
	v_fmac_f32_e32 v73, v201, v209
	v_fmac_f32_e32 v74, v202, v210
	v_fmac_f32_e32 v75, v203, v211
	v_fmac_f32_e32 v76, v204, v212
	v_fmac_f32_e32 v77, v205, v213
	v_fmac_f32_e32 v78, v206, v214
	v_fmac_f32_e32 v79, v207, v215
	v_mul_f32_e32 v200, 0xbfb8aa3b, v16
	v_mul_f32_e32 v201, 0xbfb8aa3b, v17
	v_mul_f32_e32 v202, 0xbfb8aa3b, v18
	v_mul_f32_e32 v203, 0xbfb8aa3b, v19
	v_mul_f32_e32 v204, 0xbfb8aa3b, v20
	v_mul_f32_e32 v205, 0xbfb8aa3b, v21
	v_mul_f32_e32 v206, 0xbfb8aa3b, v22
	v_mul_f32_e32 v207, 0xbfb8aa3b, v23
	v_exp_f32_e32 v200, v200
	v_exp_f32_e32 v201, v201
	v_exp_f32_e32 v202, v202
	v_exp_f32_e32 v203, v203
	v_exp_f32_e32 v204, v204
	v_exp_f32_e32 v205, v205
	v_exp_f32_e32 v206, v206
	v_exp_f32_e32 v207, v207
	v_add_f32_e32 v200, 1.0, v200
	v_add_f32_e32 v201, 1.0, v201
	v_add_f32_e32 v202, 1.0, v202
	v_add_f32_e32 v203, 1.0, v203
	v_add_f32_e32 v204, 1.0, v204
	v_add_f32_e32 v205, 1.0, v205
	v_add_f32_e32 v206, 1.0, v206
	v_add_f32_e32 v207, 1.0, v207
	v_rcp_f32_e32 v200, v200
	v_rcp_f32_e32 v201, v201
	v_rcp_f32_e32 v202, v202
; __device__ __forceinline__ float sigmoidf_(float v) { return 1.f / (1.f + __expf(-v)); }
; __device__ void phase_merge4(CParams& p, int l, int tm, int tn, char* smem) {
;     ...
; #pragma unroll
;     for (int mi = 0; mi < 4; mi++)
; #pragma unroll
;       for (int ni = 0; ni < 4; ni++) {
;         unsigned p0 = pk[mi][ni][0], p1 = pk[mi][ni][1], m0 = mer[mi][ni][0], m1 = mer[mi][ni][1];
;         float r0 = __uint_as_float(m0 << 16) + sigmoidf_(acc[mi][ni][0]) * __uint_as_float(p0 << 16);
;         float r1 = __uint_as_float(m0 & 0xffff0000u) + sigmoidf_(acc[mi][ni][1]) * __uint_as_float(p0 & 0xffff0000u);
;         float r2 = __uint_as_float(m1 << 16) + sigmoidf_(acc[mi][ni][2]) * __uint_as_float(p1 << 16);
;         float r3 = __uint_as_float(m1 & 0xffff0000u) + sigmoidf_(acc[mi][ni][3]) * __uint_as_float(p1 & 0xffff0000u);
;         mer[mi][ni][0] = (unsigned)f2bf(r0) | ((unsigned)f2bf(r1) << 16);
;         mer[mi][ni][1] = (unsigned)f2bf(r2) | ((unsigned)f2bf(r3) << 16);
;       }
	v_rcp_f32_e32 v203, v203
	v_rcp_f32_e32 v204, v204
	v_rcp_f32_e32 v205, v205
	v_rcp_f32_e32 v206, v206
	v_rcp_f32_e32 v207, v207
	v_lshlrev_b32_e32 v208, 16, v136
	v_and_b32_e32 v209, 0xffff0000, v136
	v_lshlrev_b32_e32 v210, 16, v137
	v_and_b32_e32 v211, 0xffff0000, v137
	v_lshlrev_b32_e32 v212, 16, v138
	v_and_b32_e32 v213, 0xffff0000, v138
	v_lshlrev_b32_e32 v214, 16, v139
	v_and_b32_e32 v215, 0xffff0000, v139
	v_fmac_f32_e32 v80, v200, v208
	v_fmac_f32_e32 v81, v201, v209
	v_fmac_f32_e32 v82, v202, v210
	v_fmac_f32_e32 v83, v203, v211
	v_fmac_f32_e32 v84, v204, v212
	v_fmac_f32_e32 v85, v205, v213
	v_fmac_f32_e32 v86, v206, v214
	v_fmac_f32_e32 v87, v207, v215
	v_mul_f32_e32 v200, 0xbfb8aa3b, v24
	v_mul_f32_e32 v201, 0xbfb8aa3b, v25
	v_mul_f32_e32 v202, 0xbfb8aa3b, v26
	v_mul_f32_e32 v203, 0xbfb8aa3b, v27
	v_mul_f32_e32 v204, 0xbfb8aa3b, v28
	v_mul_f32_e32 v205, 0xbfb8aa3b, v29
	v_mul_f32_e32 v206, 0xbfb8aa3b, v30
	v_mul_f32_e32 v207, 0xbfb8aa3b, v31
	v_exp_f32_e32 v200, v200
	v_exp_f32_e32 v201, v201
	v_exp_f32_e32 v202, v202
	v_exp_f32_e32 v203, v203
	v_exp_f32_e32 v204, v204
	v_exp_f32_e32 v205, v205
	v_exp_f32_e32 v206, v206
	v_exp_f32_e32 v207, v207
	v_add_f32_e32 v200, 1.0, v200
	v_add_f32_e32 v201, 1.0, v201
	v_add_f32_e32 v202, 1.0, v202
	v_add_f32_e32 v203, 1.0, v203
	v_add_f32_e32 v204, 1.0, v204
	v_add_f32_e32 v205, 1.0, v205
	v_add_f32_e32 v206, 1.0, v206
	v_add_f32_e32 v207, 1.0, v207
	v_rcp_f32_e32 v200, v200
	v_rcp_f32_e32 v201, v201
	v_rcp_f32_e32 v202, v202
	v_rcp_f32_e32 v203, v203
	v_rcp_f32_e32 v204, v204
	v_rcp_f32_e32 v205, v205
	v_rcp_f32_e32 v206, v206
	v_rcp_f32_e32 v207, v207
	v_lshlrev_b32_e32 v208, 16, v140
	v_and_b32_e32 v209, 0xffff0000, v140
	v_lshlrev_b32_e32 v210, 16, v141
	v_and_b32_e32 v211, 0xffff0000, v141
	v_lshlrev_b32_e32 v212, 16, v142
	v_and_b32_e32 v213, 0xffff0000, v142
	v_lshlrev_b32_e32 v214, 16, v143
	v_and_b32_e32 v215, 0xffff0000, v143
	v_fmac_f32_e32 v88, v200, v208
	v_fmac_f32_e32 v89, v201, v209
	v_fmac_f32_e32 v90, v202, v210
	v_fmac_f32_e32 v91, v203, v211
	v_fmac_f32_e32 v92, v204, v212
	v_fmac_f32_e32 v93, v205, v213
	v_fmac_f32_e32 v94, v206, v214
	v_fmac_f32_e32 v95, v207, v215
	v_mul_f32_e32 v200, 0xbfb8aa3b, v32
	v_mul_f32_e32 v201, 0xbfb8aa3b, v33
	v_mul_f32_e32 v202, 0xbfb8aa3b, v34
	v_mul_f32_e32 v203, 0xbfb8aa3b, v35
	v_mul_f32_e32 v204, 0xbfb8aa3b, v36
	v_mul_f32_e32 v205, 0xbfb8aa3b, v37
	v_mul_f32_e32 v206, 0xbfb8aa3b, v38
	v_mul_f32_e32 v207, 0xbfb8aa3b, v39
	v_exp_f32_e32 v200, v200
	v_exp_f32_e32 v201, v201
	v_exp_f32_e32 v202, v202
	v_exp_f32_e32 v203, v203
	v_exp_f32_e32 v204, v204
	v_exp_f32_e32 v205, v205
	v_exp_f32_e32 v206, v206
	v_exp_f32_e32 v207, v207
	v_add_f32_e32 v200, 1.0, v200
	v_add_f32_e32 v201, 1.0, v201
	v_add_f32_e32 v202, 1.0, v202
	v_add_f32_e32 v203, 1.0, v203
	v_add_f32_e32 v204, 1.0, v204
	v_add_f32_e32 v205, 1.0, v205
	v_add_f32_e32 v206, 1.0, v206
	v_add_f32_e32 v207, 1.0, v207
	v_rcp_f32_e32 v200, v200
	v_rcp_f32_e32 v201, v201
	v_rcp_f32_e32 v202, v202
	v_rcp_f32_e32 v203, v203
	v_rcp_f32_e32 v204, v204
	v_rcp_f32_e32 v205, v205
	v_rcp_f32_e32 v206, v206
	v_rcp_f32_e32 v207, v207
	v_lshlrev_b32_e32 v208, 16, v148
	v_and_b32_e32 v209, 0xffff0000, v148
	v_lshlrev_b32_e32 v210, 16, v149
	v_and_b32_e32 v211, 0xffff0000, v149
	v_lshlrev_b32_e32 v212, 16, v150
	v_and_b32_e32 v213, 0xffff0000, v150
	v_lshlrev_b32_e32 v214, 16, v151
	v_and_b32_e32 v215, 0xffff0000, v151
	v_fmac_f32_e32 v96, v200, v208
	v_fmac_f32_e32 v97, v201, v209
	v_fmac_f32_e32 v98, v202, v210
	v_fmac_f32_e32 v99, v203, v211
	v_fmac_f32_e32 v100, v204, v212
	v_fmac_f32_e32 v101, v205, v213
	v_fmac_f32_e32 v102, v206, v214
	v_fmac_f32_e32 v103, v207, v215
	v_mul_f32_e32 v200, 0xbfb8aa3b, v40
	v_mul_f32_e32 v201, 0xbfb8aa3b, v41
	v_mul_f32_e32 v202, 0xbfb8aa3b, v42
	v_mul_f32_e32 v203, 0xbfb8aa3b, v43
	v_mul_f32_e32 v204, 0xbfb8aa3b, v44
	v_mul_f32_e32 v205, 0xbfb8aa3b, v45
	v_mul_f32_e32 v206, 0xbfb8aa3b, v46
	v_mul_f32_e32 v207, 0xbfb8aa3b, v47
	v_exp_f32_e32 v200, v200
	v_exp_f32_e32 v201, v201
	v_exp_f32_e32 v202, v202
	v_exp_f32_e32 v203, v203
	v_exp_f32_e32 v204, v204
	v_exp_f32_e32 v205, v205
	v_exp_f32_e32 v206, v206
	v_exp_f32_e32 v207, v207
	v_add_f32_e32 v200, 1.0, v200
	v_add_f32_e32 v201, 1.0, v201
	v_add_f32_e32 v202, 1.0, v202
	v_add_f32_e32 v203, 1.0, v203
	v_add_f32_e32 v204, 1.0, v204
	v_add_f32_e32 v205, 1.0, v205
	v_add_f32_e32 v206, 1.0, v206
	v_add_f32_e32 v207, 1.0, v207
	v_rcp_f32_e32 v200, v200
	v_rcp_f32_e32 v201, v201
	v_rcp_f32_e32 v202, v202
	v_rcp_f32_e32 v203, v203
	v_rcp_f32_e32 v204, v204
	v_rcp_f32_e32 v205, v205
	v_rcp_f32_e32 v206, v206
	v_rcp_f32_e32 v207, v207
	v_lshlrev_b32_e32 v208, 16, v152
	v_and_b32_e32 v209, 0xffff0000, v152
	v_lshlrev_b32_e32 v210, 16, v153
	v_and_b32_e32 v211, 0xffff0000, v153
	v_lshlrev_b32_e32 v212, 16, v154
	v_and_b32_e32 v213, 0xffff0000, v154
	v_lshlrev_b32_e32 v214, 16, v155
	v_and_b32_e32 v215, 0xffff0000, v155
	v_fmac_f32_e32 v104, v200, v208
	v_fmac_f32_e32 v105, v201, v209
	v_fmac_f32_e32 v106, v202, v210
	v_fmac_f32_e32 v107, v203, v211
	v_fmac_f32_e32 v108, v204, v212
; __device__ __forceinline__ float sigmoidf_(float v) { return 1.f / (1.f + __expf(-v)); }
; __device__ void phase_merge4(CParams& p, int l, int tm, int tn, char* smem) {
;     ...
; #pragma unroll
;     for (int mi = 0; mi < 4; mi++)
; #pragma unroll
;       for (int ni = 0; ni < 4; ni++) {
;         unsigned p0 = pk[mi][ni][0], p1 = pk[mi][ni][1], m0 = mer[mi][ni][0], m1 = mer[mi][ni][1];
;         float r0 = __uint_as_float(m0 << 16) + sigmoidf_(acc[mi][ni][0]) * __uint_as_float(p0 << 16);
;         float r1 = __uint_as_float(m0 & 0xffff0000u) + sigmoidf_(acc[mi][ni][1]) * __uint_as_float(p0 & 0xffff0000u);
;         float r2 = __uint_as_float(m1 << 16) + sigmoidf_(acc[mi][ni][2]) * __uint_as_float(p1 << 16);
;         float r3 = __uint_as_float(m1 & 0xffff0000u) + sigmoidf_(acc[mi][ni][3]) * __uint_as_float(p1 & 0xffff0000u);
;         mer[mi][ni][0] = (unsigned)f2bf(r0) | ((unsigned)f2bf(r1) << 16);
;         mer[mi][ni][1] = (unsigned)f2bf(r2) | ((unsigned)f2bf(r3) << 16);
;       }
;   }
;   {
;     const int lane = tid & 63, wid = tid >> 6, wr = wid >> 1, wc = wid & 1;
; #pragma unroll
;     for (int mi = 0; mi < 4; mi++)
; #pragma unroll
;       for (int ni = 0; ni < 4; ni++)
; #pragma unroll
;         for (int j = 0; j < 4; j++) {
;           int rl = wr * 64 + mi * 16 + (lane >> 4) * 4 + j;
;           int cl = wc * 64 + ni * 16 + (lane & 15);
;           unsigned w = mer[mi][ni][j >> 1];
;           p.merged[(size_t)(row0 + rl) * 1024 + col0 + cl] = (bf16_t)((j & 1) ? (w >> 16) : (w & 0xffffu));
;         }
;   }
	v_fmac_f32_e32 v109, v205, v213
	v_fmac_f32_e32 v110, v206, v214
	v_fmac_f32_e32 v111, v207, v215
	v_mul_f32_e32 v200, 0xbfb8aa3b, v48
	v_mul_f32_e32 v201, 0xbfb8aa3b, v49
	v_mul_f32_e32 v202, 0xbfb8aa3b, v50
	v_mul_f32_e32 v203, 0xbfb8aa3b, v51
	v_mul_f32_e32 v204, 0xbfb8aa3b, v52
	v_mul_f32_e32 v205, 0xbfb8aa3b, v53
	v_mul_f32_e32 v206, 0xbfb8aa3b, v54
	v_mul_f32_e32 v207, 0xbfb8aa3b, v55
	v_exp_f32_e32 v200, v200
	v_exp_f32_e32 v201, v201
	v_exp_f32_e32 v202, v202
	v_exp_f32_e32 v203, v203
	v_exp_f32_e32 v204, v204
	v_exp_f32_e32 v205, v205
	v_exp_f32_e32 v206, v206
	v_exp_f32_e32 v207, v207
	v_add_f32_e32 v200, 1.0, v200
	v_add_f32_e32 v201, 1.0, v201
	v_add_f32_e32 v202, 1.0, v202
	v_add_f32_e32 v203, 1.0, v203
	v_add_f32_e32 v204, 1.0, v204
	v_add_f32_e32 v205, 1.0, v205
	v_add_f32_e32 v206, 1.0, v206
	v_add_f32_e32 v207, 1.0, v207
	v_rcp_f32_e32 v200, v200
	v_rcp_f32_e32 v201, v201
	v_rcp_f32_e32 v202, v202
	v_rcp_f32_e32 v203, v203
	v_rcp_f32_e32 v204, v204
	v_rcp_f32_e32 v205, v205
	v_rcp_f32_e32 v206, v206
	v_rcp_f32_e32 v207, v207
	v_lshlrev_b32_e32 v208, 16, v156
	v_and_b32_e32 v209, 0xffff0000, v156
	v_lshlrev_b32_e32 v210, 16, v157
	v_and_b32_e32 v211, 0xffff0000, v157
	v_lshlrev_b32_e32 v212, 16, v158
	v_and_b32_e32 v213, 0xffff0000, v158
	v_lshlrev_b32_e32 v214, 16, v159
	v_and_b32_e32 v215, 0xffff0000, v159
	v_fmac_f32_e32 v112, v200, v208
	v_fmac_f32_e32 v113, v201, v209
	v_fmac_f32_e32 v114, v202, v210
	v_fmac_f32_e32 v115, v203, v211
	v_fmac_f32_e32 v116, v204, v212
	v_fmac_f32_e32 v117, v205, v213
	v_fmac_f32_e32 v118, v206, v214
	v_fmac_f32_e32 v119, v207, v215
	v_mul_f32_e32 v200, 0xbfb8aa3b, v56
	v_mul_f32_e32 v201, 0xbfb8aa3b, v57
	v_mul_f32_e32 v202, 0xbfb8aa3b, v58
	v_mul_f32_e32 v203, 0xbfb8aa3b, v59
	v_mul_f32_e32 v204, 0xbfb8aa3b, v60
	v_mul_f32_e32 v205, 0xbfb8aa3b, v61
	v_mul_f32_e32 v206, 0xbfb8aa3b, v62
	v_mul_f32_e32 v207, 0xbfb8aa3b, v63
	v_exp_f32_e32 v200, v200
	v_exp_f32_e32 v201, v201
	v_exp_f32_e32 v202, v202
	v_exp_f32_e32 v203, v203
	v_exp_f32_e32 v204, v204
	v_exp_f32_e32 v205, v205
	v_exp_f32_e32 v206, v206
	v_exp_f32_e32 v207, v207
	v_add_f32_e32 v200, 1.0, v200
	v_add_f32_e32 v201, 1.0, v201
	v_add_f32_e32 v202, 1.0, v202
	v_add_f32_e32 v203, 1.0, v203
	v_add_f32_e32 v204, 1.0, v204
	v_add_f32_e32 v205, 1.0, v205
	v_add_f32_e32 v206, 1.0, v206
	v_add_f32_e32 v207, 1.0, v207
	v_rcp_f32_e32 v200, v200
	v_rcp_f32_e32 v201, v201
	v_rcp_f32_e32 v202, v202
	v_rcp_f32_e32 v203, v203
	v_rcp_f32_e32 v204, v204
	v_rcp_f32_e32 v205, v205
	v_rcp_f32_e32 v206, v206
	v_rcp_f32_e32 v207, v207
	v_lshlrev_b32_e32 v208, 16, v160
	v_and_b32_e32 v209, 0xffff0000, v160
	v_lshlrev_b32_e32 v210, 16, v161
	v_and_b32_e32 v211, 0xffff0000, v161
	v_lshlrev_b32_e32 v212, 16, v162
	v_and_b32_e32 v213, 0xffff0000, v162
	v_lshlrev_b32_e32 v214, 16, v163
	v_and_b32_e32 v215, 0xffff0000, v163
	v_fmac_f32_e32 v120, v200, v208
	v_fmac_f32_e32 v121, v201, v209
	v_fmac_f32_e32 v122, v202, v210
	v_fmac_f32_e32 v123, v203, v211
	v_fmac_f32_e32 v124, v204, v212
	v_fmac_f32_e32 v125, v205, v213
	v_fmac_f32_e32 v126, v206, v214
	v_fmac_f32_e32 v127, v207, v215
	s_and_b32 s63, s22, 3
	s_cmp_lg_u32 s63, 3
	s_cbranch_scc1 .Lmg4_nostore
	s_lshl_b32 s62, s23, 11
	s_lshl_b32 s92, s21, 1
	s_add_u32 s62, s62, s92
	s_add_u32 s58, s8, s62
	s_addc_u32 s59, s9, 0
	v_cvt_pk_bf16_f32 v200, v64, v65
	v_cvt_pk_bf16_f32 v201, v66, v67
	v_cvt_pk_bf16_f32 v202, v68, v69
	v_cvt_pk_bf16_f32 v203, v70, v71
	global_store_dwordx4 v144, v[200:203], s[58:59] offset:0
	v_cvt_pk_bf16_f32 v204, v72, v73
	v_cvt_pk_bf16_f32 v205, v74, v75
	v_cvt_pk_bf16_f32 v206, v76, v77
	v_cvt_pk_bf16_f32 v207, v78, v79
	global_store_dwordx4 v144, v[204:207], s[58:59] offset:16
	s_add_u32 s58, s58, 0x8000
	s_addc_u32 s59, s59, 0
	v_cvt_pk_bf16_f32 v208, v80, v81
	v_cvt_pk_bf16_f32 v209, v82, v83
	v_cvt_pk_bf16_f32 v210, v84, v85
	v_cvt_pk_bf16_f32 v211, v86, v87
	global_store_dwordx4 v144, v[208:211], s[58:59] offset:0
	v_cvt_pk_bf16_f32 v212, v88, v89
	v_cvt_pk_bf16_f32 v213, v90, v91
	v_cvt_pk_bf16_f32 v214, v92, v93
	v_cvt_pk_bf16_f32 v215, v94, v95
	global_store_dwordx4 v144, v[212:215], s[58:59] offset:16
	s_add_u32 s58, s58, 0x8000
	s_addc_u32 s59, s59, 0
	v_cvt_pk_bf16_f32 v216, v96, v97
	v_cvt_pk_bf16_f32 v217, v98, v99
	v_cvt_pk_bf16_f32 v218, v100, v101
	v_cvt_pk_bf16_f32 v219, v102, v103
	global_store_dwordx4 v144, v[216:219], s[58:59] offset:0
	v_cvt_pk_bf16_f32 v220, v104, v105
	v_cvt_pk_bf16_f32 v221, v106, v107
	v_cvt_pk_bf16_f32 v222, v108, v109
	v_cvt_pk_bf16_f32 v223, v110, v111
	global_store_dwordx4 v144, v[220:223], s[58:59] offset:16
	s_add_u32 s58, s58, 0x8000
	s_addc_u32 s59, s59, 0
	v_cvt_pk_bf16_f32 v228, v112, v113
	v_cvt_pk_bf16_f32 v229, v114, v115
	v_cvt_pk_bf16_f32 v230, v116, v117
	v_cvt_pk_bf16_f32 v231, v118, v119
	global_store_dwordx4 v144, v[228:231], s[58:59] offset:0
	v_cvt_pk_bf16_f32 v232, v120, v121
	v_cvt_pk_bf16_f32 v233, v122, v123
	v_cvt_pk_bf16_f32 v234, v124, v125
	v_cvt_pk_bf16_f32 v235, v126, v127
	global_store_dwordx4 v144, v[232:235], s[58:59] offset:16
	s_waitcnt vmcnt(0)

; __device__ __forceinline__ int otid() { int t = threadIdx.x; asm volatile("" : "+v"(t)); return t; }
; template <int NI> ...
;     ...
;   const int lane = tid & 63, wid = tid >> 6, wr = wid >> 1, wc = wid & 1;
;   const int lrow = tid >> 2, lch = (tid & 3) * 8;
;   const int l15 = lane & 15, lq = lane >> 4;
;   const bf16_t* pa = A + (size_t)lrow * lda + lch;
;   const bf16_t* pb = B + (size_t)lrow * ldb + lch;
;   const size_t a64 = (size_t)64 * lda, b64 = (size_t)64 * ldb;
;   u32x4 a0[2], a1[2], b0[NB], b1[NB];
;   const int nk = K >> 5;
;   const int klast = K - 32;
;   const int wofs = lrow * GROW + lch;
;   const int raofs = (wr * 64 + l15) * GROW + lq * 8;
;   const int rbofs = 128 * GROW + (wc * (16 * NI) + l15) * GROW + lq * 8;
;     ...
;   G_LOAD(a0, b0, 0);
;   G_LOAD(a1, b1, 32);
;   __syncthreads();
;   G_WRITE(a0, b0, 0);
;   __syncthreads();
; __device__ void phase_proj_res(CParams& p, int l, int tm, int tn, char* smem, const bf16_t* A, int K,
;                                const bf16_t* Bt, int gate_off, float gscale) {
;   const int tid = otid();
;   bf16_t* sA = (bf16_t*)smem;
;   bf16_t* sB = sA + 128 * LDSS;
;   int row0 = tm * 128, col0 = tn * 128;
;   f32x4 acc[4][4];
;   zero_acc<4>(acc);
;   gemm_mainloop<4>(A + (size_t)row0 * K, K, Bt + (size_t)col0 * K, K, K, sA, sB, acc, tid);
.LBB0_946:
	s_or_b64 exec, exec, s[22:23]
	s_mov_b64 s[42:43], s[34:35]
	s_waitcnt lgkmcnt(0)
	s_barrier
	s_lshl_b64 s[6:7], s[0:1], 21
	s_load_dwordx2 s[8:9], s[42:43], 0x118
	s_load_dwordx2 s[22:23], s[42:43], 0x1d8
	s_load_dwordx2 s[24:25], s[42:43], 0x160
	s_load_dwordx2 s[44:45], s[42:43], 0x148
	s_load_dwordx2 s[48:49], s[42:43], 0xf8
	s_waitcnt lgkmcnt(0)
	s_add_u32 s2, s8, s6
	s_addc_u32 s4, s9, s7
	v_readlane_b32 s6, v225, 63
	v_readlane_b32 s7, v224, 0
	s_add_u32 s50, s2, s6
	s_addc_u32 s51, s4, s7
	s_mov_b32 s2, 0
	s_mov_b64 exec, -1
	ds_read_b128 v[252:255], v145 offset:40960
	s_load_dwordx2 s[0:1], s[34:35], 0x1d8
	s_load_dwordx2 s[6:7], s[34:35], 0x118
	s_load_dwordx2 s[24:25], s[34:35], 0xf8
	s_load_dwordx2 s[28:29], s[34:35], 0x160
	v_readlane_b32 s2, v224, 26
	v_readlane_b32 s4, v225, 4
	v_readfirstlane_b32 s53, v147
	v_and_b32_e32 v166, 63, v147
	s_nop 3
	s_lshr_b32 s53, s53, 6
	s_lshl_b32 s32, s53, 12
	v_lshrrev_b32_e32 v167, 3, v166
	s_lshl_b32 s57, s53, 5
	v_add_u32_e32 v167, s57, v167
	v_and_b32_e32 v226, 7, v166
	v_lshrrev_b32_e32 v227, 4, v166
	s_mov_b32 s55, 0x800
	s_mov_b32 s56, 0x800
	v_xor_b32_e32 v248, v226, v227
	v_xor_b32_e32 v249, 0, v248
	v_lshlrev_b32_e32 v249, 4, v249
	v_add_u32_e32 v250, 0, v167
	v_mul_lo_u32 v236, v250, s55
	v_add_u32_e32 v236, v236, v249
	v_mul_lo_u32 v240, v250, s56
	v_add_u32_e32 v240, v240, v249
	v_xor_b32_e32 v249, 4, v248
	v_lshlrev_b32_e32 v249, 4, v249
	v_add_u32_e32 v250, 8, v167
	v_mul_lo_u32 v237, v250, s55
	v_add_u32_e32 v237, v237, v249
	v_mul_lo_u32 v241, v250, s56
	v_add_u32_e32 v241, v241, v249
	v_xor_b32_e32 v249, 0, v248
	v_lshlrev_b32_e32 v249, 4, v249
	v_add_u32_e32 v250, 16, v167
	v_mul_lo_u32 v238, v250, s55
	v_add_u32_e32 v238, v238, v249
	v_mul_lo_u32 v242, v250, s56
	v_add_u32_e32 v242, v242, v249
	v_xor_b32_e32 v249, 4, v248
	v_lshlrev_b32_e32 v249, 4, v249
	v_add_u32_e32 v250, 24, v167
	v_mul_lo_u32 v239, v250, s55
	v_add_u32_e32 v239, v239, v249
	v_mul_lo_u32 v243, v250, s56
	v_add_u32_e32 v243, v243, v249
	v_and_b32_e32 v167, 15, v166
	v_lshrrev_b32_e32 v227, 4, v166
	s_lshr_b32 s57, s53, 1
	s_and_b32 s58, s53, 1
	s_lshl_b32 s57, s57, 6
	s_lshl_b32 s58, s58, 6
	v_lshrrev_b32_e32 v226, 1, v167
	v_xor_b32_e32 v226, v227, v226
	v_lshlrev_b32_e32 v226, 4, v226
	v_add_u32_e32 v248, s57, v167
	v_lshl_add_u32 v248, v248, 7, v226
	v_xor_b32_e32 v249, 64, v248
	v_add_u32_e32 v250, s58, v167
	v_lshl_add_u32 v250, v250, 7, v226
	v_xor_b32_e32 v251, 64, v250
	v_lshl_add_u32 v132, v227, 2, s58
	v_lshlrev_b32_e32 v132, 2, v132
	v_add_u32_e32 v144, s57, v167
	v_lshl_add_u32 v144, v144, 12, v132
	s_mov_b32 s59, 0x0
	s_mov_b32 s62, 0x4000
	s_mov_b32 s63, 0x8000
	s_mov_b32 s92, 0xc000
	s_mov_b32 s93, 0x10000
	s_waitcnt lgkmcnt(0)
	s_mov_b32 s52, 0
	s_and_b32 s55, s4, 7
	s_lshl_b32 s55, s55, 4
	s_lshr_b32 s56, s4, 5
	s_add_u32 s55, s55, s56
	s_lshl_b32 s50, s55, 7
	s_lshr_b32 s56, s4, 3
	s_and_b32 s56, s56, 3
	s_lshl_b32 s56, s56, 1
	s_add_u32 s56, s56, s52
	s_lshl_b32 s51, s56, 7
	s_mul_i32 s55, s50, 0x800
	s_add_u32 s8, s0, s55
	s_addc_u32 s9, s1, 0
	s_mul_i32 s55, s2, 0x200000
	s_mul_i32 s56, s51, 0x800
	s_add_u32 s55, s55, s56
	s_add_u32 s12, s6, s55
	s_addc_u32 s13, s7, 0
	s_barrier
	s_add_u32 s54, s32, s59
	s_add_u32 m0, s54, 0x0
	s_nop 0
	global_load_lds_dwordx4 v236, s[8:9]
	s_add_u32 m0, s54, 0x400
	s_nop 0
	global_load_lds_dwordx4 v237, s[8:9]
	s_add_u32 m0, s54, 0x800
	s_nop 0
	global_load_lds_dwordx4 v238, s[8:9]
	s_add_u32 m0, s54, 0xc00
	s_nop 0
	global_load_lds_dwordx4 v239, s[8:9]
	s_add_u32 s8, s8, 128
	s_addc_u32 s9, s9, 0
	s_add_u32 s54, s32, s62
	s_add_u32 m0, s54, 0x0
	s_nop 0
	global_load_lds_dwordx4 v240, s[12:13]
	s_add_u32 m0, s54, 0x400
	s_nop 0
	global_load_lds_dwordx4 v241, s[12:13]
	s_add_u32 m0, s54, 0x800
	s_nop 0
	global_load_lds_dwordx4 v242, s[12:13]
	s_add_u32 m0, s54, 0xc00
	s_nop 0
	global_load_lds_dwordx4 v243, s[12:13]
	s_add_u32 s12, s12, 128
	s_addc_u32 s13, s13, 0
	s_add_u32 s54, s32, s63
	s_add_u32 m0, s54, 0x0
	s_nop 0
	global_load_lds_dwordx4 v236, s[8:9]
	s_add_u32 m0, s54, 0x400
	s_nop 0
	global_load_lds_dwordx4 v237, s[8:9]
	s_add_u32 m0, s54, 0x800
	s_nop 0
	global_load_lds_dwordx4 v238, s[8:9]
	s_add_u32 m0, s54, 0xc00
	s_nop 0
	global_load_lds_dwordx4 v239, s[8:9]
	s_add_u32 s8, s8, 128
	s_addc_u32 s9, s9, 0
	s_add_u32 s54, s32, s92
	s_add_u32 m0, s54, 0x0
	s_nop 0
	global_load_lds_dwordx4 v240, s[12:13]
	s_add_u32 m0, s54, 0x400
	s_nop 0
	global_load_lds_dwordx4 v241, s[12:13]
	s_add_u32 m0, s54, 0x800
	s_nop 0
	global_load_lds_dwordx4 v242, s[12:13]
	s_add_u32 m0, s54, 0xc00
	s_nop 0
	global_load_lds_dwordx4 v243, s[12:13]
	s_add_u32 s12, s12, 128
	s_addc_u32 s13, s13, 0
	v_mov_b32_e32 v0, 0
	v_mov_b32_e32 v1, 0
	v_mov_b32_e32 v2, 0
	v_mov_b32_e32 v3, 0
	v_mov_b32_e32 v4, 0
	v_mov_b32_e32 v5, 0
	v_mov_b32_e32 v6, 0
	v_mov_b32_e32 v7, 0
	v_mov_b32_e32 v8, 0
	v_mov_b32_e32 v9, 0
	v_mov_b32_e32 v10, 0
	v_mov_b32_e32 v11, 0
	v_mov_b32_e32 v12, 0
	v_mov_b32_e32 v13, 0
	v_mov_b32_e32 v14, 0
	v_mov_b32_e32 v15, 0
	v_mov_b32_e32 v16, 0
	v_mov_b32_e32 v17, 0
	v_mov_b32_e32 v18, 0
	v_mov_b32_e32 v19, 0
	v_mov_b32_e32 v20, 0
	v_mov_b32_e32 v21, 0
	v_mov_b32_e32 v22, 0
	v_mov_b32_e32 v23, 0
	v_mov_b32_e32 v24, 0
	v_mov_b32_e32 v25, 0
	v_mov_b32_e32 v26, 0
	v_mov_b32_e32 v27, 0
	v_mov_b32_e32 v28, 0
	v_mov_b32_e32 v29, 0
	v_mov_b32_e32 v30, 0
	v_mov_b32_e32 v31, 0
	v_mov_b32_e32 v32, 0
	v_mov_b32_e32 v33, 0
	v_mov_b32_e32 v34, 0
	v_mov_b32_e32 v35, 0
	v_mov_b32_e32 v36, 0
	v_mov_b32_e32 v37, 0
	v_mov_b32_e32 v38, 0
	v_mov_b32_e32 v39, 0
	v_mov_b32_e32 v40, 0
	v_mov_b32_e32 v41, 0
	v_mov_b32_e32 v42, 0
	v_mov_b32_e32 v43, 0
	v_mov_b32_e32 v44, 0
	v_mov_b32_e32 v45, 0
	v_mov_b32_e32 v46, 0
	v_mov_b32_e32 v47, 0
	v_mov_b32_e32 v48, 0
	v_mov_b32_e32 v49, 0
	v_mov_b32_e32 v50, 0
	v_mov_b32_e32 v51, 0
	v_mov_b32_e32 v52, 0
	v_mov_b32_e32 v53, 0
	v_mov_b32_e32 v54, 0
	v_mov_b32_e32 v55, 0
	v_mov_b32_e32 v56, 0
	v_mov_b32_e32 v57, 0
	v_mov_b32_e32 v58, 0
	v_mov_b32_e32 v59, 0
	v_mov_b32_e32 v60, 0
	v_mov_b32_e32 v61, 0
	v_mov_b32_e32 v62, 0
	v_mov_b32_e32 v63, 0
	s_waitcnt vmcnt(8)
	s_barrier
	v_add_u32_e32 v128, s59, v248
	v_add_u32_e32 v130, s62, v250
	ds_read_b128 v[168:171], v128 offset:0
	ds_read_b128 v[184:187], v130 offset:0
	ds_read_b128 v[172:175], v128 offset:2048
	ds_read_b128 v[188:191], v130 offset:2048
	ds_read_b128 v[176:179], v128 offset:4096
	ds_read_b128 v[192:195], v130 offset:4096
	ds_read_b128 v[180:183], v128 offset:6144
	ds_read_b128 v[196:199], v130 offset:6144
; template <int NI> ...
;     ...
;   for (int kt = 0; kt < nk; kt += 2) {
;     G_LOAD(a0, b0, min((kt + 2) * 32, klast));
;     G_COMPUTE(0);
;     G_WRITE(a1, b1, 1);
;     __syncthreads();
;     G_LOAD(a1, b1, min((kt + 3) * 32, klast));
;     G_COMPUTE(1);
;     G_WRITE(a0, b0, 0);
;     __syncthreads();
;   }
; __device__ void phase_proj_res(CParams& p, int l, int tm, int tn, char* smem, const bf16_t* A, int K,
;                                const bf16_t* Bt, int gate_off, float gscale) {
;     ...
;   const float* md = p.mod + ((size_t)l * 3 + modvec_of_tok(row0)) * 6144 + gate_off;
;   EPI_LOOP({
;     float* xp = xrow(p, row0 + rl) + col0 + cl;
.Loutp_tile:
	s_mul_i32 s55, s2, 3
	s_lshr_b32 s56, s50, 13
	s_add_u32 s55, s55, s56
	s_mul_i32 s55, s55, 6144
	s_add_u32 s55, s55, s51
	s_add_u32 s55, s55, 2048
	s_lshl_b32 s55, s55, 2
	s_add_u32 s44, s28, s55
	s_addc_u32 s45, s29, 0
	s_lshl_b32 s55, s50, 12
	s_lshl_b32 s56, s51, 2
	s_add_u32 s55, s55, s56
	s_add_u32 s26, s24, s55
	s_addc_u32 s27, s25, 0
	s_add_u32 s58, s52, 1
	s_min_u32 s58, s58, 1
	s_and_b32 s55, s4, 7
	s_lshl_b32 s55, s55, 4
	s_lshr_b32 s56, s4, 5
	s_add_u32 s55, s55, s56
	s_lshl_b32 s50, s55, 7
	s_lshr_b32 s56, s4, 3
	s_and_b32 s56, s56, 3
	s_lshl_b32 s56, s56, 1
	s_add_u32 s56, s56, s58
	s_lshl_b32 s51, s56, 7
	s_mul_i32 s55, s50, 0x800
	s_add_u32 s18, s0, s55
	s_addc_u32 s19, s1, 0
	s_mul_i32 s55, s2, 0x200000
	s_mul_i32 s56, s51, 0x800
	s_add_u32 s55, s55, s56
	s_add_u32 s22, s6, s55
	s_addc_u32 s23, s7, 0
	s_mov_b32 s53, 0
.Loutp_pair:
	s_waitcnt lgkmcnt(0)
	s_cmp_eq_u32 s53, 14
	s_cselect_b64 s[8:9], s[18:19], s[8:9]
	s_add_u32 s54, s32, s93
	s_add_u32 m0, s54, 0x0
	s_nop 0
	global_load_lds_dwordx4 v236, s[8:9]
	s_add_u32 m0, s54, 0x400
	s_nop 0
	global_load_lds_dwordx4 v237, s[8:9]
	s_add_u32 m0, s54, 0x800
	s_nop 0
	global_load_lds_dwordx4 v238, s[8:9]
	s_add_u32 m0, s54, 0xc00
	s_nop 0
	global_load_lds_dwordx4 v239, s[8:9]
	s_add_u32 s8, s8, 128
	s_addc_u32 s9, s9, 0
	v_add_u32_e32 v129, s59, v249
	v_add_u32_e32 v131, s62, v251
	v_mfma_f32_16x16x32_bf16 v[0:3], v[184:187], v[168:171], v[0:3]
	ds_read_b128 v[200:203], v129 offset:0
	v_mfma_f32_16x16x32_bf16 v[4:7], v[188:191], v[168:171], v[4:7]
	ds_read_b128 v[216:219], v131 offset:0
	v_mfma_f32_16x16x32_bf16 v[8:11], v[192:195], v[168:171], v[8:11]
	ds_read_b128 v[204:207], v129 offset:2048
	v_mfma_f32_16x16x32_bf16 v[12:15], v[196:199], v[168:171], v[12:15]
	ds_read_b128 v[220:223], v131 offset:2048
	v_mfma_f32_16x16x32_bf16 v[16:19], v[184:187], v[172:175], v[16:19]
	ds_read_b128 v[208:211], v129 offset:4096
	v_mfma_f32_16x16x32_bf16 v[20:23], v[188:191], v[172:175], v[20:23]
	ds_read_b128 v[228:231], v131 offset:4096
	v_mfma_f32_16x16x32_bf16 v[24:27], v[192:195], v[172:175], v[24:27]
	ds_read_b128 v[212:215], v129 offset:6144
	v_mfma_f32_16x16x32_bf16 v[28:31], v[196:199], v[172:175], v[28:31]
	ds_read_b128 v[232:235], v131 offset:6144
	v_mfma_f32_16x16x32_bf16 v[32:35], v[184:187], v[176:179], v[32:35]
	v_mfma_f32_16x16x32_bf16 v[36:39], v[188:191], v[176:179], v[36:39]
	v_mfma_f32_16x16x32_bf16 v[40:43], v[192:195], v[176:179], v[40:43]
	v_mfma_f32_16x16x32_bf16 v[44:47], v[196:199], v[176:179], v[44:47]
	v_mfma_f32_16x16x32_bf16 v[48:51], v[184:187], v[180:183], v[48:51]
	v_mfma_f32_16x16x32_bf16 v[52:55], v[188:191], v[180:183], v[52:55]
	v_mfma_f32_16x16x32_bf16 v[56:59], v[192:195], v[180:183], v[56:59]
	v_mfma_f32_16x16x32_bf16 v[60:63], v[196:199], v[180:183], v[60:63]
	s_waitcnt vmcnt(4) lgkmcnt(0)
	s_barrier
	s_cmp_eq_u32 s53, 14
	s_cselect_b64 s[12:13], s[22:23], s[12:13]
	s_add_u32 s54, s32, s59
	s_add_u32 m0, s54, 0x0
	s_nop 0
	global_load_lds_dwordx4 v240, s[12:13]
	s_add_u32 m0, s54, 0x400
	s_nop 0
	global_load_lds_dwordx4 v241, s[12:13]
	s_add_u32 m0, s54, 0x800
	s_nop 0
	global_load_lds_dwordx4 v242, s[12:13]
	s_add_u32 m0, s54, 0xc00
	s_nop 0
	global_load_lds_dwordx4 v243, s[12:13]
	s_add_u32 s12, s12, 128
	s_addc_u32 s13, s13, 0
	v_add_u32_e32 v128, s63, v248
	v_add_u32_e32 v130, s92, v250
	v_mfma_f32_16x16x32_bf16 v[0:3], v[216:219], v[200:203], v[0:3]
	ds_read_b128 v[168:171], v128 offset:0
	v_mfma_f32_16x16x32_bf16 v[4:7], v[220:223], v[200:203], v[4:7]
	ds_read_b128 v[184:187], v130 offset:0
	v_mfma_f32_16x16x32_bf16 v[8:11], v[228:231], v[200:203], v[8:11]
	ds_read_b128 v[172:175], v128 offset:2048
	v_mfma_f32_16x16x32_bf16 v[12:15], v[232:235], v[200:203], v[12:15]
	ds_read_b128 v[188:191], v130 offset:2048
	v_mfma_f32_16x16x32_bf16 v[16:19], v[216:219], v[204:207], v[16:19]
	ds_read_b128 v[176:179], v128 offset:4096
	v_mfma_f32_16x16x32_bf16 v[20:23], v[220:223], v[204:207], v[20:23]
	ds_read_b128 v[192:195], v130 offset:4096
	v_mfma_f32_16x16x32_bf16 v[24:27], v[228:231], v[204:207], v[24:27]
	ds_read_b128 v[180:183], v128 offset:6144
	v_mfma_f32_16x16x32_bf16 v[28:31], v[232:235], v[204:207], v[28:31]
	ds_read_b128 v[196:199], v130 offset:6144
	v_mfma_f32_16x16x32_bf16 v[32:35], v[216:219], v[208:211], v[32:35]
	v_mfma_f32_16x16x32_bf16 v[36:39], v[220:223], v[208:211], v[36:39]
	v_mfma_f32_16x16x32_bf16 v[40:43], v[228:231], v[208:211], v[40:43]
	v_mfma_f32_16x16x32_bf16 v[44:47], v[232:235], v[208:211], v[44:47]
	v_mfma_f32_16x16x32_bf16 v[48:51], v[216:219], v[212:215], v[48:51]
	v_mfma_f32_16x16x32_bf16 v[52:55], v[220:223], v[212:215], v[52:55]
	v_mfma_f32_16x16x32_bf16 v[56:59], v[228:231], v[212:215], v[56:59]
	v_mfma_f32_16x16x32_bf16 v[60:63], v[232:235], v[212:215], v[60:63]
	s_mov_b32 s55, s59
	s_mov_b32 s56, s62
	s_mov_b32 s59, s63
	s_mov_b32 s62, s92
	s_mov_b32 s63, s93
	s_mov_b32 s92, s55
	s_mov_b32 s93, s56
	s_add_u32 s53, s53, 1
	s_cmp_lt_u32 s53, 16
	s_cbranch_scc1 .Loutp_pair
; __device__ void phase_proj_res(CParams& p, int l, int tm, int tn, char* smem, const bf16_t* A, int K,
;                                const bf16_t* Bt, int gate_off, float gscale) {
;     ...
;   const float* md = p.mod + ((size_t)l * 3 + modvec_of_tok(row0)) * 6144 + gate_off;
;   EPI_LOOP({
;     float* xp = xrow(p, row0 + rl) + col0 + cl;
;     *xp = *xp + gscale * md[col0 + cl] * acc[mi][ni][j];
;   })
	s_nop 15
	s_nop 7
	global_load_dwordx4 v[200:203], v132, s[44:45] offset:0
	global_load_dwordx4 v[204:207], v132, s[44:45] offset:64
	global_load_dwordx4 v[208:211], v132, s[44:45] offset:128
	global_load_dwordx4 v[212:215], v132, s[44:45] offset:192
	s_mov_b64 s[44:45], s[26:27]
	global_load_dwordx4 v[64:67], v144, s[44:45] offset:0
	global_load_dwordx4 v[68:71], v144, s[44:45] offset:64
	global_load_dwordx4 v[72:75], v144, s[44:45] offset:128
	global_load_dwordx4 v[76:79], v144, s[44:45] offset:192
	s_add_u32 s44, s44, 0x10000
	s_addc_u32 s45, s45, 0
	global_load_dwordx4 v[80:83], v144, s[44:45] offset:0
	global_load_dwordx4 v[84:87], v144, s[44:45] offset:64
	global_load_dwordx4 v[88:91], v144, s[44:45] offset:128
	global_load_dwordx4 v[92:95], v144, s[44:45] offset:192
	s_add_u32 s44, s44, 0x10000
	s_addc_u32 s45, s45, 0
	global_load_dwordx4 v[96:99], v144, s[44:45] offset:0
	global_load_dwordx4 v[100:103], v144, s[44:45] offset:64
	global_load_dwordx4 v[104:107], v144, s[44:45] offset:128
	global_load_dwordx4 v[108:111], v144, s[44:45] offset:192
	s_add_u32 s44, s44, 0x10000
	s_addc_u32 s45, s45, 0
	global_load_dwordx4 v[112:115], v144, s[44:45] offset:0
	global_load_dwordx4 v[116:119], v144, s[44:45] offset:64
	global_load_dwordx4 v[120:123], v144, s[44:45] offset:128
	global_load_dwordx4 v[124:127], v144, s[44:45] offset:192
	s_waitcnt vmcnt(12)
	v_fmac_f32_e32 v64, v200, v0
	v_fmac_f32_e32 v65, v201, v1
	v_fmac_f32_e32 v66, v202, v2
	v_fmac_f32_e32 v67, v203, v3
	v_fmac_f32_e32 v68, v204, v4
	v_fmac_f32_e32 v69, v205, v5
	v_fmac_f32_e32 v70, v206, v6
	v_fmac_f32_e32 v71, v207, v7
	v_fmac_f32_e32 v72, v208, v8
	v_fmac_f32_e32 v73, v209, v9
	v_fmac_f32_e32 v74, v210, v10
	v_fmac_f32_e32 v75, v211, v11
	v_fmac_f32_e32 v76, v212, v12
	v_fmac_f32_e32 v77, v213, v13
	v_fmac_f32_e32 v78, v214, v14
	v_fmac_f32_e32 v79, v215, v15
	s_waitcnt vmcnt(8)
	v_fmac_f32_e32 v80, v200, v16
	v_fmac_f32_e32 v81, v201, v17
	v_fmac_f32_e32 v82, v202, v18
	v_fmac_f32_e32 v83, v203, v19
	v_fmac_f32_e32 v84, v204, v20
	v_fmac_f32_e32 v85, v205, v21
	v_fmac_f32_e32 v86, v206, v22
	v_fmac_f32_e32 v87, v207, v23
	v_fmac_f32_e32 v88, v208, v24
	v_fmac_f32_e32 v89, v209, v25
	v_fmac_f32_e32 v90, v210, v26
	v_fmac_f32_e32 v91, v211, v27
	v_fmac_f32_e32 v92, v212, v28
	v_fmac_f32_e32 v93, v213, v29
	v_fmac_f32_e32 v94, v214, v30
	v_fmac_f32_e32 v95, v215, v31
	s_waitcnt vmcnt(4)
	v_fmac_f32_e32 v96, v200, v32
	v_fmac_f32_e32 v97, v201, v33
	v_fmac_f32_e32 v98, v202, v34
	v_fmac_f32_e32 v99, v203, v35
	v_fmac_f32_e32 v100, v204, v36
	v_fmac_f32_e32 v101, v205, v37
	v_fmac_f32_e32 v102, v206, v38
	v_fmac_f32_e32 v103, v207, v39
	v_fmac_f32_e32 v104, v208, v40
	v_fmac_f32_e32 v105, v209, v41
	v_fmac_f32_e32 v106, v210, v42
	v_fmac_f32_e32 v107, v211, v43
	v_fmac_f32_e32 v108, v212, v44
	v_fmac_f32_e32 v109, v213, v45
	v_fmac_f32_e32 v110, v214, v46
	v_fmac_f32_e32 v111, v215, v47
	s_waitcnt vmcnt(0)
	v_fmac_f32_e32 v112, v200, v48
	v_fmac_f32_e32 v113, v201, v49
	v_fmac_f32_e32 v114, v202, v50
	v_fmac_f32_e32 v115, v203, v51
	v_fmac_f32_e32 v116, v204, v52
	v_fmac_f32_e32 v117, v205, v53
	v_fmac_f32_e32 v118, v206, v54
	v_fmac_f32_e32 v119, v207, v55
	v_fmac_f32_e32 v120, v208, v56
	v_fmac_f32_e32 v121, v209, v57
	v_fmac_f32_e32 v122, v210, v58
	v_fmac_f32_e32 v123, v211, v59
	v_fmac_f32_e32 v124, v212, v60
	v_fmac_f32_e32 v125, v213, v61
	v_fmac_f32_e32 v126, v214, v62
	v_fmac_f32_e32 v127, v215, v63
	global_store_dwordx4 v144, v[64:67], s[26:27] offset:0
	global_store_dwordx4 v144, v[68:71], s[26:27] offset:64
	global_store_dwordx4 v144, v[72:75], s[26:27] offset:128
	global_store_dwordx4 v144, v[76:79], s[26:27] offset:192
	s_add_u32 s26, s26, 0x10000
	s_addc_u32 s27, s27, 0
	global_store_dwordx4 v144, v[80:83], s[26:27] offset:0
	global_store_dwordx4 v144, v[84:87], s[26:27] offset:64
	global_store_dwordx4 v144, v[88:91], s[26:27] offset:128
	global_store_dwordx4 v144, v[92:95], s[26:27] offset:192
	s_add_u32 s26, s26, 0x10000
	s_addc_u32 s27, s27, 0
	global_store_dwordx4 v144, v[96:99], s[26:27] offset:0
	global_store_dwordx4 v144, v[100:103], s[26:27] offset:64
	global_store_dwordx4 v144, v[104:107], s[26:27] offset:128
	global_store_dwordx4 v144, v[108:111], s[26:27] offset:192
	s_add_u32 s26, s26, 0x10000
	s_addc_u32 s27, s27, 0
	global_store_dwordx4 v144, v[112:115], s[26:27] offset:0
	global_store_dwordx4 v144, v[116:119], s[26:27] offset:64
	global_store_dwordx4 v144, v[120:123], s[26:27] offset:128
	global_store_dwordx4 v144, v[124:127], s[26:27] offset:192
	v_mov_b32_e32 v0, 0
	v_mov_b32_e32 v1, 0
	v_mov_b32_e32 v2, 0
	v_mov_b32_e32 v3, 0
	v_mov_b32_e32 v4, 0
	v_mov_b32_e32 v5, 0
	v_mov_b32_e32 v6, 0
	v_mov_b32_e32 v7, 0
	v_mov_b32_e32 v8, 0
	v_mov_b32_e32 v9, 0
	v_mov_b32_e32 v10, 0
	v_mov_b32_e32 v11, 0
	v_mov_b32_e32 v12, 0
	v_mov_b32_e32 v13, 0
	v_mov_b32_e32 v14, 0
	v_mov_b32_e32 v15, 0
	v_mov_b32_e32 v16, 0
	v_mov_b32_e32 v17, 0
	v_mov_b32_e32 v18, 0
	v_mov_b32_e32 v19, 0
	v_mov_b32_e32 v20, 0
	v_mov_b32_e32 v21, 0
	v_mov_b32_e32 v22, 0
	v_mov_b32_e32 v23, 0
	v_mov_b32_e32 v24, 0
	v_mov_b32_e32 v25, 0
	v_mov_b32_e32 v26, 0
	v_mov_b32_e32 v27, 0
	v_mov_b32_e32 v28, 0
	v_mov_b32_e32 v29, 0
	v_mov_b32_e32 v30, 0
	v_mov_b32_e32 v31, 0
	v_mov_b32_e32 v32, 0
	v_mov_b32_e32 v33, 0
	v_mov_b32_e32 v34, 0
	v_mov_b32_e32 v35, 0
	v_mov_b32_e32 v36, 0
	v_mov_b32_e32 v37, 0
	v_mov_b32_e32 v38, 0
	v_mov_b32_e32 v39, 0
	v_mov_b32_e32 v40, 0
	v_mov_b32_e32 v41, 0
	v_mov_b32_e32 v42, 0
	v_mov_b32_e32 v43, 0
	v_mov_b32_e32 v44, 0
	v_mov_b32_e32 v45, 0
	v_mov_b32_e32 v46, 0
	v_mov_b32_e32 v47, 0
	v_mov_b32_e32 v48, 0
	v_mov_b32_e32 v49, 0
	v_mov_b32_e32 v50, 0
	v_mov_b32_e32 v51, 0
	v_mov_b32_e32 v52, 0
	v_mov_b32_e32 v53, 0
	v_mov_b32_e32 v54, 0
	v_mov_b32_e32 v55, 0
	v_mov_b32_e32 v56, 0
	v_mov_b32_e32 v57, 0
	v_mov_b32_e32 v58, 0
	v_mov_b32_e32 v59, 0
	v_mov_b32_e32 v60, 0
	v_mov_b32_e32 v61, 0
	v_mov_b32_e32 v62, 0
	v_mov_b32_e32 v63, 0
	s_waitcnt vmcnt(0)
	s_add_u32 s52, s52, 1
	s_cmp_lt_u32 s52, 2
	s_cbranch_scc1 .Loutp_tile
	s_waitcnt vmcnt(0) lgkmcnt(0)
	s_barrier
	ds_write_b128 v145, v[252:255] offset:40960
	s_waitcnt lgkmcnt(0)
	s_barrier
	s_mov_b64 s[52:53], 0

; __device__ __forceinline__ int otid() { int t = threadIdx.x; asm volatile("" : "+v"(t)); return t; }
; template <int NI> ...
;     ...
;   const int lane = tid & 63, wid = tid >> 6, wr = wid >> 1, wc = wid & 1;
;   const int lrow = tid >> 2, lch = (tid & 3) * 8;
;   const int l15 = lane & 15, lq = lane >> 4;
;   const bf16_t* pa = A + (size_t)lrow * lda + lch;
;   const bf16_t* pb = B + (size_t)lrow * ldb + lch;
;   const size_t a64 = (size_t)64 * lda, b64 = (size_t)64 * ldb;
;   u32x4 a0[2], a1[2], b0[NB], b1[NB];
;   const int nk = K >> 5;
;   const int klast = K - 32;
;   const int wofs = lrow * GROW + lch;
;   const int raofs = (wr * 64 + l15) * GROW + lq * 8;
;   const int rbofs = 128 * GROW + (wc * (16 * NI) + l15) * GROW + lq * 8;
;     ...
;   G_LOAD(a0, b0, 0);
;   G_LOAD(a1, b1, 32);
;   __syncthreads();
;   G_WRITE(a0, b0, 0);
;   __syncthreads();
; __device__ void phase_mlp1_big(CParams& p, int l, int tm, int tn, char* smem) {
;   const int tid = otid();
;   int row0 = tm * 128, col0 = tn * 256;
;   f32x4 acc[4][8];
;   zero_acc<8>(acc);
;   gemm_mainloop8(p.hbuf + (size_t)row0 * DM, DM, p.W1T + ((size_t)l * DFF + col0) * DM, DM, DM, (bf16_t*)smem, acc, tid);
;   const int lane = tid & 63, wid = tid >> 6, wr = wid >> 1, wc = wid & 1;
.LBB0_1064:
	s_or_b64 exec, exec, s[22:23]
	s_mov_b64 s[22:23], s[34:35]
	s_waitcnt lgkmcnt(0)
	s_barrier
	s_load_dwordx2 s[6:7], s[22:23], 0x120
	s_lshl_b64 s[18:19], s[0:1], 23
	s_load_dwordx2 s[24:25], s[22:23], 0x150
	s_load_dwordx2 s[8:9], s[22:23], 0x1e0
	v_readlane_b32 s16, v224, 4
	v_readlane_b32 s17, v224, 5
	s_waitcnt lgkmcnt(0)
	s_add_u32 s2, s6, s18
	s_addc_u32 s4, s7, s19
	s_add_u32 s42, s2, s16
	s_addc_u32 s43, s4, s17
	v_readlane_b32 s0, v224, 13
	v_readlane_b32 s1, v224, 14
	s_add_u32 s44, s8, s0
	s_addc_u32 s45, s9, s1
	s_add_u32 s2, s6, s16
	s_addc_u32 s4, s7, s17
	s_add_u32 s48, s2, s18
	s_addc_u32 s49, s4, s19
	s_mov_b64 exec, -1
	ds_read_b128 v[252:255], v145 offset:40960
	s_load_dwordx2 s[0:1], s[34:35], 0x150
	s_load_dwordx2 s[6:7], s[34:35], 0x120
	s_load_dwordx2 s[28:29], s[34:35], 0x1e0
	v_readlane_b32 s2, v224, 26
	v_readlane_b32 s4, v225, 4
	v_readfirstlane_b32 s45, v147
	v_and_b32_e32 v166, 63, v147
	s_nop 3
	s_lshr_b32 s45, s45, 6
	s_lshl_b32 s8, s45, 12
	v_lshrrev_b32_e32 v167, 3, v166
	s_lshl_b32 s55, s45, 5
	v_add_u32_e32 v167, s55, v167
	v_and_b32_e32 v226, 7, v166
	v_lshrrev_b32_e32 v227, 4, v166
	s_mov_b32 s51, 0x800
	s_mov_b32 s54, 0x800
	v_xor_b32_e32 v248, v226, v227
	v_xor_b32_e32 v249, 0, v248
	v_lshlrev_b32_e32 v249, 4, v249
	v_add_u32_e32 v250, 0, v167
	v_mul_lo_u32 v236, v250, s51
	v_add_u32_e32 v236, v236, v249
	v_xor_b32_e32 v249, 4, v248
	v_lshlrev_b32_e32 v249, 4, v249
	v_add_u32_e32 v250, 8, v167
	v_mul_lo_u32 v237, v250, s51
	v_add_u32_e32 v237, v237, v249
	v_xor_b32_e32 v249, 0, v248
	v_lshlrev_b32_e32 v249, 4, v249
	v_add_u32_e32 v250, 16, v167
	v_mul_lo_u32 v238, v250, s51
	v_add_u32_e32 v238, v238, v249
	v_xor_b32_e32 v249, 4, v248
	v_lshlrev_b32_e32 v249, 4, v249
	v_add_u32_e32 v250, 24, v167
	v_mul_lo_u32 v239, v250, s51
	v_add_u32_e32 v239, v239, v249
	s_and_b32 s56, s45, 1
	s_lshl_b32 s56, s56, 2
	v_and_b32_e32 v248, 1, v227
	v_or_b32_e32 v248, s56, v248
	v_xor_b32_e32 v248, v226, v248
	v_xor_b32_e32 v249, 0, v248
	v_lshlrev_b32_e32 v249, 4, v249
	v_add_u32_e32 v250, 0, v167
	v_mul_lo_u32 v240, v250, s54
	v_add_u32_e32 v240, v240, v249
	v_xor_b32_e32 v249, 0, v248
	v_lshlrev_b32_e32 v249, 4, v249
	v_add_u32_e32 v250, 8, v167
	v_mul_lo_u32 v241, v250, s54
	v_add_u32_e32 v241, v241, v249
	v_xor_b32_e32 v249, 2, v248
	v_lshlrev_b32_e32 v249, 4, v249
	v_add_u32_e32 v250, 16, v167
	v_mul_lo_u32 v242, v250, s54
	v_add_u32_e32 v242, v242, v249
	v_xor_b32_e32 v249, 2, v248
	v_lshlrev_b32_e32 v249, 4, v249
	v_add_u32_e32 v250, 24, v167
	v_mul_lo_u32 v243, v250, s54
	v_add_u32_e32 v243, v243, v249
	v_and_b32_e32 v167, 15, v166
	v_lshrrev_b32_e32 v227, 4, v166
	s_lshr_b32 s55, s45, 1
	s_and_b32 s56, s45, 1
	s_lshl_b32 s55, s55, 6
	s_lshl_b32 s56, s56, 6
	v_lshrrev_b32_e32 v226, 1, v167
	v_xor_b32_e32 v226, v227, v226
	v_lshlrev_b32_e32 v226, 4, v226
	v_add_u32_e32 v248, s55, v167
	v_lshl_add_u32 v248, v248, 7, v226
	v_xor_b32_e32 v249, 64, v248
	v_lshrrev_b32_e32 v226, 2, v167
	v_lshrrev_b32_e32 v250, 1, v167
	v_and_b32_e32 v250, 1, v250
	v_lshl_or_b32 v250, v226, 1, v250
	v_xor_b32_e32 v250, v227, v250
	v_lshlrev_b32_e32 v250, 4, v250
	v_and_b32_e32 v251, 3, v167
	v_lshl_add_u32 v251, v226, 4, v251
	v_add_u32_e32 v251, s56, v251
	v_lshl_add_u32 v250, v251, 7, v250
	v_xor_b32_e32 v251, 64, v250
	v_lshl_add_u32 v132, v227, 4, s56
	v_lshlrev_b32_e32 v132, 1, v132
	v_add_u32_e32 v144, s55, v167
	s_mov_b32 s51, 0x2000
	v_mul_lo_u32 v144, v144, s51
	v_add_u32_e32 v144, v144, v132
	s_mov_b32 s57, 0x0
	s_mov_b32 s58, 0x4000
	s_mov_b32 s59, 0x8000
	s_mov_b32 s62, 0xc000
	s_mov_b32 s63, 0x10000
	s_waitcnt lgkmcnt(0)
	s_mov_b32 s44, 0
	s_lshr_b32 s51, s44, 1
	s_lshl_b32 s51, s51, 3
	s_and_b32 s54, s4, 7
	s_add_u32 s51, s51, s54
	s_lshr_b32 s54, s51, 1
	s_lshl_b32 s54, s54, 3
	s_lshr_b32 s55, s4, 6
	s_add_u32 s54, s54, s55
	s_lshl_b32 s10, s54, 7
	s_and_b32 s51, s51, 1
	s_lshl_b32 s51, s51, 3
	s_lshr_b32 s55, s4, 3
	s_and_b32 s55, s55, 7
	s_add_u32 s51, s51, s55
	s_lshl_b32 s51, s51, 1
	s_and_b32 s55, s44, 1
	s_add_u32 s51, s51, s55
	s_lshl_b32 s32, s51, 7
	s_mul_i32 s51, s10, 0x800
	s_add_u32 s12, s0, s51
	s_addc_u32 s13, s1, 0
	s_mul_i32 s51, s2, 0x800000
	s_mul_i32 s54, s32, 0x800
	s_add_u32 s51, s51, s54
	s_add_u32 s16, s6, s51
	s_addc_u32 s17, s7, 0
	s_barrier
; __device__ __forceinline__ int otid() { int t = threadIdx.x; asm volatile("" : "+v"(t)); return t; }
; template <int NI> ...
;     ...
;   G_LOAD(a0, b0, 0);
;   G_LOAD(a1, b1, 32);
;   __syncthreads();
;   G_WRITE(a0, b0, 0);
;   __syncthreads();
;   for (int kt = 0; kt < nk; kt += 2) {
;     G_LOAD(a0, b0, min((kt + 2) * 32, klast));
;     G_COMPUTE(0);
;     G_WRITE(a1, b1, 1);
;     __syncthreads();
;     G_LOAD(a1, b1, min((kt + 3) * 32, klast));
;     G_COMPUTE(1);
;     G_WRITE(a0, b0, 0);
;     __syncthreads();
;   }
; __device__ void phase_mlp1_big(CParams& p, int l, int tm, int tn, char* smem) {
;   const int tid = otid();
;   int row0 = tm * 128, col0 = tn * 256;
;   f32x4 acc[4][8];
;   zero_acc<8>(acc);
;   gemm_mainloop8(p.hbuf + (size_t)row0 * DM, DM, p.W1T + ((size_t)l * DFF + col0) * DM, DM, DM, (bf16_t*)smem, acc, tid);
	s_add_u32 s50, s8, s57
	s_add_u32 m0, s50, 0x0
	s_nop 0
	global_load_lds_dwordx4 v236, s[12:13]
	s_add_u32 m0, s50, 0x400
	s_nop 0
	global_load_lds_dwordx4 v237, s[12:13]
	s_add_u32 m0, s50, 0x800
	s_nop 0
	global_load_lds_dwordx4 v238, s[12:13]
	s_add_u32 m0, s50, 0xc00
	s_nop 0
	global_load_lds_dwordx4 v239, s[12:13]
	s_add_u32 s12, s12, 128
	s_addc_u32 s13, s13, 0
	s_add_u32 s50, s8, s58
	s_add_u32 m0, s50, 0x0
	s_nop 0
	global_load_lds_dwordx4 v240, s[16:17]
	s_add_u32 m0, s50, 0x400
	s_nop 0
	global_load_lds_dwordx4 v241, s[16:17]
	s_add_u32 m0, s50, 0x800
	s_nop 0
	global_load_lds_dwordx4 v242, s[16:17]
	s_add_u32 m0, s50, 0xc00
	s_nop 0
	global_load_lds_dwordx4 v243, s[16:17]
	s_add_u32 s16, s16, 128
	s_addc_u32 s17, s17, 0
	s_add_u32 s50, s8, s59
	s_add_u32 m0, s50, 0x0
	s_nop 0
	global_load_lds_dwordx4 v236, s[12:13]
	s_add_u32 m0, s50, 0x400
	s_nop 0
	global_load_lds_dwordx4 v237, s[12:13]
	s_add_u32 m0, s50, 0x800
	s_nop 0
	global_load_lds_dwordx4 v238, s[12:13]
	s_add_u32 m0, s50, 0xc00
	s_nop 0
	global_load_lds_dwordx4 v239, s[12:13]
	s_add_u32 s12, s12, 128
	s_addc_u32 s13, s13, 0
	s_add_u32 s50, s8, s62
	s_add_u32 m0, s50, 0x0
	s_nop 0
	global_load_lds_dwordx4 v240, s[16:17]
	s_add_u32 m0, s50, 0x400
	s_nop 0
	global_load_lds_dwordx4 v241, s[16:17]
	s_add_u32 m0, s50, 0x800
	s_nop 0
	global_load_lds_dwordx4 v242, s[16:17]
	s_add_u32 m0, s50, 0xc00
	s_nop 0
	global_load_lds_dwordx4 v243, s[16:17]
	s_add_u32 s16, s16, 128
	s_addc_u32 s17, s17, 0
	v_mov_b32_e32 v0, 0
	v_mov_b32_e32 v1, 0
	v_mov_b32_e32 v2, 0
	v_mov_b32_e32 v3, 0
	v_mov_b32_e32 v4, 0
	v_mov_b32_e32 v5, 0
	v_mov_b32_e32 v6, 0
	v_mov_b32_e32 v7, 0
	v_mov_b32_e32 v8, 0
	v_mov_b32_e32 v9, 0
	v_mov_b32_e32 v10, 0
	v_mov_b32_e32 v11, 0
	v_mov_b32_e32 v12, 0
	v_mov_b32_e32 v13, 0
	v_mov_b32_e32 v14, 0
	v_mov_b32_e32 v15, 0
	v_mov_b32_e32 v16, 0
	v_mov_b32_e32 v17, 0
	v_mov_b32_e32 v18, 0
	v_mov_b32_e32 v19, 0
	v_mov_b32_e32 v20, 0
	v_mov_b32_e32 v21, 0
	v_mov_b32_e32 v22, 0
	v_mov_b32_e32 v23, 0
	v_mov_b32_e32 v24, 0
	v_mov_b32_e32 v25, 0
	v_mov_b32_e32 v26, 0
	v_mov_b32_e32 v27, 0
	v_mov_b32_e32 v28, 0
	v_mov_b32_e32 v29, 0
	v_mov_b32_e32 v30, 0
	v_mov_b32_e32 v31, 0
	v_mov_b32_e32 v32, 0
	v_mov_b32_e32 v33, 0
	v_mov_b32_e32 v34, 0
	v_mov_b32_e32 v35, 0
	v_mov_b32_e32 v36, 0
	v_mov_b32_e32 v37, 0
	v_mov_b32_e32 v38, 0
	v_mov_b32_e32 v39, 0
	v_mov_b32_e32 v40, 0
	v_mov_b32_e32 v41, 0
	v_mov_b32_e32 v42, 0
	v_mov_b32_e32 v43, 0
	v_mov_b32_e32 v44, 0
	v_mov_b32_e32 v45, 0
	v_mov_b32_e32 v46, 0
	v_mov_b32_e32 v47, 0
	v_mov_b32_e32 v48, 0
	v_mov_b32_e32 v49, 0
	v_mov_b32_e32 v50, 0
	v_mov_b32_e32 v51, 0
	v_mov_b32_e32 v52, 0
	v_mov_b32_e32 v53, 0
	v_mov_b32_e32 v54, 0
	v_mov_b32_e32 v55, 0
	v_mov_b32_e32 v56, 0
	v_mov_b32_e32 v57, 0
	v_mov_b32_e32 v58, 0
	v_mov_b32_e32 v59, 0
	v_mov_b32_e32 v60, 0
	v_mov_b32_e32 v61, 0
	v_mov_b32_e32 v62, 0
	v_mov_b32_e32 v63, 0
	s_waitcnt vmcnt(8)
	s_barrier
	v_add_u32_e32 v128, s57, v248
	v_add_u32_e32 v130, s58, v250
	ds_read_b128 v[168:171], v128 offset:0
	ds_read_b128 v[184:187], v130 offset:0
	ds_read_b128 v[172:175], v128 offset:2048
	ds_read_b128 v[188:191], v130 offset:512
	ds_read_b128 v[176:179], v128 offset:4096
	ds_read_b128 v[192:195], v130 offset:1024
	ds_read_b128 v[180:183], v128 offset:6144
	ds_read_b128 v[196:199], v130 offset:1536
.Lmlp1_tile:
	s_mul_i32 s51, s10, 0x2000
	s_lshl_b32 s54, s32, 1
	s_add_u32 s51, s51, s54
	s_add_u32 s42, s28, s51
	s_addc_u32 s43, s29, 0
	s_add_u32 s56, s44, 1
	s_min_u32 s56, s56, 7
	s_lshr_b32 s51, s56, 1
	s_lshl_b32 s51, s51, 3
	s_and_b32 s54, s4, 7
	s_add_u32 s51, s51, s54
	s_lshr_b32 s54, s51, 1
	s_lshl_b32 s54, s54, 3
	s_lshr_b32 s55, s4, 6
	s_add_u32 s54, s54, s55
	s_lshl_b32 s10, s54, 7
	s_and_b32 s51, s51, 1
	s_lshl_b32 s51, s51, 3
	s_lshr_b32 s55, s4, 3
	s_and_b32 s55, s55, 7
	s_add_u32 s51, s51, s55
	s_lshl_b32 s51, s51, 1
	s_and_b32 s55, s56, 1
	s_add_u32 s51, s51, s55
	s_lshl_b32 s32, s51, 7
	s_mul_i32 s51, s10, 0x800
	s_add_u32 s24, s0, s51
	s_addc_u32 s25, s1, 0
	s_mul_i32 s51, s2, 0x800000
	s_mul_i32 s54, s32, 0x800
	s_add_u32 s51, s51, s54
	s_add_u32 s26, s6, s51
	s_addc_u32 s27, s7, 0
	s_mov_b32 s45, 0
.Lmlp1_pair:
	s_waitcnt lgkmcnt(0)
	s_cmp_eq_u32 s45, 14
	s_cselect_b64 s[12:13], s[24:25], s[12:13]
	s_add_u32 s50, s8, s63
	s_add_u32 m0, s50, 0x0
	s_nop 0
	global_load_lds_dwordx4 v236, s[12:13]
	s_add_u32 m0, s50, 0x400
	s_nop 0
	global_load_lds_dwordx4 v237, s[12:13]
	s_add_u32 m0, s50, 0x800
	s_nop 0
	global_load_lds_dwordx4 v238, s[12:13]
	s_add_u32 m0, s50, 0xc00
	s_nop 0
	global_load_lds_dwordx4 v239, s[12:13]
	s_add_u32 s12, s12, 128
	s_addc_u32 s13, s13, 0
	v_add_u32_e32 v129, s57, v249
	v_add_u32_e32 v131, s58, v251
	v_mfma_f32_16x16x32_bf16 v[0:3], v[184:187], v[168:171], v[0:3]
	ds_read_b128 v[200:203], v129 offset:0
	v_mfma_f32_16x16x32_bf16 v[4:7], v[188:191], v[168:171], v[4:7]
	ds_read_b128 v[216:219], v131 offset:0
	v_mfma_f32_16x16x32_bf16 v[8:11], v[192:195], v[168:171], v[8:11]
	ds_read_b128 v[204:207], v129 offset:2048
	v_mfma_f32_16x16x32_bf16 v[12:15], v[196:199], v[168:171], v[12:15]
	ds_read_b128 v[220:223], v131 offset:512
	v_mfma_f32_16x16x32_bf16 v[16:19], v[184:187], v[172:175], v[16:19]
	ds_read_b128 v[208:211], v129 offset:4096
	v_mfma_f32_16x16x32_bf16 v[20:23], v[188:191], v[172:175], v[20:23]
	ds_read_b128 v[228:231], v131 offset:1024
	v_mfma_f32_16x16x32_bf16 v[24:27], v[192:195], v[172:175], v[24:27]
	ds_read_b128 v[212:215], v129 offset:6144
	v_mfma_f32_16x16x32_bf16 v[28:31], v[196:199], v[172:175], v[28:31]
	ds_read_b128 v[232:235], v131 offset:1536
	v_mfma_f32_16x16x32_bf16 v[32:35], v[184:187], v[176:179], v[32:35]
	v_mfma_f32_16x16x32_bf16 v[36:39], v[188:191], v[176:179], v[36:39]
	v_mfma_f32_16x16x32_bf16 v[40:43], v[192:195], v[176:179], v[40:43]
	v_mfma_f32_16x16x32_bf16 v[44:47], v[196:199], v[176:179], v[44:47]
	v_mfma_f32_16x16x32_bf16 v[48:51], v[184:187], v[180:183], v[48:51]
	v_mfma_f32_16x16x32_bf16 v[52:55], v[188:191], v[180:183], v[52:55]
	v_mfma_f32_16x16x32_bf16 v[56:59], v[192:195], v[180:183], v[56:59]
	v_mfma_f32_16x16x32_bf16 v[60:63], v[196:199], v[180:183], v[60:63]
	s_waitcnt vmcnt(4) lgkmcnt(0)
	s_barrier
; template <int NI> ...
;     ...
;   for (int kt = 0; kt < nk; kt += 2) {
;     G_LOAD(a0, b0, min((kt + 2) * 32, klast));
;     G_COMPUTE(0);
;     G_WRITE(a1, b1, 1);
;     __syncthreads();
;     G_LOAD(a1, b1, min((kt + 3) * 32, klast));
;     G_COMPUTE(1);
;     G_WRITE(a0, b0, 0);
;     __syncthreads();
;   }
	s_cmp_eq_u32 s45, 14
	s_cselect_b64 s[16:17], s[26:27], s[16:17]
	s_add_u32 s50, s8, s57
	s_add_u32 m0, s50, 0x0
	s_nop 0
	global_load_lds_dwordx4 v240, s[16:17]
	s_add_u32 m0, s50, 0x400
	s_nop 0
	global_load_lds_dwordx4 v241, s[16:17]
	s_add_u32 m0, s50, 0x800
	s_nop 0
	global_load_lds_dwordx4 v242, s[16:17]
	s_add_u32 m0, s50, 0xc00
	s_nop 0
	global_load_lds_dwordx4 v243, s[16:17]
	s_add_u32 s16, s16, 128
	s_addc_u32 s17, s17, 0
	v_add_u32_e32 v128, s59, v248
	v_add_u32_e32 v130, s62, v250
	v_mfma_f32_16x16x32_bf16 v[0:3], v[216:219], v[200:203], v[0:3]
	ds_read_b128 v[168:171], v128 offset:0
	v_mfma_f32_16x16x32_bf16 v[4:7], v[220:223], v[200:203], v[4:7]
	ds_read_b128 v[184:187], v130 offset:0
	v_mfma_f32_16x16x32_bf16 v[8:11], v[228:231], v[200:203], v[8:11]
	ds_read_b128 v[172:175], v128 offset:2048
	v_mfma_f32_16x16x32_bf16 v[12:15], v[232:235], v[200:203], v[12:15]
	ds_read_b128 v[188:191], v130 offset:512
	v_mfma_f32_16x16x32_bf16 v[16:19], v[216:219], v[204:207], v[16:19]
	ds_read_b128 v[176:179], v128 offset:4096
	v_mfma_f32_16x16x32_bf16 v[20:23], v[220:223], v[204:207], v[20:23]
	ds_read_b128 v[192:195], v130 offset:1024
	v_mfma_f32_16x16x32_bf16 v[24:27], v[228:231], v[204:207], v[24:27]
	ds_read_b128 v[180:183], v128 offset:6144
	v_mfma_f32_16x16x32_bf16 v[28:31], v[232:235], v[204:207], v[28:31]
	ds_read_b128 v[196:199], v130 offset:1536
	v_mfma_f32_16x16x32_bf16 v[32:35], v[216:219], v[208:211], v[32:35]
	v_mfma_f32_16x16x32_bf16 v[36:39], v[220:223], v[208:211], v[36:39]
	v_mfma_f32_16x16x32_bf16 v[40:43], v[228:231], v[208:211], v[40:43]
	v_mfma_f32_16x16x32_bf16 v[44:47], v[232:235], v[208:211], v[44:47]
	v_mfma_f32_16x16x32_bf16 v[48:51], v[216:219], v[212:215], v[48:51]
	v_mfma_f32_16x16x32_bf16 v[52:55], v[220:223], v[212:215], v[52:55]
	v_mfma_f32_16x16x32_bf16 v[56:59], v[228:231], v[212:215], v[56:59]
	v_mfma_f32_16x16x32_bf16 v[60:63], v[232:235], v[212:215], v[60:63]
	s_mov_b32 s51, s57
	s_mov_b32 s54, s58
	s_mov_b32 s57, s59
	s_mov_b32 s58, s62
	s_mov_b32 s59, s63
	s_mov_b32 s62, s51
	s_mov_b32 s63, s54
	s_add_u32 s45, s45, 1
	s_cmp_lt_u32 s45, 16
	s_cbranch_scc1 .Lmlp1_pair
; __device__ void phase_mlp1_big(CParams& p, int l, int tm, int tn, char* smem) {
;     ...
;   const int lane = tid & 63, wid = tid >> 6, wr = wid >> 1, wc = wid & 1;
; #pragma unroll
;   for (int mi = 0; mi < 4; mi++)
; #pragma unroll
;     for (int ni = 0; ni < 8; ni++)
; #pragma unroll
;       for (int j = 0; j < 4; j++) {
;         int rl = wr * 64 + mi * 16 + (lane >> 4) * 4 + j;
;         int cl = wc * 128 + ni * 16 + (lane & 15);
;         float a = fmaxf(acc[mi][ni][j], 0.f);
;         p.hidden[(size_t)(row0 + rl) * DFF + col0 + cl] = f2bf(a * a);
;       }
	s_nop 15
	s_nop 7
	v_max_f32_e32 v0, 0, v0
	v_max_f32_e32 v1, 0, v1
	v_max_f32_e32 v2, 0, v2
	v_max_f32_e32 v3, 0, v3
	v_max_f32_e32 v4, 0, v4
	v_max_f32_e32 v5, 0, v5
	v_max_f32_e32 v6, 0, v6
	v_max_f32_e32 v7, 0, v7
	v_max_f32_e32 v8, 0, v8
	v_max_f32_e32 v9, 0, v9
	v_max_f32_e32 v10, 0, v10
	v_max_f32_e32 v11, 0, v11
	v_max_f32_e32 v12, 0, v12
	v_max_f32_e32 v13, 0, v13
	v_max_f32_e32 v14, 0, v14
	v_max_f32_e32 v15, 0, v15
	v_mul_f32_e32 v0, v0, v0
	v_mul_f32_e32 v1, v1, v1
	v_mul_f32_e32 v2, v2, v2
	v_mul_f32_e32 v3, v3, v3
	v_mul_f32_e32 v4, v4, v4
	v_mul_f32_e32 v5, v5, v5
	v_mul_f32_e32 v6, v6, v6
	v_mul_f32_e32 v7, v7, v7
	v_mul_f32_e32 v8, v8, v8
	v_mul_f32_e32 v9, v9, v9
	v_mul_f32_e32 v10, v10, v10
	v_mul_f32_e32 v11, v11, v11
	v_mul_f32_e32 v12, v12, v12
	v_mul_f32_e32 v13, v13, v13
	v_mul_f32_e32 v14, v14, v14
	v_mul_f32_e32 v15, v15, v15
	v_cvt_pk_bf16_f32 v64, v0, v1
	v_cvt_pk_bf16_f32 v65, v2, v3
	v_cvt_pk_bf16_f32 v66, v4, v5
	v_cvt_pk_bf16_f32 v67, v6, v7
	global_store_dwordx4 v144, v[64:67], s[42:43] offset:0
	v_cvt_pk_bf16_f32 v68, v8, v9
	v_cvt_pk_bf16_f32 v69, v10, v11
	v_cvt_pk_bf16_f32 v70, v12, v13
	v_cvt_pk_bf16_f32 v71, v14, v15
	global_store_dwordx4 v144, v[68:71], s[42:43] offset:16
	s_add_u32 s42, s42, 0x20000
	s_addc_u32 s43, s43, 0
	v_max_f32_e32 v16, 0, v16
	v_max_f32_e32 v17, 0, v17
	v_max_f32_e32 v18, 0, v18
	v_max_f32_e32 v19, 0, v19
	v_max_f32_e32 v20, 0, v20
	v_max_f32_e32 v21, 0, v21
	v_max_f32_e32 v22, 0, v22
	v_max_f32_e32 v23, 0, v23
	v_max_f32_e32 v24, 0, v24
	v_max_f32_e32 v25, 0, v25
	v_max_f32_e32 v26, 0, v26
	v_max_f32_e32 v27, 0, v27
	v_max_f32_e32 v28, 0, v28
	v_max_f32_e32 v29, 0, v29
	v_max_f32_e32 v30, 0, v30
	v_max_f32_e32 v31, 0, v31
	v_mul_f32_e32 v16, v16, v16
	v_mul_f32_e32 v17, v17, v17
	v_mul_f32_e32 v18, v18, v18
	v_mul_f32_e32 v19, v19, v19
	v_mul_f32_e32 v20, v20, v20
	v_mul_f32_e32 v21, v21, v21
	v_mul_f32_e32 v22, v22, v22
	v_mul_f32_e32 v23, v23, v23
	v_mul_f32_e32 v24, v24, v24
	v_mul_f32_e32 v25, v25, v25
	v_mul_f32_e32 v26, v26, v26
	v_mul_f32_e32 v27, v27, v27
	v_mul_f32_e32 v28, v28, v28
	v_mul_f32_e32 v29, v29, v29
	v_mul_f32_e32 v30, v30, v30
	v_mul_f32_e32 v31, v31, v31
	v_cvt_pk_bf16_f32 v72, v16, v17
	v_cvt_pk_bf16_f32 v73, v18, v19
	v_cvt_pk_bf16_f32 v74, v20, v21
	v_cvt_pk_bf16_f32 v75, v22, v23
	global_store_dwordx4 v144, v[72:75], s[42:43] offset:0
	v_cvt_pk_bf16_f32 v76, v24, v25
	v_cvt_pk_bf16_f32 v77, v26, v27
	v_cvt_pk_bf16_f32 v78, v28, v29
	v_cvt_pk_bf16_f32 v79, v30, v31
	global_store_dwordx4 v144, v[76:79], s[42:43] offset:16
	s_add_u32 s42, s42, 0x20000
	s_addc_u32 s43, s43, 0
	v_max_f32_e32 v32, 0, v32
	v_max_f32_e32 v33, 0, v33
	v_max_f32_e32 v34, 0, v34
	v_max_f32_e32 v35, 0, v35
	v_max_f32_e32 v36, 0, v36
	v_max_f32_e32 v37, 0, v37
	v_max_f32_e32 v38, 0, v38
	v_max_f32_e32 v39, 0, v39
	v_max_f32_e32 v40, 0, v40
	v_max_f32_e32 v41, 0, v41
	v_max_f32_e32 v42, 0, v42
	v_max_f32_e32 v43, 0, v43
	v_max_f32_e32 v44, 0, v44
	v_max_f32_e32 v45, 0, v45
	v_max_f32_e32 v46, 0, v46
	v_max_f32_e32 v47, 0, v47
	v_mul_f32_e32 v32, v32, v32
	v_mul_f32_e32 v33, v33, v33
	v_mul_f32_e32 v34, v34, v34
	v_mul_f32_e32 v35, v35, v35
	v_mul_f32_e32 v36, v36, v36
	v_mul_f32_e32 v37, v37, v37
	v_mul_f32_e32 v38, v38, v38
	v_mul_f32_e32 v39, v39, v39
	v_mul_f32_e32 v40, v40, v40
	v_mul_f32_e32 v41, v41, v41
	v_mul_f32_e32 v42, v42, v42
	v_mul_f32_e32 v43, v43, v43
	v_mul_f32_e32 v44, v44, v44
	v_mul_f32_e32 v45, v45, v45
	v_mul_f32_e32 v46, v46, v46
	v_mul_f32_e32 v47, v47, v47
	v_cvt_pk_bf16_f32 v80, v32, v33
	v_cvt_pk_bf16_f32 v81, v34, v35
	v_cvt_pk_bf16_f32 v82, v36, v37
	v_cvt_pk_bf16_f32 v83, v38, v39
	global_store_dwordx4 v144, v[80:83], s[42:43] offset:0
	v_cvt_pk_bf16_f32 v84, v40, v41
	v_cvt_pk_bf16_f32 v85, v42, v43
	v_cvt_pk_bf16_f32 v86, v44, v45
	v_cvt_pk_bf16_f32 v87, v46, v47
	global_store_dwordx4 v144, v[84:87], s[42:43] offset:16
	s_add_u32 s42, s42, 0x20000
	s_addc_u32 s43, s43, 0
	v_max_f32_e32 v48, 0, v48
	v_max_f32_e32 v49, 0, v49
	v_max_f32_e32 v50, 0, v50
	v_max_f32_e32 v51, 0, v51
	v_max_f32_e32 v52, 0, v52
	v_max_f32_e32 v53, 0, v53
	v_max_f32_e32 v54, 0, v54
	v_max_f32_e32 v55, 0, v55
	v_max_f32_e32 v56, 0, v56
	v_max_f32_e32 v57, 0, v57
	v_max_f32_e32 v58, 0, v58
	v_max_f32_e32 v59, 0, v59
	v_max_f32_e32 v60, 0, v60
	v_max_f32_e32 v61, 0, v61
	v_max_f32_e32 v62, 0, v62
	v_max_f32_e32 v63, 0, v63
	v_mul_f32_e32 v48, v48, v48
	v_mul_f32_e32 v49, v49, v49
	v_mul_f32_e32 v50, v50, v50
	v_mul_f32_e32 v51, v51, v51
	v_mul_f32_e32 v52, v52, v52
	v_mul_f32_e32 v53, v53, v53
	v_mul_f32_e32 v54, v54, v54
	v_mul_f32_e32 v55, v55, v55
	v_mul_f32_e32 v56, v56, v56
	v_mul_f32_e32 v57, v57, v57
	v_mul_f32_e32 v58, v58, v58
	v_mul_f32_e32 v59, v59, v59
	v_mul_f32_e32 v60, v60, v60
	v_mul_f32_e32 v61, v61, v61
	v_mul_f32_e32 v62, v62, v62
	v_mul_f32_e32 v63, v63, v63
	v_cvt_pk_bf16_f32 v88, v48, v49
	v_cvt_pk_bf16_f32 v89, v50, v51
	v_cvt_pk_bf16_f32 v90, v52, v53
	v_cvt_pk_bf16_f32 v91, v54, v55
	global_store_dwordx4 v144, v[88:91], s[42:43] offset:0
	v_cvt_pk_bf16_f32 v92, v56, v57
	v_cvt_pk_bf16_f32 v93, v58, v59
	v_cvt_pk_bf16_f32 v94, v60, v61
	v_cvt_pk_bf16_f32 v95, v62, v63
	global_store_dwordx4 v144, v[92:95], s[42:43] offset:16
	v_mov_b32_e32 v0, 0
	v_mov_b32_e32 v1, 0
	v_mov_b32_e32 v2, 0
	v_mov_b32_e32 v3, 0
	v_mov_b32_e32 v4, 0
	v_mov_b32_e32 v5, 0
	v_mov_b32_e32 v6, 0
	v_mov_b32_e32 v7, 0
	v_mov_b32_e32 v8, 0
	v_mov_b32_e32 v9, 0
	v_mov_b32_e32 v10, 0
	v_mov_b32_e32 v11, 0
	v_mov_b32_e32 v12, 0
	v_mov_b32_e32 v13, 0
	v_mov_b32_e32 v14, 0
	v_mov_b32_e32 v15, 0
	v_mov_b32_e32 v16, 0
	v_mov_b32_e32 v17, 0
	v_mov_b32_e32 v18, 0
	v_mov_b32_e32 v19, 0
	v_mov_b32_e32 v20, 0
	v_mov_b32_e32 v21, 0
	v_mov_b32_e32 v22, 0
	v_mov_b32_e32 v23, 0
	v_mov_b32_e32 v24, 0
	v_mov_b32_e32 v25, 0
	v_mov_b32_e32 v26, 0
	v_mov_b32_e32 v27, 0
	v_mov_b32_e32 v28, 0
	v_mov_b32_e32 v29, 0
	v_mov_b32_e32 v30, 0
	v_mov_b32_e32 v31, 0
	v_mov_b32_e32 v32, 0
	v_mov_b32_e32 v33, 0
	v_mov_b32_e32 v34, 0
	v_mov_b32_e32 v35, 0
	v_mov_b32_e32 v36, 0
	v_mov_b32_e32 v37, 0
	v_mov_b32_e32 v38, 0
	v_mov_b32_e32 v39, 0
	v_mov_b32_e32 v40, 0
	v_mov_b32_e32 v41, 0
	v_mov_b32_e32 v42, 0
	v_mov_b32_e32 v43, 0
	v_mov_b32_e32 v44, 0
	v_mov_b32_e32 v45, 0
	v_mov_b32_e32 v46, 0
	v_mov_b32_e32 v47, 0
	v_mov_b32_e32 v48, 0
	v_mov_b32_e32 v49, 0
	v_mov_b32_e32 v50, 0
	v_mov_b32_e32 v51, 0
	v_mov_b32_e32 v52, 0
	v_mov_b32_e32 v53, 0
	v_mov_b32_e32 v54, 0
	v_mov_b32_e32 v55, 0
	v_mov_b32_e32 v56, 0
	v_mov_b32_e32 v57, 0
	v_mov_b32_e32 v58, 0
	v_mov_b32_e32 v59, 0
	v_mov_b32_e32 v60, 0
	v_mov_b32_e32 v61, 0
	v_mov_b32_e32 v62, 0
	v_mov_b32_e32 v63, 0
	s_waitcnt vmcnt(0)
	s_add_u32 s44, s44, 1
	s_cmp_lt_u32 s44, 8
	s_cbranch_scc1 .Lmlp1_tile
	s_waitcnt vmcnt(0) lgkmcnt(0)
	s_barrier
	ds_write_b128 v145, v[252:255] offset:40960
	s_waitcnt lgkmcnt(0)
	s_barrier

; __device__ __forceinline__ int otid() { int t = threadIdx.x; asm volatile("" : "+v"(t)); return t; }
; template <int NI> ...
;     ...
;   const int lane = tid & 63, wid = tid >> 6, wr = wid >> 1, wc = wid & 1;
;   const int lrow = tid >> 2, lch = (tid & 3) * 8;
;   const int l15 = lane & 15, lq = lane >> 4;
;   const bf16_t* pa = A + (size_t)lrow * lda + lch;
;   const bf16_t* pb = B + (size_t)lrow * ldb + lch;
;   const size_t a64 = (size_t)64 * lda, b64 = (size_t)64 * ldb;
;   u32x4 a0[2], a1[2], b0[NB], b1[NB];
;   const int nk = K >> 5;
;   const int klast = K - 32;
;   const int wofs = lrow * GROW + lch;
;   const int raofs = (wr * 64 + l15) * GROW + lq * 8;
;   const int rbofs = 128 * GROW + (wc * (16 * NI) + l15) * GROW + lq * 8;
;     ...
;   G_LOAD(a0, b0, 0);
;   G_LOAD(a1, b1, 32);
;   __syncthreads();
;   G_WRITE(a0, b0, 0);
;   __syncthreads();
; __device__ void phase_proj_res(CParams& p, int l, int tm, int tn, char* smem, const bf16_t* A, int K,
;                                const bf16_t* Bt, int gate_off, float gscale) {
;   const int tid = otid();
;   bf16_t* sA = (bf16_t*)smem;
;   bf16_t* sB = sA + 128 * LDSS;
;   int row0 = tm * 128, col0 = tn * 128;
;   f32x4 acc[4][4];
;   zero_acc<4>(acc);
;   gemm_mainloop<4>(A + (size_t)row0 * K, K, Bt + (size_t)col0 * K, K, K, sA, sB, acc, tid);
.LBB0_1127:
	s_or_b64 exec, exec, s[20:21]
	s_mov_b64 s[20:21], s[34:35]
	s_waitcnt lgkmcnt(0)
	s_barrier
	s_load_dwordx2 s[6:7], s[20:21], 0x128
	s_load_dwordx2 s[22:23], s[20:21], 0x1e0
	s_load_dwordx2 s[24:25], s[20:21], 0x160
	s_load_dwordx2 s[44:45], s[20:21], 0x148
	s_load_dwordx2 s[48:49], s[20:21], 0xf8
	s_waitcnt lgkmcnt(0)
	s_add_u32 s2, s6, s18
	s_addc_u32 s4, s7, s19
	v_readlane_b32 s6, v224, 15
	v_readlane_b32 s7, v224, 16
	s_add_u32 s18, s2, s6
	s_addc_u32 s19, s4, s7
	s_mov_b32 s2, 0
	s_mov_b64 exec, -1
	ds_read_b128 v[252:255], v145 offset:40960
	s_load_dwordx2 s[6:7], s[20:21], 0x1e0
	s_load_dwordx2 s[12:13], s[20:21], 0x128
	s_load_dwordx2 s[28:29], s[20:21], 0xf8
	s_load_dwordx2 s[50:51], s[20:21], 0x160
	v_readlane_b32 s0, v224, 26
	v_readlane_b32 s2, v225, 4
	v_readfirstlane_b32 s54, v147
	v_and_b32_e32 v166, 63, v147
	s_nop 3
	s_lshr_b32 s54, s54, 6
	s_lshl_b32 s4, s54, 12
	v_lshrrev_b32_e32 v167, 3, v166
	s_lshl_b32 s58, s54, 5
	v_add_u32_e32 v167, s58, v167
	v_and_b32_e32 v226, 7, v166
	v_lshrrev_b32_e32 v227, 4, v166
	s_mov_b32 s56, 0x2000
	s_mov_b32 s57, 0x2000
	v_xor_b32_e32 v248, v226, v227
	v_xor_b32_e32 v249, 0, v248
	v_lshlrev_b32_e32 v249, 4, v249
	v_add_u32_e32 v250, 0, v167
	v_mul_lo_u32 v236, v250, s56
	v_add_u32_e32 v236, v236, v249
	v_mul_lo_u32 v240, v250, s57
	v_add_u32_e32 v240, v240, v249
	v_xor_b32_e32 v249, 4, v248
	v_lshlrev_b32_e32 v249, 4, v249
	v_add_u32_e32 v250, 8, v167
	v_mul_lo_u32 v237, v250, s56
	v_add_u32_e32 v237, v237, v249
	v_mul_lo_u32 v241, v250, s57
	v_add_u32_e32 v241, v241, v249
	v_xor_b32_e32 v249, 0, v248
	v_lshlrev_b32_e32 v249, 4, v249
	v_add_u32_e32 v250, 16, v167
	v_mul_lo_u32 v238, v250, s56
	v_add_u32_e32 v238, v238, v249
	v_mul_lo_u32 v242, v250, s57
	v_add_u32_e32 v242, v242, v249
	v_xor_b32_e32 v249, 4, v248
	v_lshlrev_b32_e32 v249, 4, v249
	v_add_u32_e32 v250, 24, v167
	v_mul_lo_u32 v239, v250, s56
	v_add_u32_e32 v239, v239, v249
	v_mul_lo_u32 v243, v250, s57
	v_add_u32_e32 v243, v243, v249
	v_and_b32_e32 v167, 15, v166
	v_lshrrev_b32_e32 v227, 4, v166
	s_lshr_b32 s58, s54, 1
	s_and_b32 s59, s54, 1
	s_lshl_b32 s58, s58, 6
	s_lshl_b32 s59, s59, 6
	v_lshrrev_b32_e32 v226, 1, v167
	v_xor_b32_e32 v226, v227, v226
	v_lshlrev_b32_e32 v226, 4, v226
	v_add_u32_e32 v248, s58, v167
	v_lshl_add_u32 v248, v248, 7, v226
	v_xor_b32_e32 v249, 64, v248
	v_add_u32_e32 v250, s59, v167
	v_lshl_add_u32 v250, v250, 7, v226
	v_xor_b32_e32 v251, 64, v250
	v_lshl_add_u32 v132, v227, 2, s59
	v_lshlrev_b32_e32 v132, 2, v132
	v_add_u32_e32 v144, s58, v167
	v_lshl_add_u32 v144, v144, 12, v132
	s_mov_b32 s62, 0x0
	s_mov_b32 s63, 0x4000
	s_mov_b32 s92, 0x8000
	s_mov_b32 s93, 0xc000
	s_mov_b32 s98, 0x10000
	s_waitcnt lgkmcnt(0)
	s_mov_b32 s32, 0
	s_and_b32 s56, s2, 7
	s_lshl_b32 s56, s56, 4
	s_lshr_b32 s57, s2, 5
	s_add_u32 s56, s56, s57
	s_lshl_b32 s8, s56, 7
	s_lshr_b32 s57, s2, 3
	s_and_b32 s57, s57, 3
	s_lshl_b32 s57, s57, 1
	s_add_u32 s57, s57, s32
	s_lshl_b32 s10, s57, 7
	s_mul_i32 s56, s8, 0x2000
	s_add_u32 s16, s6, s56
	s_addc_u32 s17, s7, 0
	s_mul_i32 s56, s0, 0x800000
	s_mul_i32 s57, s10, 0x2000
	s_add_u32 s56, s56, s57
	s_add_u32 s18, s12, s56
	s_addc_u32 s19, s13, 0
	s_barrier
	s_add_u32 s55, s4, s62
	s_add_u32 m0, s55, 0x0
	s_nop 0
	global_load_lds_dwordx4 v236, s[16:17]
	s_add_u32 m0, s55, 0x400
	s_nop 0
	global_load_lds_dwordx4 v237, s[16:17]
	s_add_u32 m0, s55, 0x800
	s_nop 0
	global_load_lds_dwordx4 v238, s[16:17]
	s_add_u32 m0, s55, 0xc00
	s_nop 0
	global_load_lds_dwordx4 v239, s[16:17]
	s_add_u32 s16, s16, 128
	s_addc_u32 s17, s17, 0
	s_add_u32 s55, s4, s63
	s_add_u32 m0, s55, 0x0
	s_nop 0
	global_load_lds_dwordx4 v240, s[18:19]
	s_add_u32 m0, s55, 0x400
	s_nop 0
	global_load_lds_dwordx4 v241, s[18:19]
	s_add_u32 m0, s55, 0x800
	s_nop 0
	global_load_lds_dwordx4 v242, s[18:19]
	s_add_u32 m0, s55, 0xc00
	s_nop 0
	global_load_lds_dwordx4 v243, s[18:19]
	s_add_u32 s18, s18, 128
	s_addc_u32 s19, s19, 0
	s_add_u32 s55, s4, s92
	s_add_u32 m0, s55, 0x0
	s_nop 0
	global_load_lds_dwordx4 v236, s[16:17]
	s_add_u32 m0, s55, 0x400
	s_nop 0
	global_load_lds_dwordx4 v237, s[16:17]
	s_add_u32 m0, s55, 0x800
	s_nop 0
	global_load_lds_dwordx4 v238, s[16:17]
	s_add_u32 m0, s55, 0xc00
	s_nop 0
	global_load_lds_dwordx4 v239, s[16:17]
	s_add_u32 s16, s16, 128
	s_addc_u32 s17, s17, 0
	s_add_u32 s55, s4, s93
	s_add_u32 m0, s55, 0x0
	s_nop 0
	global_load_lds_dwordx4 v240, s[18:19]
	s_add_u32 m0, s55, 0x400
	s_nop 0
	global_load_lds_dwordx4 v241, s[18:19]
	s_add_u32 m0, s55, 0x800
	s_nop 0
	global_load_lds_dwordx4 v242, s[18:19]
	s_add_u32 m0, s55, 0xc00
	s_nop 0
	global_load_lds_dwordx4 v243, s[18:19]
	s_add_u32 s18, s18, 128
	s_addc_u32 s19, s19, 0
	v_mov_b32_e32 v0, 0
	v_mov_b32_e32 v1, 0
	v_mov_b32_e32 v2, 0
	v_mov_b32_e32 v3, 0
	v_mov_b32_e32 v4, 0
	v_mov_b32_e32 v5, 0
	v_mov_b32_e32 v6, 0
	v_mov_b32_e32 v7, 0
	v_mov_b32_e32 v8, 0
	v_mov_b32_e32 v9, 0
	v_mov_b32_e32 v10, 0
	v_mov_b32_e32 v11, 0
	v_mov_b32_e32 v12, 0
	v_mov_b32_e32 v13, 0
	v_mov_b32_e32 v14, 0
	v_mov_b32_e32 v15, 0
	v_mov_b32_e32 v16, 0
	v_mov_b32_e32 v17, 0
	v_mov_b32_e32 v18, 0
	v_mov_b32_e32 v19, 0
	v_mov_b32_e32 v20, 0
	v_mov_b32_e32 v21, 0
	v_mov_b32_e32 v22, 0
	v_mov_b32_e32 v23, 0
	v_mov_b32_e32 v24, 0
	v_mov_b32_e32 v25, 0
	v_mov_b32_e32 v26, 0
	v_mov_b32_e32 v27, 0
	v_mov_b32_e32 v28, 0
	v_mov_b32_e32 v29, 0
	v_mov_b32_e32 v30, 0
	v_mov_b32_e32 v31, 0
	v_mov_b32_e32 v32, 0
	v_mov_b32_e32 v33, 0
	v_mov_b32_e32 v34, 0
	v_mov_b32_e32 v35, 0
	v_mov_b32_e32 v36, 0
	v_mov_b32_e32 v37, 0
	v_mov_b32_e32 v38, 0
	v_mov_b32_e32 v39, 0
	v_mov_b32_e32 v40, 0
	v_mov_b32_e32 v41, 0
	v_mov_b32_e32 v42, 0
	v_mov_b32_e32 v43, 0
	v_mov_b32_e32 v44, 0
	v_mov_b32_e32 v45, 0
	v_mov_b32_e32 v46, 0
	v_mov_b32_e32 v47, 0
	v_mov_b32_e32 v48, 0
	v_mov_b32_e32 v49, 0
	v_mov_b32_e32 v50, 0
	v_mov_b32_e32 v51, 0
	v_mov_b32_e32 v52, 0
	v_mov_b32_e32 v53, 0
	v_mov_b32_e32 v54, 0
	v_mov_b32_e32 v55, 0
	v_mov_b32_e32 v56, 0
	v_mov_b32_e32 v57, 0
	v_mov_b32_e32 v58, 0
	v_mov_b32_e32 v59, 0
	v_mov_b32_e32 v60, 0
	v_mov_b32_e32 v61, 0
	v_mov_b32_e32 v62, 0
	v_mov_b32_e32 v63, 0
	s_waitcnt vmcnt(8)
	s_barrier
	v_add_u32_e32 v128, s62, v248
	v_add_u32_e32 v130, s63, v250
	ds_read_b128 v[168:171], v128 offset:0
	ds_read_b128 v[184:187], v130 offset:0
	ds_read_b128 v[172:175], v128 offset:2048
	ds_read_b128 v[188:191], v130 offset:2048
	ds_read_b128 v[176:179], v128 offset:4096
	ds_read_b128 v[192:195], v130 offset:4096
	ds_read_b128 v[180:183], v128 offset:6144
	ds_read_b128 v[196:199], v130 offset:6144
; template <int NI> ...
;     ...
;   for (int kt = 0; kt < nk; kt += 2) {
;     G_LOAD(a0, b0, min((kt + 2) * 32, klast));
;     G_COMPUTE(0);
;     G_WRITE(a1, b1, 1);
;     __syncthreads();
;     G_LOAD(a1, b1, min((kt + 3) * 32, klast));
;     G_COMPUTE(1);
;     G_WRITE(a0, b0, 0);
;     __syncthreads();
;   }
; __device__ void phase_proj_res(CParams& p, int l, int tm, int tn, char* smem, const bf16_t* A, int K,
;                                const bf16_t* Bt, int gate_off, float gscale) {
;     ...
;   const float* md = p.mod + ((size_t)l * 3 + modvec_of_tok(row0)) * 6144 + gate_off;
;   EPI_LOOP({
;     float* xp = xrow(p, row0 + rl) + col0 + cl;
.Lmlp2_tile:
	s_mul_i32 s56, s0, 3
	s_lshr_b32 s57, s8, 13
	s_add_u32 s56, s56, s57
	s_mul_i32 s56, s56, 6144
	s_add_u32 s56, s56, s10
	s_add_u32 s56, s56, 5120
	s_lshl_b32 s56, s56, 2
	s_add_u32 s52, s50, s56
	s_addc_u32 s53, s51, 0
	s_lshl_b32 s56, s8, 12
	s_lshl_b32 s57, s10, 2
	s_add_u32 s56, s56, s57
	s_add_u32 s40, s28, s56
	s_addc_u32 s41, s29, 0
	s_add_u32 s59, s32, 1
	s_min_u32 s59, s59, 1
	s_and_b32 s56, s2, 7
	s_lshl_b32 s56, s56, 4
	s_lshr_b32 s57, s2, 5
	s_add_u32 s56, s56, s57
	s_lshl_b32 s8, s56, 7
	s_lshr_b32 s57, s2, 3
	s_and_b32 s57, s57, 3
	s_lshl_b32 s57, s57, 1
	s_add_u32 s57, s57, s59
	s_lshl_b32 s10, s57, 7
	s_mul_i32 s56, s8, 0x2000
	s_add_u32 s22, s6, s56
	s_addc_u32 s23, s7, 0
	s_mul_i32 s56, s0, 0x800000
	s_mul_i32 s57, s10, 0x2000
	s_add_u32 s56, s56, s57
	s_add_u32 s26, s12, s56
	s_addc_u32 s27, s13, 0
	s_mov_b32 s54, 0
.Lmlp2_pair:
	s_waitcnt lgkmcnt(0)
	s_cmp_eq_u32 s54, 62
	s_cselect_b64 s[16:17], s[22:23], s[16:17]
	s_add_u32 s55, s4, s98
	s_add_u32 m0, s55, 0x0
	s_nop 0
	global_load_lds_dwordx4 v236, s[16:17]
	s_add_u32 m0, s55, 0x400
	s_nop 0
	global_load_lds_dwordx4 v237, s[16:17]
	s_add_u32 m0, s55, 0x800
	s_nop 0
	global_load_lds_dwordx4 v238, s[16:17]
	s_add_u32 m0, s55, 0xc00
	s_nop 0
	global_load_lds_dwordx4 v239, s[16:17]
	s_add_u32 s16, s16, 128
	s_addc_u32 s17, s17, 0
	v_add_u32_e32 v129, s62, v249
	v_add_u32_e32 v131, s63, v251
	v_mfma_f32_16x16x32_bf16 v[0:3], v[184:187], v[168:171], v[0:3]
	ds_read_b128 v[200:203], v129 offset:0
	v_mfma_f32_16x16x32_bf16 v[4:7], v[188:191], v[168:171], v[4:7]
	ds_read_b128 v[216:219], v131 offset:0
	v_mfma_f32_16x16x32_bf16 v[8:11], v[192:195], v[168:171], v[8:11]
	ds_read_b128 v[204:207], v129 offset:2048
	v_mfma_f32_16x16x32_bf16 v[12:15], v[196:199], v[168:171], v[12:15]
	ds_read_b128 v[220:223], v131 offset:2048
	v_mfma_f32_16x16x32_bf16 v[16:19], v[184:187], v[172:175], v[16:19]
	ds_read_b128 v[208:211], v129 offset:4096
	v_mfma_f32_16x16x32_bf16 v[20:23], v[188:191], v[172:175], v[20:23]
	ds_read_b128 v[228:231], v131 offset:4096
	v_mfma_f32_16x16x32_bf16 v[24:27], v[192:195], v[172:175], v[24:27]
	ds_read_b128 v[212:215], v129 offset:6144
	v_mfma_f32_16x16x32_bf16 v[28:31], v[196:199], v[172:175], v[28:31]
	ds_read_b128 v[232:235], v131 offset:6144
	v_mfma_f32_16x16x32_bf16 v[32:35], v[184:187], v[176:179], v[32:35]
	v_mfma_f32_16x16x32_bf16 v[36:39], v[188:191], v[176:179], v[36:39]
	v_mfma_f32_16x16x32_bf16 v[40:43], v[192:195], v[176:179], v[40:43]
	v_mfma_f32_16x16x32_bf16 v[44:47], v[196:199], v[176:179], v[44:47]
	v_mfma_f32_16x16x32_bf16 v[48:51], v[184:187], v[180:183], v[48:51]
	v_mfma_f32_16x16x32_bf16 v[52:55], v[188:191], v[180:183], v[52:55]
	v_mfma_f32_16x16x32_bf16 v[56:59], v[192:195], v[180:183], v[56:59]
	v_mfma_f32_16x16x32_bf16 v[60:63], v[196:199], v[180:183], v[60:63]
	s_waitcnt vmcnt(4) lgkmcnt(0)
	s_barrier
	s_cmp_eq_u32 s54, 62
	s_cselect_b64 s[18:19], s[26:27], s[18:19]
	s_add_u32 s55, s4, s62
	s_add_u32 m0, s55, 0x0
	s_nop 0
	global_load_lds_dwordx4 v240, s[18:19]
	s_add_u32 m0, s55, 0x400
	s_nop 0
	global_load_lds_dwordx4 v241, s[18:19]
	s_add_u32 m0, s55, 0x800
	s_nop 0
	global_load_lds_dwordx4 v242, s[18:19]
	s_add_u32 m0, s55, 0xc00
	s_nop 0
	global_load_lds_dwordx4 v243, s[18:19]
	s_add_u32 s18, s18, 128
	s_addc_u32 s19, s19, 0
	v_add_u32_e32 v128, s92, v248
	v_add_u32_e32 v130, s93, v250
	v_mfma_f32_16x16x32_bf16 v[0:3], v[216:219], v[200:203], v[0:3]
	ds_read_b128 v[168:171], v128 offset:0
	v_mfma_f32_16x16x32_bf16 v[4:7], v[220:223], v[200:203], v[4:7]
	ds_read_b128 v[184:187], v130 offset:0
	v_mfma_f32_16x16x32_bf16 v[8:11], v[228:231], v[200:203], v[8:11]
	ds_read_b128 v[172:175], v128 offset:2048
	v_mfma_f32_16x16x32_bf16 v[12:15], v[232:235], v[200:203], v[12:15]
	ds_read_b128 v[188:191], v130 offset:2048
	v_mfma_f32_16x16x32_bf16 v[16:19], v[216:219], v[204:207], v[16:19]
	ds_read_b128 v[176:179], v128 offset:4096
	v_mfma_f32_16x16x32_bf16 v[20:23], v[220:223], v[204:207], v[20:23]
	ds_read_b128 v[192:195], v130 offset:4096
	v_mfma_f32_16x16x32_bf16 v[24:27], v[228:231], v[204:207], v[24:27]
	ds_read_b128 v[180:183], v128 offset:6144
	v_mfma_f32_16x16x32_bf16 v[28:31], v[232:235], v[204:207], v[28:31]
	ds_read_b128 v[196:199], v130 offset:6144
	v_mfma_f32_16x16x32_bf16 v[32:35], v[216:219], v[208:211], v[32:35]
	v_mfma_f32_16x16x32_bf16 v[36:39], v[220:223], v[208:211], v[36:39]
	v_mfma_f32_16x16x32_bf16 v[40:43], v[228:231], v[208:211], v[40:43]
	v_mfma_f32_16x16x32_bf16 v[44:47], v[232:235], v[208:211], v[44:47]
	v_mfma_f32_16x16x32_bf16 v[48:51], v[216:219], v[212:215], v[48:51]
	v_mfma_f32_16x16x32_bf16 v[52:55], v[220:223], v[212:215], v[52:55]
	v_mfma_f32_16x16x32_bf16 v[56:59], v[228:231], v[212:215], v[56:59]
	v_mfma_f32_16x16x32_bf16 v[60:63], v[232:235], v[212:215], v[60:63]
	s_mov_b32 s56, s62
	s_mov_b32 s57, s63
	s_mov_b32 s62, s92
	s_mov_b32 s63, s93
	s_mov_b32 s92, s98
	s_mov_b32 s93, s56
	s_mov_b32 s98, s57
	s_add_u32 s54, s54, 1
	s_cmp_lt_u32 s54, 64
	s_cbranch_scc1 .Lmlp2_pair
; __device__ void phase_proj_res(CParams& p, int l, int tm, int tn, char* smem, const bf16_t* A, int K,
;                                const bf16_t* Bt, int gate_off, float gscale) {
;     ...
;   const float* md = p.mod + ((size_t)l * 3 + modvec_of_tok(row0)) * 6144 + gate_off;
;   EPI_LOOP({
;     float* xp = xrow(p, row0 + rl) + col0 + cl;
;     *xp = *xp + gscale * md[col0 + cl] * acc[mi][ni][j];
;   })
	s_nop 15
	s_nop 7
	global_load_dwordx4 v[200:203], v132, s[52:53] offset:0
	global_load_dwordx4 v[204:207], v132, s[52:53] offset:64
	global_load_dwordx4 v[208:211], v132, s[52:53] offset:128
	global_load_dwordx4 v[212:215], v132, s[52:53] offset:192
	s_mov_b64 s[52:53], s[40:41]
	global_load_dwordx4 v[64:67], v144, s[52:53] offset:0
	global_load_dwordx4 v[68:71], v144, s[52:53] offset:64
	global_load_dwordx4 v[72:75], v144, s[52:53] offset:128
	global_load_dwordx4 v[76:79], v144, s[52:53] offset:192
	s_add_u32 s52, s52, 0x10000
	s_addc_u32 s53, s53, 0
	global_load_dwordx4 v[80:83], v144, s[52:53] offset:0
	global_load_dwordx4 v[84:87], v144, s[52:53] offset:64
	global_load_dwordx4 v[88:91], v144, s[52:53] offset:128
	global_load_dwordx4 v[92:95], v144, s[52:53] offset:192
	s_add_u32 s52, s52, 0x10000
	s_addc_u32 s53, s53, 0
	global_load_dwordx4 v[96:99], v144, s[52:53] offset:0
	global_load_dwordx4 v[100:103], v144, s[52:53] offset:64
	global_load_dwordx4 v[104:107], v144, s[52:53] offset:128
	global_load_dwordx4 v[108:111], v144, s[52:53] offset:192
	s_add_u32 s52, s52, 0x10000
	s_addc_u32 s53, s53, 0
	global_load_dwordx4 v[112:115], v144, s[52:53] offset:0
	global_load_dwordx4 v[116:119], v144, s[52:53] offset:64
	global_load_dwordx4 v[120:123], v144, s[52:53] offset:128
	global_load_dwordx4 v[124:127], v144, s[52:53] offset:192
	s_waitcnt vmcnt(12)
	v_fmac_f32_e32 v64, v200, v0
	v_fmac_f32_e32 v65, v201, v1
	v_fmac_f32_e32 v66, v202, v2
	v_fmac_f32_e32 v67, v203, v3
	v_fmac_f32_e32 v68, v204, v4
	v_fmac_f32_e32 v69, v205, v5
	v_fmac_f32_e32 v70, v206, v6
	v_fmac_f32_e32 v71, v207, v7
	v_fmac_f32_e32 v72, v208, v8
	v_fmac_f32_e32 v73, v209, v9
	v_fmac_f32_e32 v74, v210, v10
	v_fmac_f32_e32 v75, v211, v11
	v_fmac_f32_e32 v76, v212, v12
	v_fmac_f32_e32 v77, v213, v13
	v_fmac_f32_e32 v78, v214, v14
	v_fmac_f32_e32 v79, v215, v15
	s_waitcnt vmcnt(8)
	v_fmac_f32_e32 v80, v200, v16
	v_fmac_f32_e32 v81, v201, v17
	v_fmac_f32_e32 v82, v202, v18
	v_fmac_f32_e32 v83, v203, v19
	v_fmac_f32_e32 v84, v204, v20
	v_fmac_f32_e32 v85, v205, v21
	v_fmac_f32_e32 v86, v206, v22
	v_fmac_f32_e32 v87, v207, v23
	v_fmac_f32_e32 v88, v208, v24
	v_fmac_f32_e32 v89, v209, v25
	v_fmac_f32_e32 v90, v210, v26
	v_fmac_f32_e32 v91, v211, v27
	v_fmac_f32_e32 v92, v212, v28
	v_fmac_f32_e32 v93, v213, v29
	v_fmac_f32_e32 v94, v214, v30
	v_fmac_f32_e32 v95, v215, v31
	s_waitcnt vmcnt(4)
	v_fmac_f32_e32 v96, v200, v32
	v_fmac_f32_e32 v97, v201, v33
	v_fmac_f32_e32 v98, v202, v34
	v_fmac_f32_e32 v99, v203, v35
	v_fmac_f32_e32 v100, v204, v36
	v_fmac_f32_e32 v101, v205, v37
	v_fmac_f32_e32 v102, v206, v38
	v_fmac_f32_e32 v103, v207, v39
	v_fmac_f32_e32 v104, v208, v40
	v_fmac_f32_e32 v105, v209, v41
	v_fmac_f32_e32 v106, v210, v42
	v_fmac_f32_e32 v107, v211, v43
	v_fmac_f32_e32 v108, v212, v44
	v_fmac_f32_e32 v109, v213, v45
	v_fmac_f32_e32 v110, v214, v46
	v_fmac_f32_e32 v111, v215, v47
	s_waitcnt vmcnt(0)
	v_fmac_f32_e32 v112, v200, v48
	v_fmac_f32_e32 v113, v201, v49
	v_fmac_f32_e32 v114, v202, v50
	v_fmac_f32_e32 v115, v203, v51
	v_fmac_f32_e32 v116, v204, v52
	v_fmac_f32_e32 v117, v205, v53
	v_fmac_f32_e32 v118, v206, v54
	v_fmac_f32_e32 v119, v207, v55
	v_fmac_f32_e32 v120, v208, v56
	v_fmac_f32_e32 v121, v209, v57
	v_fmac_f32_e32 v122, v210, v58
	v_fmac_f32_e32 v123, v211, v59
	v_fmac_f32_e32 v124, v212, v60
	v_fmac_f32_e32 v125, v213, v61
	v_fmac_f32_e32 v126, v214, v62
	v_fmac_f32_e32 v127, v215, v63
	global_store_dwordx4 v144, v[64:67], s[40:41] offset:0
	global_store_dwordx4 v144, v[68:71], s[40:41] offset:64
	global_store_dwordx4 v144, v[72:75], s[40:41] offset:128
	global_store_dwordx4 v144, v[76:79], s[40:41] offset:192
	s_add_u32 s40, s40, 0x10000
	s_addc_u32 s41, s41, 0
	global_store_dwordx4 v144, v[80:83], s[40:41] offset:0
	global_store_dwordx4 v144, v[84:87], s[40:41] offset:64
	global_store_dwordx4 v144, v[88:91], s[40:41] offset:128
	global_store_dwordx4 v144, v[92:95], s[40:41] offset:192
	s_add_u32 s40, s40, 0x10000
	s_addc_u32 s41, s41, 0
	global_store_dwordx4 v144, v[96:99], s[40:41] offset:0
	global_store_dwordx4 v144, v[100:103], s[40:41] offset:64
	global_store_dwordx4 v144, v[104:107], s[40:41] offset:128
	global_store_dwordx4 v144, v[108:111], s[40:41] offset:192
	s_add_u32 s40, s40, 0x10000
	s_addc_u32 s41, s41, 0
	global_store_dwordx4 v144, v[112:115], s[40:41] offset:0
	global_store_dwordx4 v144, v[116:119], s[40:41] offset:64
	global_store_dwordx4 v144, v[120:123], s[40:41] offset:128
	global_store_dwordx4 v144, v[124:127], s[40:41] offset:192
	v_mov_b32_e32 v0, 0
	v_mov_b32_e32 v1, 0
	v_mov_b32_e32 v2, 0
	v_mov_b32_e32 v3, 0
	v_mov_b32_e32 v4, 0
	v_mov_b32_e32 v5, 0
	v_mov_b32_e32 v6, 0
	v_mov_b32_e32 v7, 0
	v_mov_b32_e32 v8, 0
	v_mov_b32_e32 v9, 0
	v_mov_b32_e32 v10, 0
	v_mov_b32_e32 v11, 0
	v_mov_b32_e32 v12, 0
	v_mov_b32_e32 v13, 0
	v_mov_b32_e32 v14, 0
	v_mov_b32_e32 v15, 0
	v_mov_b32_e32 v16, 0
	v_mov_b32_e32 v17, 0
	v_mov_b32_e32 v18, 0
	v_mov_b32_e32 v19, 0
	v_mov_b32_e32 v20, 0
	v_mov_b32_e32 v21, 0
	v_mov_b32_e32 v22, 0
	v_mov_b32_e32 v23, 0
	v_mov_b32_e32 v24, 0
	v_mov_b32_e32 v25, 0
	v_mov_b32_e32 v26, 0
	v_mov_b32_e32 v27, 0
	v_mov_b32_e32 v28, 0
	v_mov_b32_e32 v29, 0
	v_mov_b32_e32 v30, 0
	v_mov_b32_e32 v31, 0
	v_mov_b32_e32 v32, 0
	v_mov_b32_e32 v33, 0
	v_mov_b32_e32 v34, 0
	v_mov_b32_e32 v35, 0
	v_mov_b32_e32 v36, 0
	v_mov_b32_e32 v37, 0
	v_mov_b32_e32 v38, 0
	v_mov_b32_e32 v39, 0
	v_mov_b32_e32 v40, 0
	v_mov_b32_e32 v41, 0
	v_mov_b32_e32 v42, 0
	v_mov_b32_e32 v43, 0
	v_mov_b32_e32 v44, 0
	v_mov_b32_e32 v45, 0
	v_mov_b32_e32 v46, 0
	v_mov_b32_e32 v47, 0
	v_mov_b32_e32 v48, 0
	v_mov_b32_e32 v49, 0
	v_mov_b32_e32 v50, 0
	v_mov_b32_e32 v51, 0
	v_mov_b32_e32 v52, 0
	v_mov_b32_e32 v53, 0
	v_mov_b32_e32 v54, 0
	v_mov_b32_e32 v55, 0
	v_mov_b32_e32 v56, 0
	v_mov_b32_e32 v57, 0
	v_mov_b32_e32 v58, 0
	v_mov_b32_e32 v59, 0
	v_mov_b32_e32 v60, 0
	v_mov_b32_e32 v61, 0
	v_mov_b32_e32 v62, 0
	v_mov_b32_e32 v63, 0
	s_waitcnt vmcnt(0)
	s_add_u32 s32, s32, 1
	s_cmp_lt_u32 s32, 2
	s_cbranch_scc1 .Lmlp2_tile
	s_waitcnt vmcnt(0) lgkmcnt(0)
	s_barrier
	ds_write_b128 v145, v[252:255] offset:40960
	s_waitcnt lgkmcnt(0)
	s_barrier
	s_mov_b64 s[50:51], 0

; __global__ void __launch_bounds__(256, 2) fwd_megakernel(Params p_unused) {
;   cg::grid_group grid = cg::this_grid();
;   __shared__ __attribute__((aligned(16))) char smem[SMEM_BYTES];
;   __shared__ uint4 xb_words;
	.amdhsa_kernel _Z14fwd_megakernel6Params
		.amdhsa_group_segment_fixed_size 81920
		.amdhsa_private_segment_fixed_size 0
		.amdhsa_kernarg_size 808
		.amdhsa_user_sgpr_count 2
		.amdhsa_user_sgpr_dispatch_ptr 0
		.amdhsa_user_sgpr_queue_ptr 0
		.amdhsa_user_sgpr_kernarg_segment_ptr 1
		.amdhsa_user_sgpr_dispatch_id 0
		.amdhsa_user_sgpr_kernarg_preload_length 0
		.amdhsa_user_sgpr_kernarg_preload_offset 0
		.amdhsa_user_sgpr_private_segment_size 0
		.amdhsa_uses_dynamic_stack 0
		.amdhsa_enable_private_segment 0
		.amdhsa_system_sgpr_workgroup_id_x 1
		.amdhsa_system_sgpr_workgroup_id_y 0
		.amdhsa_system_sgpr_workgroup_id_z 0
		.amdhsa_system_sgpr_workgroup_info 0
		.amdhsa_system_vgpr_workitem_id 2
		.amdhsa_next_free_vgpr 256
		.amdhsa_next_free_sgpr 100
		.amdhsa_accum_offset 256
		.amdhsa_reserve_vcc 1
		.amdhsa_float_round_mode_32 0
		.amdhsa_float_round_mode_16_64 0
		.amdhsa_float_denorm_mode_32 3
		.amdhsa_float_denorm_mode_16_64 3
		.amdhsa_dx10_clamp 1
		.amdhsa_ieee_mode 1
		.amdhsa_fp16_overflow 0
		.amdhsa_tg_split 0
		.amdhsa_exception_fp_ieee_invalid_op 0
		.amdhsa_exception_fp_denorm_src 0
		.amdhsa_exception_fp_ieee_div_zero 0
		.amdhsa_exception_fp_ieee_overflow 0
		.amdhsa_exception_fp_ieee_underflow 0
		.amdhsa_exception_fp_ieee_inexact 0
		.amdhsa_exception_int_div_zero 0
	.end_amdhsa_kernel

; __global__ void __launch_bounds__(256, 2) fwd_megakernel(Params p_unused) {
;   cg::grid_group grid = cg::this_grid();
;   __shared__ __attribute__((aligned(16))) char smem[SMEM_BYTES];
;   __shared__ uint4 xb_words;
amdhsa.kernels:
  - .agpr_count:     0
    .args:
      - .offset:         0
        .size:           552
        .value_kind:     by_value
      - .offset:         552
        .size:           4
        .value_kind:     hidden_block_count_x
      - .offset:         556
        .size:           4
        .value_kind:     hidden_block_count_y
      - .offset:         560
        .size:           4
        .value_kind:     hidden_block_count_z
      - .offset:         564
        .size:           2
        .value_kind:     hidden_group_size_x
      - .offset:         566
        .size:           2
        .value_kind:     hidden_group_size_y
      - .offset:         568
        .size:           2
        .value_kind:     hidden_group_size_z
      - .offset:         570
        .size:           2
        .value_kind:     hidden_remainder_x
      - .offset:         572
        .size:           2
        .value_kind:     hidden_remainder_y
      - .offset:         574
        .size:           2
        .value_kind:     hidden_remainder_z
      - .offset:         592
        .size:           8
        .value_kind:     hidden_global_offset_x
      - .offset:         600
        .size:           8
        .value_kind:     hidden_global_offset_y
      - .offset:         608
        .size:           8
        .value_kind:     hidden_global_offset_z
      - .offset:         616
        .size:           2
        .value_kind:     hidden_grid_dims
      - .offset:         640
        .size:           8
        .value_kind:     hidden_multigrid_sync_arg
    .group_segment_fixed_size: 81920
    .kernarg_segment_align: 8
    .kernarg_segment_size: 808
    .language:       OpenCL C
    .language_version:
      - 2
      - 0
    .max_flat_workgroup_size: 256
    .name:           _Z14fwd_megakernel6Params
    .private_segment_fixed_size: 0
    .sgpr_count:     106
    .sgpr_spill_count: 120
    .symbol:         _Z14fwd_megakernel6Params.kd
    .uniform_work_group_size: 1
    .uses_dynamic_stack: false
    .vgpr_count:     256
    .vgpr_spill_count: 0
    .wavefront_size: 64
